# e7: GEMM MFMA-segment barrier issued 4 MFMAs early (hand-off overlap)
# baseline (speedup 1.0000x reference)
; #define PG8_STAGE(bufoff, gbase, voff) do { _Pragma("unroll") for (int _i = 0; _i < 2; ++_i) \
;         __builtin_amdgcn_global_load_lds((const unsigned*)((const char*)(gbase) + (voff)[_i]), (PG8_LAS unsigned*)(lds + (bufoff) + ldsw + _i * 8192), 16, 0, 0); } while (0)
; #define PG8_LDA(dst, b, h) do { _Pragma("unroll") for (int m = 0; m < 4; ++m) _Pragma("unroll") for (int k = 0; k < 2; ++k) dst[m][k] = *(const PG8_LAS bf16x8*)(lds + PG8_SA(b, h) + aoff + m * 2048 + k * 1024); } while (0)
; #define PG8_LDB(dst, b, h) do { _Pragma("unroll") for (int n = 0; n < 2; ++n) _Pragma("unroll") for (int k = 0; k < 2; ++k) dst[n][k] = *(const PG8_LAS bf16x8*)(lds + PG8_SB(b, h) + boff + n * 2048 + k * 1024); } while (0)
; #define PG8_MMA(ai, bj, At, Bt) do { __builtin_amdgcn_s_setprio(1); _Pragma("unroll") for (int m = 0; m < 4; ++m) _Pragma("unroll") for (int n = 0; n < 2; ++n) _Pragma("unroll") for (int k = 0; k < 2; ++k) \
;         acc[ai][bj][m][n] = __builtin_amdgcn_mfma_f32_16x16x32_bf16(Bt[n][k], At[m][k], acc[ai][bj][m][n], 0, 0, 0); __builtin_amdgcn_s_setprio(0); } while (0)
; #define PG8_WAIT_V(n) asm volatile("s_waitcnt vmcnt(" #n ")" ::: "memory")
; #define PG8_WAIT_L(n) asm volatile("s_waitcnt lgkmcnt(" #n ")" ::: "memory")
; template <class Epi, class Sched, bool ALIGN_EPI = false, bool SP2 = false>
; __device__ __forceinline__ void gemm_phase(PG8_LAS unsigned char* lds, const Gemm g, const Sched& S, const Epi& E, const int tid) {
;     ...
;             const bool last = (t == nt - 2);
;             const char* a1 = cA + (size_t)(t + 1) * kstep;
;             const char* a2 = last ? nA : cA + (size_t)(t + 2) * kstep; const char* b2 = last ? nB : cB + (size_t)(t + 2) * kstep;
;             const char* a3 = a2 + kstep; const char* b3 = b2 + kstep;
;             if (last && has_next) S.a_ready(nxt);
;             if constexpr (SP2) {
;             PG8_LDB(B0, 0, 0); PG8_LDB(B1, 0, 1); PG8_SCHED; PG8_LDA(At, 0, 0); PG8_STAGE(PG8_SA(1, 1), a1 + hstep, voffA);
;             PG8_WAIT_V(8); PG8_WAIT_L(0); PG8_BAR; PG8_MMA(0, 0, At, B0); PG8_MMA(0, 1, At, B1); PG8_BAR; PG8_SCHED;
;             PG8_LDA(At, 0, 1); PG8_STAGE(PG8_SB(0, 0), b2, voffB); PG8_STAGE(PG8_SB(0, 1), b2 + hstep, voffB); PG8_STAGE(PG8_SA(0, 0), a2, voffA);
;             PG8_WAIT_V(8); PG8_WAIT_L(0); PG8_BAR; PG8_MMA(1, 0, At, B0); PG8_MMA(1, 1, At, B1); PG8_BAR; PG8_SCHED;
.LBB0_38:
	s_add_u32 s58, s44, 0xfffc0080
	s_addc_u32 s59, s45, -1
	s_add_i32 s73, 0, 0x10000
	s_cmp_eq_u32 s72, 12
	s_cselect_b32 s79, s17, s59
	s_cselect_b32 s78, s60, s58
	v_add_u32_e32 v138, s73, v140
	s_cselect_b32 s59, s15, s71
	s_cselect_b32 s58, s70, s62
	s_add_i32 s76, 0, 0x14000
	ds_read_b128 v[142:145], v138
	ds_read_b128 v[146:149], v138 offset:1024
	ds_read_b128 v[150:153], v138 offset:2048
	ds_read_b128 v[154:157], v138 offset:3072
	v_add_u32_e32 v138, s76, v140
	ds_read_b128 v[158:161], v138
	ds_read_b128 v[162:165], v138 offset:1024
	ds_read_b128 v[166:169], v138 offset:2048
	ds_read_b128 v[170:173], v138 offset:3072
	v_lshl_add_u64 v[138:139], s[44:45], 0, v[134:135]
	s_add_i32 m0, s38, 0xc000
	ds_read_b128 v[174:177], v141
	ds_read_b128 v[178:181], v141 offset:1024
	ds_read_b128 v[182:185], v141 offset:2048
	ds_read_b128 v[186:189], v141 offset:3072
	ds_read_b128 v[212:215], v141 offset:4096
	ds_read_b128 v[216:219], v141 offset:5120
	ds_read_b128 v[232:235], v141 offset:6144
	ds_read_b128 v[236:239], v141 offset:7168
	global_load_lds_dwordx4 v[138:139], off
	v_lshl_add_u64 v[138:139], s[44:45], 0, v[136:137]
	s_add_i32 m0, s38, 0xe000
	s_nop 0
	global_load_lds_dwordx4 v[138:139], off
	s_waitcnt vmcnt(8)
	s_waitcnt lgkmcnt(0)
	s_barrier
	s_setprio 1
	s_waitcnt lgkmcnt(0)
	v_mfma_f32_16x16x32_bf16 v[124:127], v[142:145], v[174:177], v[124:127]
	v_mfma_f32_16x16x32_bf16 v[120:123], v[150:153], v[174:177], v[120:123]
	v_mfma_f32_16x16x32_bf16 v[108:111], v[142:145], v[182:185], v[108:111]
	v_mfma_f32_16x16x32_bf16 v[104:107], v[150:153], v[182:185], v[104:107]
	v_mfma_f32_16x16x32_bf16 v[92:95], v[142:145], v[212:215], v[92:95]
	v_mfma_f32_16x16x32_bf16 v[88:91], v[150:153], v[212:215], v[88:91]
	v_mfma_f32_16x16x32_bf16 v[76:79], v[142:145], v[232:235], v[76:79]
	v_mfma_f32_16x16x32_bf16 v[72:75], v[150:153], v[232:235], v[72:75]
	v_mfma_f32_16x16x32_bf16 v[124:127], v[146:149], v[178:181], v[124:127]
	v_mfma_f32_16x16x32_bf16 v[120:123], v[154:157], v[178:181], v[120:123]
	v_mfma_f32_16x16x32_bf16 v[108:111], v[146:149], v[186:189], v[108:111]
	v_mfma_f32_16x16x32_bf16 v[104:107], v[154:157], v[186:189], v[104:107]
	v_mfma_f32_16x16x32_bf16 v[92:95], v[146:149], v[216:219], v[92:95]
	v_mfma_f32_16x16x32_bf16 v[88:91], v[154:157], v[216:219], v[88:91]
	v_mfma_f32_16x16x32_bf16 v[76:79], v[146:149], v[236:239], v[76:79]
	v_mfma_f32_16x16x32_bf16 v[72:75], v[154:157], v[236:239], v[72:75]
	s_setprio 0
	s_setprio 1
	v_mfma_f32_16x16x32_bf16 v[116:119], v[158:161], v[174:177], v[116:119]
	v_mfma_f32_16x16x32_bf16 v[112:115], v[166:169], v[174:177], v[112:115]
	v_mfma_f32_16x16x32_bf16 v[100:103], v[158:161], v[182:185], v[100:103]
	v_mfma_f32_16x16x32_bf16 v[96:99], v[166:169], v[182:185], v[96:99]
	v_mfma_f32_16x16x32_bf16 v[84:87], v[158:161], v[212:215], v[84:87]
	v_mfma_f32_16x16x32_bf16 v[80:83], v[166:169], v[212:215], v[80:83]
	v_mfma_f32_16x16x32_bf16 v[68:71], v[158:161], v[232:235], v[68:71]
	v_mfma_f32_16x16x32_bf16 v[64:67], v[166:169], v[232:235], v[64:67]
	v_mfma_f32_16x16x32_bf16 v[116:119], v[162:165], v[178:181], v[116:119]
	v_mfma_f32_16x16x32_bf16 v[112:115], v[170:173], v[178:181], v[112:115]
	v_mfma_f32_16x16x32_bf16 v[100:103], v[162:165], v[186:189], v[100:103]
	v_mfma_f32_16x16x32_bf16 v[96:99], v[170:173], v[186:189], v[96:99]
	s_barrier
	v_mfma_f32_16x16x32_bf16 v[84:87], v[162:165], v[216:219], v[84:87]
	v_mfma_f32_16x16x32_bf16 v[80:83], v[170:173], v[216:219], v[80:83]
	v_mfma_f32_16x16x32_bf16 v[68:71], v[162:165], v[236:239], v[68:71]
	v_mfma_f32_16x16x32_bf16 v[64:67], v[170:173], v[236:239], v[64:67]
	s_setprio 0
	s_add_i32 s73, s73, s35
	v_lshl_add_u64 v[138:139], s[58:59], 0, v[192:193]
	s_mov_b32 m0, s73
	ds_read_b128 v[174:177], v141 offset:16384
	ds_read_b128 v[178:181], v141 offset:17408
	ds_read_b128 v[182:185], v141 offset:18432
	ds_read_b128 v[186:189], v141 offset:19456
	ds_read_b128 v[212:215], v141 offset:20480
	ds_read_b128 v[216:219], v141 offset:21504
	ds_read_b128 v[232:235], v141 offset:22528
	ds_read_b128 v[236:239], v141 offset:23552
	global_load_lds_dwordx4 v[138:139], off
	s_add_i32 m0, s73, 0x2000
	s_add_u32 s74, s58, 0x40000
	v_lshl_add_u64 v[190:191], s[58:59], 0, v[132:133]
	s_addc_u32 s75, s59, 0
	s_add_i32 s73, s76, s35
	global_load_lds_dwordx4 v[190:191], off
	v_lshl_add_u64 v[194:195], s[74:75], 0, v[192:193]
	s_mov_b32 m0, s73
	v_lshl_add_u64 v[196:197], s[78:79], 0, v[130:131]
	global_load_lds_dwordx4 v[194:195], off
	v_lshl_add_u64 v[194:195], s[74:75], 0, v[132:133]
	s_add_i32 m0, s73, 0x2000
	s_nop 0
	global_load_lds_dwordx4 v[194:195], off
	v_lshl_add_u64 v[194:195], s[78:79], 0, v[128:129]
	s_mov_b32 m0, s38
	s_nop 0
	global_load_lds_dwordx4 v[194:195], off
	s_mov_b32 m0, s40
	s_nop 0
	global_load_lds_dwordx4 v[196:197], off
	s_waitcnt vmcnt(8)
	s_waitcnt lgkmcnt(0)
	s_barrier
; #define PG8_STAGE(bufoff, gbase, voff) do { _Pragma("unroll") for (int _i = 0; _i < 2; ++_i) \
;         __builtin_amdgcn_global_load_lds((const unsigned*)((const char*)(gbase) + (voff)[_i]), (PG8_LAS unsigned*)(lds + (bufoff) + ldsw + _i * 8192), 16, 0, 0); } while (0)
; #define PG8_LDA(dst, b, h) do { _Pragma("unroll") for (int m = 0; m < 4; ++m) _Pragma("unroll") for (int k = 0; k < 2; ++k) dst[m][k] = *(const PG8_LAS bf16x8*)(lds + PG8_SA(b, h) + aoff + m * 2048 + k * 1024); } while (0)
; #define PG8_LDB(dst, b, h) do { _Pragma("unroll") for (int n = 0; n < 2; ++n) _Pragma("unroll") for (int k = 0; k < 2; ++k) dst[n][k] = *(const PG8_LAS bf16x8*)(lds + PG8_SB(b, h) + boff + n * 2048 + k * 1024); } while (0)
; #define PG8_MMA(ai, bj, At, Bt) do { __builtin_amdgcn_s_setprio(1); _Pragma("unroll") for (int m = 0; m < 4; ++m) _Pragma("unroll") for (int n = 0; n < 2; ++n) _Pragma("unroll") for (int k = 0; k < 2; ++k) \
;         acc[ai][bj][m][n] = __builtin_amdgcn_mfma_f32_16x16x32_bf16(Bt[n][k], At[m][k], acc[ai][bj][m][n], 0, 0, 0); __builtin_amdgcn_s_setprio(0); } while (0)
; #define PG8_WAIT_V(n) asm volatile("s_waitcnt vmcnt(" #n ")" ::: "memory")
; #define PG8_WAIT_L(n) asm volatile("s_waitcnt lgkmcnt(" #n ")" ::: "memory")
; #define PG8_BAR __builtin_amdgcn_s_barrier()
; #define PG8_SCHED __builtin_amdgcn_sched_barrier(0)
; template <class Epi, class Sched, bool ALIGN_EPI = false, bool SP2 = false>
; __device__ __forceinline__ void gemm_phase(PG8_LAS unsigned char* lds, const Gemm g, const Sched& S, const Epi& E, const int tid) {
;     ...
;             PG8_WAIT_V(8); PG8_WAIT_L(0); PG8_BAR; PG8_MMA(1, 0, At, B0); PG8_MMA(1, 1, At, B1); PG8_BAR; PG8_SCHED;
;             PG8_LDB(B0, 1, 0); PG8_LDB(B1, 1, 1); PG8_SCHED; PG8_LDA(At, 1, 0); PG8_STAGE(PG8_SA(0, 1), a2 + hstep, voffA);
;             PG8_WAIT_V(8); PG8_WAIT_L(0); PG8_BAR; PG8_MMA(0, 0, At, B0); PG8_MMA(0, 1, At, B1); PG8_BAR; PG8_SCHED;
;             PG8_LDA(At, 1, 1); PG8_STAGE(PG8_SB(1, 0), b3, voffB); PG8_STAGE(PG8_SB(1, 1), b3 + hstep, voffB); PG8_STAGE(PG8_SA(1, 0), a3, voffA);
	s_setprio 1
	s_waitcnt lgkmcnt(0)
	v_mfma_f32_16x16x32_bf16 v[60:63], v[142:145], v[174:177], v[60:63]
	v_mfma_f32_16x16x32_bf16 v[56:59], v[150:153], v[174:177], v[56:59]
	v_mfma_f32_16x16x32_bf16 v[44:47], v[142:145], v[182:185], v[44:47]
	v_mfma_f32_16x16x32_bf16 v[40:43], v[150:153], v[182:185], v[40:43]
	v_mfma_f32_16x16x32_bf16 v[28:31], v[142:145], v[212:215], v[28:31]
	v_mfma_f32_16x16x32_bf16 v[24:27], v[150:153], v[212:215], v[24:27]
	v_mfma_f32_16x16x32_bf16 v[12:15], v[142:145], v[232:235], v[12:15]
	v_mfma_f32_16x16x32_bf16 v[8:11], v[150:153], v[232:235], v[8:11]
	v_mfma_f32_16x16x32_bf16 v[60:63], v[146:149], v[178:181], v[60:63]
	v_mfma_f32_16x16x32_bf16 v[56:59], v[154:157], v[178:181], v[56:59]
	v_mfma_f32_16x16x32_bf16 v[44:47], v[146:149], v[186:189], v[44:47]
	v_mfma_f32_16x16x32_bf16 v[40:43], v[154:157], v[186:189], v[40:43]
	v_mfma_f32_16x16x32_bf16 v[28:31], v[146:149], v[216:219], v[28:31]
	v_mfma_f32_16x16x32_bf16 v[24:27], v[154:157], v[216:219], v[24:27]
	v_mfma_f32_16x16x32_bf16 v[12:15], v[146:149], v[236:239], v[12:15]
	v_mfma_f32_16x16x32_bf16 v[8:11], v[154:157], v[236:239], v[8:11]
	s_setprio 0
	s_setprio 1
	v_mfma_f32_16x16x32_bf16 v[52:55], v[158:161], v[174:177], v[52:55]
	v_mfma_f32_16x16x32_bf16 v[48:51], v[166:169], v[174:177], v[48:51]
	v_mfma_f32_16x16x32_bf16 v[36:39], v[158:161], v[182:185], v[36:39]
	v_mfma_f32_16x16x32_bf16 v[32:35], v[166:169], v[182:185], v[32:35]
	v_mfma_f32_16x16x32_bf16 v[20:23], v[158:161], v[212:215], v[20:23]
	v_mfma_f32_16x16x32_bf16 v[16:19], v[166:169], v[212:215], v[16:19]
	v_mfma_f32_16x16x32_bf16 v[4:7], v[158:161], v[232:235], v[4:7]
	v_mfma_f32_16x16x32_bf16 v[0:3], v[166:169], v[232:235], v[0:3]
	v_mfma_f32_16x16x32_bf16 v[52:55], v[162:165], v[178:181], v[52:55]
	v_mfma_f32_16x16x32_bf16 v[48:51], v[170:173], v[178:181], v[48:51]
	v_mfma_f32_16x16x32_bf16 v[36:39], v[162:165], v[186:189], v[36:39]
	v_mfma_f32_16x16x32_bf16 v[32:35], v[170:173], v[186:189], v[32:35]
	s_barrier
	v_mfma_f32_16x16x32_bf16 v[20:23], v[162:165], v[216:219], v[20:23]
	v_mfma_f32_16x16x32_bf16 v[16:19], v[170:173], v[216:219], v[16:19]
	v_mfma_f32_16x16x32_bf16 v[4:7], v[162:165], v[236:239], v[4:7]
	v_mfma_f32_16x16x32_bf16 v[0:3], v[170:173], v[236:239], v[0:3]
	s_setprio 0
	s_add_i32 s73, 0, 0x18000
	s_add_i32 s76, 0, 0x1c000
	v_add_u32_e32 v154, s73, v140
	v_add_u32_e32 v170, s76, v140
	ds_read_b128 v[142:145], v154
	ds_read_b128 v[146:149], v154 offset:1024
	ds_read_b128 v[150:153], v154 offset:2048
	ds_read_b128 v[154:157], v154 offset:3072
	ds_read_b128 v[158:161], v170
	ds_read_b128 v[162:165], v170 offset:1024
	ds_read_b128 v[166:169], v170 offset:2048
	ds_read_b128 v[170:173], v170 offset:3072
	s_add_u32 s74, s78, 0x40000
	s_addc_u32 s75, s79, 0
	s_mov_b32 m0, s41
	v_lshl_add_u64 v[202:203], s[74:75], 0, v[128:129]
	ds_read_b128 v[174:177], v141 offset:32768
	ds_read_b128 v[178:181], v141 offset:33792
	ds_read_b128 v[182:185], v141 offset:34816
	ds_read_b128 v[186:189], v141 offset:35840
	ds_read_b128 v[212:215], v141 offset:36864
	ds_read_b128 v[216:219], v141 offset:37888
	ds_read_b128 v[232:235], v141 offset:38912
	ds_read_b128 v[236:239], v141 offset:39936
	global_load_lds_dwordx4 v[202:203], off
	v_lshl_add_u64 v[202:203], s[74:75], 0, v[130:131]
	s_mov_b32 m0, s46
	s_nop 0
	global_load_lds_dwordx4 v[202:203], off
	s_waitcnt vmcnt(8)
	s_waitcnt lgkmcnt(0)
	s_barrier
	s_setprio 1
	s_waitcnt lgkmcnt(0)
	v_mfma_f32_16x16x32_bf16 v[124:127], v[142:145], v[174:177], v[124:127]
	v_mfma_f32_16x16x32_bf16 v[120:123], v[150:153], v[174:177], v[120:123]
	v_mfma_f32_16x16x32_bf16 v[108:111], v[142:145], v[182:185], v[108:111]
	v_mfma_f32_16x16x32_bf16 v[104:107], v[150:153], v[182:185], v[104:107]
	v_mfma_f32_16x16x32_bf16 v[92:95], v[142:145], v[212:215], v[92:95]
	v_mfma_f32_16x16x32_bf16 v[88:91], v[150:153], v[212:215], v[88:91]
	v_mfma_f32_16x16x32_bf16 v[76:79], v[142:145], v[232:235], v[76:79]
	v_mfma_f32_16x16x32_bf16 v[72:75], v[150:153], v[232:235], v[72:75]
	v_mfma_f32_16x16x32_bf16 v[124:127], v[146:149], v[178:181], v[124:127]
	v_mfma_f32_16x16x32_bf16 v[120:123], v[154:157], v[178:181], v[120:123]
	v_mfma_f32_16x16x32_bf16 v[108:111], v[146:149], v[186:189], v[108:111]
	v_mfma_f32_16x16x32_bf16 v[104:107], v[154:157], v[186:189], v[104:107]
	v_mfma_f32_16x16x32_bf16 v[92:95], v[146:149], v[216:219], v[92:95]
	v_mfma_f32_16x16x32_bf16 v[88:91], v[154:157], v[216:219], v[88:91]
	v_mfma_f32_16x16x32_bf16 v[76:79], v[146:149], v[236:239], v[76:79]
	v_mfma_f32_16x16x32_bf16 v[72:75], v[154:157], v[236:239], v[72:75]
	s_setprio 0
	s_setprio 1
	v_mfma_f32_16x16x32_bf16 v[116:119], v[158:161], v[174:177], v[116:119]
	v_mfma_f32_16x16x32_bf16 v[112:115], v[166:169], v[174:177], v[112:115]
	v_mfma_f32_16x16x32_bf16 v[100:103], v[158:161], v[182:185], v[100:103]
	v_mfma_f32_16x16x32_bf16 v[96:99], v[166:169], v[182:185], v[96:99]
	v_mfma_f32_16x16x32_bf16 v[84:87], v[158:161], v[212:215], v[84:87]
	v_mfma_f32_16x16x32_bf16 v[80:83], v[166:169], v[212:215], v[80:83]
	v_mfma_f32_16x16x32_bf16 v[68:71], v[158:161], v[232:235], v[68:71]
	v_mfma_f32_16x16x32_bf16 v[64:67], v[166:169], v[232:235], v[64:67]
	v_mfma_f32_16x16x32_bf16 v[116:119], v[162:165], v[178:181], v[116:119]
	v_mfma_f32_16x16x32_bf16 v[112:115], v[170:173], v[178:181], v[112:115]
	v_mfma_f32_16x16x32_bf16 v[100:103], v[162:165], v[186:189], v[100:103]
	v_mfma_f32_16x16x32_bf16 v[96:99], v[170:173], v[186:189], v[96:99]
	s_barrier
; #define PG8_STAGE(bufoff, gbase, voff) do { _Pragma("unroll") for (int _i = 0; _i < 2; ++_i) \
;         __builtin_amdgcn_global_load_lds((const unsigned*)((const char*)(gbase) + (voff)[_i]), (PG8_LAS unsigned*)(lds + (bufoff) + ldsw + _i * 8192), 16, 0, 0); } while (0)
; #define PG8_LDA(dst, b, h) do { _Pragma("unroll") for (int m = 0; m < 4; ++m) _Pragma("unroll") for (int k = 0; k < 2; ++k) dst[m][k] = *(const PG8_LAS bf16x8*)(lds + PG8_SA(b, h) + aoff + m * 2048 + k * 1024); } while (0)
; #define PG8_MMA(ai, bj, At, Bt) do { __builtin_amdgcn_s_setprio(1); _Pragma("unroll") for (int m = 0; m < 4; ++m) _Pragma("unroll") for (int n = 0; n < 2; ++n) _Pragma("unroll") for (int k = 0; k < 2; ++k) \
;         acc[ai][bj][m][n] = __builtin_amdgcn_mfma_f32_16x16x32_bf16(Bt[n][k], At[m][k], acc[ai][bj][m][n], 0, 0, 0); __builtin_amdgcn_s_setprio(0); } while (0)
; #define PG8_WAIT_V(n) asm volatile("s_waitcnt vmcnt(" #n ")" ::: "memory")
; #define PG8_WAIT_L(n) asm volatile("s_waitcnt lgkmcnt(" #n ")" ::: "memory")
; #define PG8_BAR __builtin_amdgcn_s_barrier()
; #define PG8_SCHED __builtin_amdgcn_sched_barrier(0)
; template <class Epi, class Sched, bool ALIGN_EPI = false, bool SP2 = false>
; __device__ __forceinline__ void gemm_phase(PG8_LAS unsigned char* lds, const Gemm g, const Sched& S, const Epi& E, const int tid) {
;     ...
;             PG8_WAIT_V(8); PG8_WAIT_L(0); PG8_BAR; PG8_MMA(0, 0, At, B0); PG8_MMA(0, 1, At, B1); PG8_BAR; PG8_SCHED;
;             PG8_LDA(At, 1, 1); PG8_STAGE(PG8_SB(1, 0), b3, voffB); PG8_STAGE(PG8_SB(1, 1), b3 + hstep, voffB); PG8_STAGE(PG8_SA(1, 0), a3, voffA);
;             PG8_WAIT_V(8); PG8_WAIT_L(0); PG8_BAR; PG8_MMA(1, 0, At, B0); PG8_MMA(1, 1, At, B1); PG8_BAR; PG8_SCHED;
;     ...
;         }
;         if constexpr (ALIGN_EPI) { if (wr == 0) PG8_BAR; }
	v_mfma_f32_16x16x32_bf16 v[84:87], v[162:165], v[216:219], v[84:87]
	v_mfma_f32_16x16x32_bf16 v[80:83], v[170:173], v[216:219], v[80:83]
	v_mfma_f32_16x16x32_bf16 v[68:71], v[162:165], v[236:239], v[68:71]
	v_mfma_f32_16x16x32_bf16 v[64:67], v[170:173], v[236:239], v[64:67]
	s_setprio 0
	s_add_i32 s73, s73, s35
	v_lshl_add_u64 v[138:139], v[138:139], 0, s[36:37]
	s_mov_b32 m0, s73
	ds_read_b128 v[174:177], v141 offset:49152
	ds_read_b128 v[178:181], v141 offset:50176
	ds_read_b128 v[182:185], v141 offset:51200
	ds_read_b128 v[186:189], v141 offset:52224
	ds_read_b128 v[212:215], v141 offset:53248
	ds_read_b128 v[216:219], v141 offset:54272
	ds_read_b128 v[232:235], v141 offset:55296
	ds_read_b128 v[236:239], v141 offset:56320
	global_load_lds_dwordx4 v[138:139], off
	s_add_i32 m0, s73, 0x2000
	s_add_u32 s58, s58, 0x40080
	v_lshl_add_u64 v[138:139], v[190:191], 0, s[36:37]
	s_addc_u32 s59, s59, 0
	s_add_i32 s73, s76, s35
	global_load_lds_dwordx4 v[138:139], off
	v_lshl_add_u64 v[138:139], s[58:59], 0, v[192:193]
	s_mov_b32 m0, s73
	s_nop 0
	global_load_lds_dwordx4 v[138:139], off
	v_lshl_add_u64 v[138:139], s[58:59], 0, v[132:133]
	s_add_i32 m0, s73, 0x2000
	s_nop 0
	global_load_lds_dwordx4 v[138:139], off
	v_lshl_add_u64 v[138:139], v[194:195], 0, s[36:37]
	s_mov_b32 m0, s47
	s_nop 0
	global_load_lds_dwordx4 v[138:139], off
	v_lshl_add_u64 v[138:139], v[196:197], 0, s[36:37]
	s_mov_b32 m0, s53
	s_nop 0
	global_load_lds_dwordx4 v[138:139], off
	s_waitcnt vmcnt(8)
	s_waitcnt lgkmcnt(0)
	s_barrier
	s_setprio 1
	s_waitcnt lgkmcnt(0)
	v_mfma_f32_16x16x32_bf16 v[60:63], v[142:145], v[174:177], v[60:63]
	v_mfma_f32_16x16x32_bf16 v[56:59], v[150:153], v[174:177], v[56:59]
	v_mfma_f32_16x16x32_bf16 v[44:47], v[142:145], v[182:185], v[44:47]
	v_mfma_f32_16x16x32_bf16 v[40:43], v[150:153], v[182:185], v[40:43]
	v_mfma_f32_16x16x32_bf16 v[28:31], v[142:145], v[212:215], v[28:31]
	v_mfma_f32_16x16x32_bf16 v[24:27], v[150:153], v[212:215], v[24:27]
	v_mfma_f32_16x16x32_bf16 v[12:15], v[142:145], v[232:235], v[12:15]
	v_mfma_f32_16x16x32_bf16 v[8:11], v[150:153], v[232:235], v[8:11]
	v_mfma_f32_16x16x32_bf16 v[60:63], v[146:149], v[178:181], v[60:63]
	v_mfma_f32_16x16x32_bf16 v[56:59], v[154:157], v[178:181], v[56:59]
	v_mfma_f32_16x16x32_bf16 v[44:47], v[146:149], v[186:189], v[44:47]
	v_mfma_f32_16x16x32_bf16 v[40:43], v[154:157], v[186:189], v[40:43]
	v_mfma_f32_16x16x32_bf16 v[28:31], v[146:149], v[216:219], v[28:31]
	v_mfma_f32_16x16x32_bf16 v[24:27], v[154:157], v[216:219], v[24:27]
	v_mfma_f32_16x16x32_bf16 v[12:15], v[146:149], v[236:239], v[12:15]
	v_mfma_f32_16x16x32_bf16 v[8:11], v[154:157], v[236:239], v[8:11]
	s_setprio 0
	s_setprio 1
	v_mfma_f32_16x16x32_bf16 v[52:55], v[158:161], v[174:177], v[52:55]
	v_mfma_f32_16x16x32_bf16 v[48:51], v[166:169], v[174:177], v[48:51]
	v_mfma_f32_16x16x32_bf16 v[36:39], v[158:161], v[182:185], v[36:39]
	v_mfma_f32_16x16x32_bf16 v[32:35], v[166:169], v[182:185], v[32:35]
	v_mfma_f32_16x16x32_bf16 v[20:23], v[158:161], v[212:215], v[20:23]
	v_mfma_f32_16x16x32_bf16 v[16:19], v[166:169], v[212:215], v[16:19]
	v_mfma_f32_16x16x32_bf16 v[4:7], v[158:161], v[232:235], v[4:7]
	v_mfma_f32_16x16x32_bf16 v[0:3], v[166:169], v[232:235], v[0:3]
	v_mfma_f32_16x16x32_bf16 v[52:55], v[162:165], v[178:181], v[52:55]
	v_mfma_f32_16x16x32_bf16 v[48:51], v[170:173], v[178:181], v[48:51]
	v_mfma_f32_16x16x32_bf16 v[36:39], v[162:165], v[186:189], v[36:39]
	v_mfma_f32_16x16x32_bf16 v[32:35], v[170:173], v[186:189], v[32:35]
	s_barrier
	v_mfma_f32_16x16x32_bf16 v[20:23], v[162:165], v[216:219], v[20:23]
	v_mfma_f32_16x16x32_bf16 v[16:19], v[170:173], v[216:219], v[16:19]
	v_mfma_f32_16x16x32_bf16 v[4:7], v[162:165], v[236:239], v[4:7]
	v_mfma_f32_16x16x32_bf16 v[0:3], v[170:173], v[236:239], v[0:3]
	s_setprio 0
	s_add_i32 s72, s72, 2
	s_add_u32 s44, s44, 0x100
	s_addc_u32 s45, s45, 0
	s_add_u32 s62, s62, 0x100
	s_addc_u32 s71, s71, 0
	s_cmp_gt_u32 s72, 13
	s_cbranch_scc0 .LBB0_38
	s_nop 7
	s_and_b64 vcc, exec, s[10:11]
	s_mov_b64 s[72:73], 0x20000
	s_cbranch_vccz .LBB0_41
	s_barrier

; #define PG8_STAGE(bufoff, gbase, voff) do { _Pragma("unroll") for (int _i = 0; _i < 2; ++_i) \
;         __builtin_amdgcn_global_load_lds((const unsigned*)((const char*)(gbase) + (voff)[_i]), (PG8_LAS unsigned*)(lds + (bufoff) + ldsw + _i * 8192), 16, 0, 0); } while (0)
; #define PG8_LDA(dst, b, h) do { _Pragma("unroll") for (int m = 0; m < 4; ++m) _Pragma("unroll") for (int k = 0; k < 2; ++k) dst[m][k] = *(const PG8_LAS bf16x8*)(lds + PG8_SA(b, h) + aoff + m * 2048 + k * 1024); } while (0)
; #define PG8_LDB(dst, b, h) do { _Pragma("unroll") for (int n = 0; n < 2; ++n) _Pragma("unroll") for (int k = 0; k < 2; ++k) dst[n][k] = *(const PG8_LAS bf16x8*)(lds + PG8_SB(b, h) + boff + n * 2048 + k * 1024); } while (0)
; #define PG8_WAIT_V(n) asm volatile("s_waitcnt vmcnt(" #n ")" ::: "memory")
; #define PG8_WAIT_L(n) asm volatile("s_waitcnt lgkmcnt(" #n ")" ::: "memory")
; #define PG8_BAR __builtin_amdgcn_s_barrier()
; #define PG8_SCHED __builtin_amdgcn_sched_barrier(0)
; template <class Epi, class Sched, bool ALIGN_EPI = false, bool SP2 = false>
; __device__ __forceinline__ void gemm_phase(PG8_LAS unsigned char* lds, const Gemm g, const Sched& S, const Epi& E, const int tid) {
;     ...
;         const char* nA = has_next ? (const char*)g.A + (size_t)nxt.pm * tstep : cA; const char* nB = has_next ? (const char*)g.Bt + (size_t)nxt.pn * tstep : cB;
;         for (int t = 0; t < nt; t += 2) {
;             const bool last = (t == nt - 2);
;             const char* a1 = cA + (size_t)(t + 1) * kstep;
;             const char* a2 = last ? nA : cA + (size_t)(t + 2) * kstep; const char* b2 = last ? nB : cB + (size_t)(t + 2) * kstep;
;             const char* a3 = a2 + kstep; const char* b3 = b2 + kstep;
;             if (last && has_next) S.a_ready(nxt);
;             if constexpr (SP2) {
;             PG8_LDB(B0, 0, 0); PG8_LDB(B1, 0, 1); PG8_SCHED; PG8_LDA(At, 0, 0); PG8_STAGE(PG8_SA(1, 1), a1 + hstep, voffA);
;             PG8_WAIT_V(8); PG8_WAIT_L(0); PG8_BAR; PG8_MMA(0, 0, At, B0); PG8_MMA(0, 1, At, B1); PG8_BAR; PG8_SCHED;
;             PG8_LDA(At, 0, 1); PG8_STAGE(PG8_SB(0, 0), b2, voffB); PG8_STAGE(PG8_SB(0, 1), b2 + hstep, voffB); PG8_STAGE(PG8_SA(0, 0), a2, voffA);
;             PG8_WAIT_V(8); PG8_WAIT_L(0); PG8_BAR; PG8_MMA(1, 0, At, B0); PG8_MMA(1, 1, At, B1); PG8_BAR; PG8_SCHED;
.LBB0_61:
	s_ashr_i32 s23, s22, 31
	s_lshl_b64 s[44:45], s[22:23], 17
	s_add_u32 s44, s0, s44
	s_addc_u32 s45, s1, s45
	s_and_b64 s[58:59], s[6:7], exec
	s_cselect_b32 s87, s45, s81
	s_cselect_b32 s86, s44, s80
	s_ashr_i32 s21, s20, 31
	s_lshl_b64 s[58:59], s[20:21], 17
	s_add_u32 s58, s2, s58
	s_addc_u32 s59, s26, s59
	s_and_b64 s[70:71], s[6:7], exec
	s_cselect_b32 s85, s59, s83
	s_cselect_b32 s84, s58, s82
	s_add_i32 s62, 0, 0x10000
	s_add_i32 s55, 0, 0x14000
	v_add_u32_e32 v204, s62, v140
	v_add_u32_e32 v205, s55, v140
	ds_read_b128 v[0:3], v204
	ds_read_b128 v[4:7], v204 offset:1024
	ds_read_b128 v[8:11], v204 offset:2048
	ds_read_b128 v[12:15], v204 offset:3072
	ds_read_b128 v[16:19], v205
	ds_read_b128 v[20:23], v205 offset:1024
	ds_read_b128 v[24:27], v205 offset:2048
	ds_read_b128 v[28:31], v205 offset:3072
	v_mov_b64_e32 v[228:229], 0xff
	v_mov_b64_e32 v[200:201], 0x100
	v_mov_b64_e32 v[198:199], 0x1ff
	v_mov_b64_e32 v[252:253], 0x200
	s_add_u32 s72, s80, 0x10080
	s_addc_u32 s73, s81, 0
	s_add_i32 s71, s35, 0xc000
	v_lshl_add_u64 v[64:65], s[72:73], 0, v[128:129]
	s_mov_b32 m0, s71
	s_add_i32 s21, s35, 0xe000
	ds_read_b128 v[32:35], v141
	ds_read_b128 v[36:39], v141 offset:1024
	ds_read_b128 v[40:43], v141 offset:2048
	ds_read_b128 v[44:47], v141 offset:3072
	ds_read_b128 v[48:51], v141 offset:4096
	ds_read_b128 v[52:55], v141 offset:5120
	ds_read_b128 v[56:59], v141 offset:6144
	ds_read_b128 v[60:63], v141 offset:7168
	global_load_lds_dwordx4 v[64:65], off
	v_lshl_add_u64 v[64:65], s[72:73], 0, v[130:131]
	s_mov_b32 m0, s21
	s_nop 0
	global_load_lds_dwordx4 v[64:65], off
	s_waitcnt vmcnt(8)
	s_waitcnt lgkmcnt(0)
	s_barrier
	s_setprio 1
	s_waitcnt lgkmcnt(0)
	v_mfma_f32_16x16x32_bf16 v[64:67], v[0:3], v[32:35], 0
	v_mfma_f32_16x16x32_bf16 v[68:71], v[8:11], v[32:35], 0
	v_mfma_f32_16x16x32_bf16 v[72:75], v[0:3], v[40:43], 0
	v_mfma_f32_16x16x32_bf16 v[76:79], v[8:11], v[40:43], 0
	v_mfma_f32_16x16x32_bf16 v[80:83], v[0:3], v[48:51], 0
	v_mfma_f32_16x16x32_bf16 v[84:87], v[8:11], v[48:51], 0
	v_mfma_f32_16x16x32_bf16 v[88:91], v[0:3], v[56:59], 0
	v_mfma_f32_16x16x32_bf16 v[92:95], v[8:11], v[56:59], 0
	v_mfma_f32_16x16x32_bf16 v[64:67], v[4:7], v[36:39], v[64:67]
	v_mfma_f32_16x16x32_bf16 v[68:71], v[12:15], v[36:39], v[68:71]
	v_mfma_f32_16x16x32_bf16 v[72:75], v[4:7], v[44:47], v[72:75]
	v_mfma_f32_16x16x32_bf16 v[76:79], v[12:15], v[44:47], v[76:79]
	v_mfma_f32_16x16x32_bf16 v[80:83], v[4:7], v[52:55], v[80:83]
	v_mfma_f32_16x16x32_bf16 v[84:87], v[12:15], v[52:55], v[84:87]
	v_mfma_f32_16x16x32_bf16 v[88:91], v[4:7], v[60:63], v[88:91]
	v_mfma_f32_16x16x32_bf16 v[92:95], v[12:15], v[60:63], v[92:95]
	s_setprio 0
	s_setprio 1
	v_mfma_f32_16x16x32_bf16 v[96:99], v[16:19], v[32:35], 0
	v_mfma_f32_16x16x32_bf16 v[32:35], v[24:27], v[32:35], 0
	v_mfma_f32_16x16x32_bf16 v[96:99], v[20:23], v[36:39], v[96:99]
	v_mfma_f32_16x16x32_bf16 v[32:35], v[28:31], v[36:39], v[32:35]
	v_mfma_f32_16x16x32_bf16 v[36:39], v[16:19], v[40:43], 0
	v_mfma_f32_16x16x32_bf16 v[40:43], v[24:27], v[40:43], 0
	v_mfma_f32_16x16x32_bf16 v[36:39], v[20:23], v[44:47], v[36:39]
	v_mfma_f32_16x16x32_bf16 v[40:43], v[28:31], v[44:47], v[40:43]
	v_mfma_f32_16x16x32_bf16 v[44:47], v[16:19], v[48:51], 0
	v_mfma_f32_16x16x32_bf16 v[48:51], v[24:27], v[48:51], 0
	v_mfma_f32_16x16x32_bf16 v[44:47], v[20:23], v[52:55], v[44:47]
	v_mfma_f32_16x16x32_bf16 v[48:51], v[28:31], v[52:55], v[48:51]
	s_barrier
	v_mfma_f32_16x16x32_bf16 v[52:55], v[16:19], v[56:59], 0
	v_mfma_f32_16x16x32_bf16 v[56:59], v[24:27], v[56:59], 0
	v_mfma_f32_16x16x32_bf16 v[52:55], v[20:23], v[60:63], v[52:55]
	v_mfma_f32_16x16x32_bf16 v[56:59], v[28:31], v[60:63], v[56:59]
	s_setprio 0
	s_add_i32 s62, s62, s34
	v_lshl_add_u64 v[138:139], s[82:83], 0, v[192:193]
	s_mov_b64 s[74:75], 0x100
	s_add_i32 s23, s62, 0x2000
	v_lshl_add_u64 v[134:135], v[138:139], 0, s[74:75]
	s_mov_b32 m0, s62
	v_lshl_add_u64 v[190:191], s[82:83], 0, v[132:133]
	s_add_u32 s72, s82, 0x10100
	ds_read_b128 v[60:63], v141 offset:16384
	ds_read_b128 v[100:103], v141 offset:17408
	ds_read_b128 v[104:107], v141 offset:18432
	ds_read_b128 v[108:111], v141 offset:19456
	ds_read_b128 v[112:115], v141 offset:20480
	ds_read_b128 v[116:119], v141 offset:21504
	ds_read_b128 v[120:123], v141 offset:22528
	ds_read_b128 v[124:127], v141 offset:23552
	global_load_lds_dwordx4 v[134:135], off
	v_lshl_add_u64 v[134:135], v[190:191], 0, s[74:75]
	s_mov_b32 m0, s23
	s_addc_u32 s73, s83, 0
	s_add_i32 s55, s55, s34
	global_load_lds_dwordx4 v[134:135], off
	v_lshl_add_u64 v[134:135], s[72:73], 0, v[192:193]
	s_mov_b32 m0, s55
	s_add_i32 s60, s55, 0x2000
	global_load_lds_dwordx4 v[134:135], off
	v_lshl_add_u64 v[134:135], s[72:73], 0, v[132:133]
	s_mov_b32 m0, s60
	v_lshl_add_u64 v[194:195], s[80:81], 0, v[128:129]
	global_load_lds_dwordx4 v[134:135], off
	v_lshl_add_u64 v[134:135], v[194:195], 0, s[74:75]
	s_mov_b32 m0, s35
	v_lshl_add_u64 v[196:197], s[80:81], 0, v[130:131]
	global_load_lds_dwordx4 v[134:135], off
	v_lshl_add_u64 v[134:135], v[196:197], 0, s[74:75]
	s_mov_b32 m0, s38
	s_nop 0
	global_load_lds_dwordx4 v[134:135], off
	s_waitcnt vmcnt(8)
	s_waitcnt lgkmcnt(0)
	s_barrier
; #define PG8_STAGE(bufoff, gbase, voff) do { _Pragma("unroll") for (int _i = 0; _i < 2; ++_i) \
;         __builtin_amdgcn_global_load_lds((const unsigned*)((const char*)(gbase) + (voff)[_i]), (PG8_LAS unsigned*)(lds + (bufoff) + ldsw + _i * 8192), 16, 0, 0); } while (0)
; #define PG8_LDA(dst, b, h) do { _Pragma("unroll") for (int m = 0; m < 4; ++m) _Pragma("unroll") for (int k = 0; k < 2; ++k) dst[m][k] = *(const PG8_LAS bf16x8*)(lds + PG8_SA(b, h) + aoff + m * 2048 + k * 1024); } while (0)
; #define PG8_LDB(dst, b, h) do { _Pragma("unroll") for (int n = 0; n < 2; ++n) _Pragma("unroll") for (int k = 0; k < 2; ++k) dst[n][k] = *(const PG8_LAS bf16x8*)(lds + PG8_SB(b, h) + boff + n * 2048 + k * 1024); } while (0)
; #define PG8_MMA(ai, bj, At, Bt) do { __builtin_amdgcn_s_setprio(1); _Pragma("unroll") for (int m = 0; m < 4; ++m) _Pragma("unroll") for (int n = 0; n < 2; ++n) _Pragma("unroll") for (int k = 0; k < 2; ++k) \
;         acc[ai][bj][m][n] = __builtin_amdgcn_mfma_f32_16x16x32_bf16(Bt[n][k], At[m][k], acc[ai][bj][m][n], 0, 0, 0); __builtin_amdgcn_s_setprio(0); } while (0)
; #define PG8_WAIT_V(n) asm volatile("s_waitcnt vmcnt(" #n ")" ::: "memory")
; #define PG8_WAIT_L(n) asm volatile("s_waitcnt lgkmcnt(" #n ")" ::: "memory")
; #define PG8_BAR __builtin_amdgcn_s_barrier()
; #define PG8_SCHED __builtin_amdgcn_sched_barrier(0)
; template <class Epi, class Sched, bool ALIGN_EPI = false, bool SP2 = false>
; __device__ __forceinline__ void gemm_phase(PG8_LAS unsigned char* lds, const Gemm g, const Sched& S, const Epi& E, const int tid) {
;     ...
;             PG8_WAIT_V(8); PG8_WAIT_L(0); PG8_BAR; PG8_MMA(1, 0, At, B0); PG8_MMA(1, 1, At, B1); PG8_BAR; PG8_SCHED;
;             PG8_LDB(B0, 1, 0); PG8_LDB(B1, 1, 1); PG8_SCHED; PG8_LDA(At, 1, 0); PG8_STAGE(PG8_SA(0, 1), a2 + hstep, voffA);
;             PG8_WAIT_V(8); PG8_WAIT_L(0); PG8_BAR; PG8_MMA(0, 0, At, B0); PG8_MMA(0, 1, At, B1); PG8_BAR; PG8_SCHED;
;             PG8_LDA(At, 1, 1); PG8_STAGE(PG8_SB(1, 0), b3, voffB); PG8_STAGE(PG8_SB(1, 1), b3 + hstep, voffB); PG8_STAGE(PG8_SA(1, 0), a3, voffA);
	s_setprio 1
	s_waitcnt lgkmcnt(0)
	v_mfma_f32_16x16x32_bf16 v[134:137], v[0:3], v[60:63], 0
	v_mfma_f32_16x16x32_bf16 v[146:149], v[0:3], v[104:107], 0
	v_mfma_f32_16x16x32_bf16 v[154:157], v[0:3], v[112:115], 0
	v_mfma_f32_16x16x32_bf16 v[0:3], v[0:3], v[120:123], 0
	v_mfma_f32_16x16x32_bf16 v[134:137], v[4:7], v[100:103], v[134:137]
	v_mfma_f32_16x16x32_bf16 v[146:149], v[4:7], v[108:111], v[146:149]
	v_mfma_f32_16x16x32_bf16 v[154:157], v[4:7], v[116:119], v[154:157]
	v_mfma_f32_16x16x32_bf16 v[0:3], v[4:7], v[124:127], v[0:3]
	v_mfma_f32_16x16x32_bf16 v[4:7], v[8:11], v[120:123], 0
	v_mfma_f32_16x16x32_bf16 v[142:145], v[8:11], v[60:63], 0
	v_mfma_f32_16x16x32_bf16 v[150:153], v[8:11], v[104:107], 0
	v_mfma_f32_16x16x32_bf16 v[158:161], v[8:11], v[112:115], 0
	v_mfma_f32_16x16x32_bf16 v[4:7], v[12:15], v[124:127], v[4:7]
	v_mfma_f32_16x16x32_bf16 v[142:145], v[12:15], v[100:103], v[142:145]
	v_mfma_f32_16x16x32_bf16 v[150:153], v[12:15], v[108:111], v[150:153]
	v_mfma_f32_16x16x32_bf16 v[158:161], v[12:15], v[116:119], v[158:161]
	s_setprio 0
	s_setprio 1
	v_mfma_f32_16x16x32_bf16 v[8:11], v[16:19], v[60:63], 0
	v_mfma_f32_16x16x32_bf16 v[12:15], v[24:27], v[60:63], 0
	v_mfma_f32_16x16x32_bf16 v[8:11], v[20:23], v[100:103], v[8:11]
	v_mfma_f32_16x16x32_bf16 v[12:15], v[28:31], v[100:103], v[12:15]
	v_mfma_f32_16x16x32_bf16 v[60:63], v[16:19], v[104:107], 0
	v_mfma_f32_16x16x32_bf16 v[100:103], v[24:27], v[104:107], 0
	v_mfma_f32_16x16x32_bf16 v[104:107], v[16:19], v[112:115], 0
	v_mfma_f32_16x16x32_bf16 v[16:19], v[16:19], v[120:123], 0
	v_mfma_f32_16x16x32_bf16 v[60:63], v[20:23], v[108:111], v[60:63]
	v_mfma_f32_16x16x32_bf16 v[100:103], v[28:31], v[108:111], v[100:103]
	v_mfma_f32_16x16x32_bf16 v[104:107], v[20:23], v[116:119], v[104:107]
	v_mfma_f32_16x16x32_bf16 v[108:111], v[24:27], v[112:115], 0
	s_barrier
	v_mfma_f32_16x16x32_bf16 v[16:19], v[20:23], v[124:127], v[16:19]
	v_mfma_f32_16x16x32_bf16 v[20:23], v[24:27], v[120:123], 0
	v_mfma_f32_16x16x32_bf16 v[108:111], v[28:31], v[116:119], v[108:111]
	v_mfma_f32_16x16x32_bf16 v[20:23], v[28:31], v[124:127], v[20:23]
	s_setprio 0
	s_add_i32 s74, 0, 0x18000
	s_add_i32 s75, 0, 0x1c000
	v_add_u32_e32 v206, s74, v140
	v_add_u32_e32 v207, s75, v140
	ds_read_b128 v[24:27], v206
	ds_read_b128 v[28:31], v206 offset:1024
	ds_read_b128 v[112:115], v206 offset:2048
	ds_read_b128 v[116:119], v206 offset:3072
	ds_read_b128 v[120:123], v207
	ds_read_b128 v[124:127], v207 offset:1024
	ds_read_b128 v[162:165], v207 offset:2048
	ds_read_b128 v[166:169], v207 offset:3072
	s_add_u32 s72, s80, 0x10100
	s_addc_u32 s73, s81, 0
	s_mov_b32 m0, s40
	v_lshl_add_u64 v[202:203], s[72:73], 0, v[128:129]
	ds_read_b128 v[170:173], v141 offset:32768
	ds_read_b128 v[174:177], v141 offset:33792
	ds_read_b128 v[178:181], v141 offset:34816
	ds_read_b128 v[182:185], v141 offset:35840
	ds_read_b128 v[186:189], v141 offset:36864
	ds_read_b128 v[212:215], v141 offset:37888
	ds_read_b128 v[216:219], v141 offset:38912
	ds_read_b128 v[232:235], v141 offset:39936
	global_load_lds_dwordx4 v[202:203], off
	v_lshl_add_u64 v[202:203], s[72:73], 0, v[130:131]
	s_mov_b32 m0, s41
	s_nop 0
	global_load_lds_dwordx4 v[202:203], off
	s_waitcnt vmcnt(8)
	s_waitcnt lgkmcnt(0)
	s_barrier
	s_setprio 1
	s_waitcnt lgkmcnt(0)
	v_mfma_f32_16x16x32_bf16 v[64:67], v[24:27], v[170:173], v[64:67]
	v_mfma_f32_16x16x32_bf16 v[68:71], v[112:115], v[170:173], v[68:71]
	v_mfma_f32_16x16x32_bf16 v[72:75], v[24:27], v[178:181], v[72:75]
	v_mfma_f32_16x16x32_bf16 v[76:79], v[112:115], v[178:181], v[76:79]
	v_mfma_f32_16x16x32_bf16 v[80:83], v[24:27], v[186:189], v[80:83]
	v_mfma_f32_16x16x32_bf16 v[84:87], v[112:115], v[186:189], v[84:87]
	v_mfma_f32_16x16x32_bf16 v[88:91], v[24:27], v[216:219], v[88:91]
	v_mfma_f32_16x16x32_bf16 v[92:95], v[112:115], v[216:219], v[92:95]
	v_mfma_f32_16x16x32_bf16 v[64:67], v[28:31], v[174:177], v[64:67]
	v_mfma_f32_16x16x32_bf16 v[68:71], v[116:119], v[174:177], v[68:71]
	v_mfma_f32_16x16x32_bf16 v[72:75], v[28:31], v[182:185], v[72:75]
	v_mfma_f32_16x16x32_bf16 v[76:79], v[116:119], v[182:185], v[76:79]
	v_mfma_f32_16x16x32_bf16 v[80:83], v[28:31], v[212:215], v[80:83]
	v_mfma_f32_16x16x32_bf16 v[84:87], v[116:119], v[212:215], v[84:87]
	v_mfma_f32_16x16x32_bf16 v[88:91], v[28:31], v[232:235], v[88:91]
	v_mfma_f32_16x16x32_bf16 v[92:95], v[116:119], v[232:235], v[92:95]
	s_setprio 0
	s_setprio 1
	v_mfma_f32_16x16x32_bf16 v[96:99], v[120:123], v[170:173], v[96:99]
	v_mfma_f32_16x16x32_bf16 v[32:35], v[162:165], v[170:173], v[32:35]
	v_mfma_f32_16x16x32_bf16 v[36:39], v[120:123], v[178:181], v[36:39]
	v_mfma_f32_16x16x32_bf16 v[40:43], v[162:165], v[178:181], v[40:43]
	v_mfma_f32_16x16x32_bf16 v[44:47], v[120:123], v[186:189], v[44:47]
	v_mfma_f32_16x16x32_bf16 v[48:51], v[162:165], v[186:189], v[48:51]
	v_mfma_f32_16x16x32_bf16 v[52:55], v[120:123], v[216:219], v[52:55]
	v_mfma_f32_16x16x32_bf16 v[56:59], v[162:165], v[216:219], v[56:59]
	v_mfma_f32_16x16x32_bf16 v[96:99], v[124:127], v[174:177], v[96:99]
	v_mfma_f32_16x16x32_bf16 v[32:35], v[166:169], v[174:177], v[32:35]
	v_mfma_f32_16x16x32_bf16 v[36:39], v[124:127], v[182:185], v[36:39]
	v_mfma_f32_16x16x32_bf16 v[40:43], v[166:169], v[182:185], v[40:43]
	s_barrier
; #define PG8_STAGE(bufoff, gbase, voff) do { _Pragma("unroll") for (int _i = 0; _i < 2; ++_i) \
;         __builtin_amdgcn_global_load_lds((const unsigned*)((const char*)(gbase) + (voff)[_i]), (PG8_LAS unsigned*)(lds + (bufoff) + ldsw + _i * 8192), 16, 0, 0); } while (0)
; #define PG8_LDA(dst, b, h) do { _Pragma("unroll") for (int m = 0; m < 4; ++m) _Pragma("unroll") for (int k = 0; k < 2; ++k) dst[m][k] = *(const PG8_LAS bf16x8*)(lds + PG8_SA(b, h) + aoff + m * 2048 + k * 1024); } while (0)
; #define PG8_LDB(dst, b, h) do { _Pragma("unroll") for (int n = 0; n < 2; ++n) _Pragma("unroll") for (int k = 0; k < 2; ++k) dst[n][k] = *(const PG8_LAS bf16x8*)(lds + PG8_SB(b, h) + boff + n * 2048 + k * 1024); } while (0)
; #define PG8_MMA(ai, bj, At, Bt) do { __builtin_amdgcn_s_setprio(1); _Pragma("unroll") for (int m = 0; m < 4; ++m) _Pragma("unroll") for (int n = 0; n < 2; ++n) _Pragma("unroll") for (int k = 0; k < 2; ++k) \
;         acc[ai][bj][m][n] = __builtin_amdgcn_mfma_f32_16x16x32_bf16(Bt[n][k], At[m][k], acc[ai][bj][m][n], 0, 0, 0); __builtin_amdgcn_s_setprio(0); } while (0)
; #define PG8_WAIT_V(n) asm volatile("s_waitcnt vmcnt(" #n ")" ::: "memory")
; #define PG8_WAIT_L(n) asm volatile("s_waitcnt lgkmcnt(" #n ")" ::: "memory")
; #define PG8_BAR __builtin_amdgcn_s_barrier()
; #define PG8_SCHED __builtin_amdgcn_sched_barrier(0)
; template <class Epi, class Sched, bool ALIGN_EPI = false, bool SP2 = false>
; __device__ __forceinline__ void gemm_phase(PG8_LAS unsigned char* lds, const Gemm g, const Sched& S, const Epi& E, const int tid) {
;     ...
;             PG8_LDB(B0, 0, 0); PG8_LDB(B1, 0, 1); PG8_SCHED; PG8_LDA(At, 0, 0); PG8_STAGE(PG8_SA(1, 1), a1 + hstep, voffA);
;             PG8_WAIT_V(8); PG8_WAIT_L(0); PG8_BAR; PG8_MMA(0, 0, At, B0); PG8_MMA(0, 1, At, B1); PG8_BAR; PG8_SCHED;
;     ...
;             PG8_WAIT_V(8); PG8_WAIT_L(0); PG8_BAR; PG8_MMA(0, 0, At, B0); PG8_MMA(0, 1, At, B1); PG8_BAR; PG8_SCHED;
;             PG8_LDA(At, 1, 1); PG8_STAGE(PG8_SB(1, 0), b3, voffB); PG8_STAGE(PG8_SB(1, 1), b3 + hstep, voffB); PG8_STAGE(PG8_SA(1, 0), a3, voffA);
;             PG8_WAIT_V(8); PG8_WAIT_L(0); PG8_BAR; PG8_MMA(1, 0, At, B0); PG8_MMA(1, 1, At, B1); PG8_BAR; PG8_SCHED;
	v_mfma_f32_16x16x32_bf16 v[44:47], v[124:127], v[212:215], v[44:47]
	v_mfma_f32_16x16x32_bf16 v[48:51], v[166:169], v[212:215], v[48:51]
	v_mfma_f32_16x16x32_bf16 v[52:55], v[124:127], v[232:235], v[52:55]
	v_mfma_f32_16x16x32_bf16 v[56:59], v[166:169], v[232:235], v[56:59]
	s_setprio 0
	s_add_i32 s74, s74, s34
	s_mov_b64 s[88:89], 0x180
	s_add_i32 s70, s74, 0x2000
	v_lshl_add_u64 v[138:139], v[138:139], 0, s[88:89]
	s_mov_b32 m0, s74
	s_add_u32 s76, s82, 0x10180
	ds_read_b128 v[170:173], v141 offset:49152
	ds_read_b128 v[174:177], v141 offset:50176
	ds_read_b128 v[178:181], v141 offset:51200
	ds_read_b128 v[182:185], v141 offset:52224
	ds_read_b128 v[186:189], v141 offset:53248
	ds_read_b128 v[212:215], v141 offset:54272
	ds_read_b128 v[216:219], v141 offset:55296
	ds_read_b128 v[232:235], v141 offset:56320
	global_load_lds_dwordx4 v[138:139], off
	v_lshl_add_u64 v[138:139], v[190:191], 0, s[88:89]
	s_mov_b32 m0, s70
	s_addc_u32 s77, s83, 0
	s_add_i32 s72, s75, s34
	global_load_lds_dwordx4 v[138:139], off
	v_lshl_add_u64 v[138:139], s[76:77], 0, v[192:193]
	s_mov_b32 m0, s72
	s_add_i32 s73, s72, 0x2000
	global_load_lds_dwordx4 v[138:139], off
	v_lshl_add_u64 v[138:139], s[76:77], 0, v[132:133]
	s_mov_b32 m0, s73
	s_nop 0
	global_load_lds_dwordx4 v[138:139], off
	v_lshl_add_u64 v[138:139], v[194:195], 0, s[88:89]
	s_mov_b32 m0, s46
	s_nop 0
	global_load_lds_dwordx4 v[138:139], off
	v_lshl_add_u64 v[138:139], v[196:197], 0, s[88:89]
	s_mov_b32 m0, s47
	s_nop 0
	global_load_lds_dwordx4 v[138:139], off
	s_waitcnt vmcnt(8)
	s_waitcnt lgkmcnt(0)
	s_barrier
	s_setprio 1
	s_waitcnt lgkmcnt(0)
	v_mfma_f32_16x16x32_bf16 v[0:3], v[24:27], v[216:219], v[0:3]
	v_mfma_f32_16x16x32_bf16 v[4:7], v[112:115], v[216:219], v[4:7]
	v_mfma_f32_16x16x32_bf16 v[134:137], v[24:27], v[170:173], v[134:137]
	v_mfma_f32_16x16x32_bf16 v[142:145], v[112:115], v[170:173], v[142:145]
	v_mfma_f32_16x16x32_bf16 v[146:149], v[24:27], v[178:181], v[146:149]
	v_mfma_f32_16x16x32_bf16 v[150:153], v[112:115], v[178:181], v[150:153]
	v_mfma_f32_16x16x32_bf16 v[154:157], v[24:27], v[186:189], v[154:157]
	v_mfma_f32_16x16x32_bf16 v[158:161], v[112:115], v[186:189], v[158:161]
	v_mfma_f32_16x16x32_bf16 v[0:3], v[28:31], v[232:235], v[0:3]
	v_mfma_f32_16x16x32_bf16 v[4:7], v[116:119], v[232:235], v[4:7]
	v_mfma_f32_16x16x32_bf16 v[134:137], v[28:31], v[174:177], v[134:137]
	v_mfma_f32_16x16x32_bf16 v[142:145], v[116:119], v[174:177], v[142:145]
	v_mfma_f32_16x16x32_bf16 v[146:149], v[28:31], v[182:185], v[146:149]
	v_mfma_f32_16x16x32_bf16 v[150:153], v[116:119], v[182:185], v[150:153]
	v_mfma_f32_16x16x32_bf16 v[154:157], v[28:31], v[212:215], v[154:157]
	v_mfma_f32_16x16x32_bf16 v[158:161], v[116:119], v[212:215], v[158:161]
	s_setprio 0
	s_setprio 1
	v_mfma_f32_16x16x32_bf16 v[8:11], v[120:123], v[170:173], v[8:11]
	v_mfma_f32_16x16x32_bf16 v[12:15], v[162:165], v[170:173], v[12:15]
	v_mfma_f32_16x16x32_bf16 v[24:27], v[120:123], v[178:181], v[60:63]
	v_mfma_f32_16x16x32_bf16 v[28:31], v[162:165], v[178:181], v[100:103]
	v_mfma_f32_16x16x32_bf16 v[60:63], v[120:123], v[186:189], v[104:107]
	v_mfma_f32_16x16x32_bf16 v[100:103], v[162:165], v[186:189], v[108:111]
	v_mfma_f32_16x16x32_bf16 v[16:19], v[120:123], v[216:219], v[16:19]
	v_mfma_f32_16x16x32_bf16 v[20:23], v[162:165], v[216:219], v[20:23]
	v_mfma_f32_16x16x32_bf16 v[8:11], v[124:127], v[174:177], v[8:11]
	v_mfma_f32_16x16x32_bf16 v[12:15], v[166:169], v[174:177], v[12:15]
	v_mfma_f32_16x16x32_bf16 v[24:27], v[124:127], v[182:185], v[24:27]
	v_mfma_f32_16x16x32_bf16 v[28:31], v[166:169], v[182:185], v[28:31]
	s_barrier
	v_mfma_f32_16x16x32_bf16 v[60:63], v[124:127], v[212:215], v[60:63]
	v_mfma_f32_16x16x32_bf16 v[100:103], v[166:169], v[212:215], v[100:103]
	v_mfma_f32_16x16x32_bf16 v[16:19], v[124:127], v[232:235], v[16:19]
	v_mfma_f32_16x16x32_bf16 v[20:23], v[166:169], v[232:235], v[20:23]
	s_setprio 0
	ds_read_b128 v[104:107], v204
	ds_read_b128 v[108:111], v204 offset:1024
	ds_read_b128 v[112:115], v204 offset:2048
	ds_read_b128 v[116:119], v204 offset:3072
	ds_read_b128 v[120:123], v205
	ds_read_b128 v[124:127], v205 offset:1024
	ds_read_b128 v[162:165], v205 offset:2048
	ds_read_b128 v[166:169], v205 offset:3072
	s_add_u32 s76, s80, 0x10180
	s_addc_u32 s77, s81, 0
	s_mov_b32 m0, s71
	v_lshl_add_u64 v[138:139], s[76:77], 0, v[128:129]
	ds_read_b128 v[170:173], v141
	ds_read_b128 v[174:177], v141 offset:1024
	ds_read_b128 v[178:181], v141 offset:2048
	ds_read_b128 v[182:185], v141 offset:3072
	ds_read_b128 v[186:189], v141 offset:4096
	ds_read_b128 v[212:215], v141 offset:5120
	ds_read_b128 v[216:219], v141 offset:6144
	ds_read_b128 v[232:235], v141 offset:7168
	global_load_lds_dwordx4 v[138:139], off
	v_lshl_add_u64 v[138:139], s[76:77], 0, v[130:131]
	s_mov_b32 m0, s21
	s_nop 0
	global_load_lds_dwordx4 v[138:139], off
	s_waitcnt vmcnt(8)
	s_waitcnt lgkmcnt(0)
	s_barrier
; #define PG8_STAGE(bufoff, gbase, voff) do { _Pragma("unroll") for (int _i = 0; _i < 2; ++_i) \
;         __builtin_amdgcn_global_load_lds((const unsigned*)((const char*)(gbase) + (voff)[_i]), (PG8_LAS unsigned*)(lds + (bufoff) + ldsw + _i * 8192), 16, 0, 0); } while (0)
; #define PG8_LDA(dst, b, h) do { _Pragma("unroll") for (int m = 0; m < 4; ++m) _Pragma("unroll") for (int k = 0; k < 2; ++k) dst[m][k] = *(const PG8_LAS bf16x8*)(lds + PG8_SA(b, h) + aoff + m * 2048 + k * 1024); } while (0)
; #define PG8_LDB(dst, b, h) do { _Pragma("unroll") for (int n = 0; n < 2; ++n) _Pragma("unroll") for (int k = 0; k < 2; ++k) dst[n][k] = *(const PG8_LAS bf16x8*)(lds + PG8_SB(b, h) + boff + n * 2048 + k * 1024); } while (0)
; #define PG8_MMA(ai, bj, At, Bt) do { __builtin_amdgcn_s_setprio(1); _Pragma("unroll") for (int m = 0; m < 4; ++m) _Pragma("unroll") for (int n = 0; n < 2; ++n) _Pragma("unroll") for (int k = 0; k < 2; ++k) \
;         acc[ai][bj][m][n] = __builtin_amdgcn_mfma_f32_16x16x32_bf16(Bt[n][k], At[m][k], acc[ai][bj][m][n], 0, 0, 0); __builtin_amdgcn_s_setprio(0); } while (0)
; #define PG8_WAIT_V(n) asm volatile("s_waitcnt vmcnt(" #n ")" ::: "memory")
; #define PG8_WAIT_L(n) asm volatile("s_waitcnt lgkmcnt(" #n ")" ::: "memory")
; #define PG8_BAR __builtin_amdgcn_s_barrier()
; #define PG8_SCHED __builtin_amdgcn_sched_barrier(0)
; template <class Epi, class Sched, bool ALIGN_EPI = false, bool SP2 = false>
; __device__ __forceinline__ void gemm_phase(PG8_LAS unsigned char* lds, const Gemm g, const Sched& S, const Epi& E, const int tid) {
;     ...
;             PG8_LDB(B0, 0, 0); PG8_LDB(B1, 0, 1); PG8_SCHED; PG8_LDA(At, 0, 0); PG8_STAGE(PG8_SA(1, 1), a1 + hstep, voffA);
;             PG8_WAIT_V(8); PG8_WAIT_L(0); PG8_BAR; PG8_MMA(0, 0, At, B0); PG8_MMA(0, 1, At, B1); PG8_BAR; PG8_SCHED;
;             PG8_LDA(At, 0, 1); PG8_STAGE(PG8_SB(0, 0), b2, voffB); PG8_STAGE(PG8_SB(0, 1), b2 + hstep, voffB); PG8_STAGE(PG8_SA(0, 0), a2, voffA);
;             PG8_WAIT_V(8); PG8_WAIT_L(0); PG8_BAR; PG8_MMA(1, 0, At, B0); PG8_MMA(1, 1, At, B1); PG8_BAR; PG8_SCHED;
;             PG8_LDB(B0, 1, 0); PG8_LDB(B1, 1, 1); PG8_SCHED; PG8_LDA(At, 1, 0); PG8_STAGE(PG8_SA(0, 1), a2 + hstep, voffA);
;             PG8_WAIT_V(8); PG8_WAIT_L(0); PG8_BAR; PG8_MMA(0, 0, At, B0); PG8_MMA(0, 1, At, B1); PG8_BAR; PG8_SCHED;
	s_setprio 1
	s_waitcnt lgkmcnt(0)
	v_mfma_f32_16x16x32_bf16 v[64:67], v[104:107], v[170:173], v[64:67]
	v_mfma_f32_16x16x32_bf16 v[68:71], v[112:115], v[170:173], v[68:71]
	v_mfma_f32_16x16x32_bf16 v[72:75], v[104:107], v[178:181], v[72:75]
	v_mfma_f32_16x16x32_bf16 v[76:79], v[112:115], v[178:181], v[76:79]
	v_mfma_f32_16x16x32_bf16 v[80:83], v[104:107], v[186:189], v[80:83]
	v_mfma_f32_16x16x32_bf16 v[84:87], v[112:115], v[186:189], v[84:87]
	v_mfma_f32_16x16x32_bf16 v[88:91], v[104:107], v[216:219], v[88:91]
	v_mfma_f32_16x16x32_bf16 v[64:67], v[108:111], v[174:177], v[64:67]
	v_mfma_f32_16x16x32_bf16 v[68:71], v[116:119], v[174:177], v[68:71]
	v_mfma_f32_16x16x32_bf16 v[72:75], v[108:111], v[182:185], v[72:75]
	v_mfma_f32_16x16x32_bf16 v[76:79], v[116:119], v[182:185], v[76:79]
	v_mfma_f32_16x16x32_bf16 v[80:83], v[108:111], v[212:215], v[80:83]
	v_mfma_f32_16x16x32_bf16 v[84:87], v[116:119], v[212:215], v[84:87]
	v_mfma_f32_16x16x32_bf16 v[236:239], v[108:111], v[232:235], v[88:91]
	v_mfma_f32_16x16x32_bf16 v[88:91], v[112:115], v[216:219], v[92:95]
	v_mfma_f32_16x16x32_bf16 v[240:243], v[116:119], v[232:235], v[88:91]
	s_setprio 0
	s_setprio 1
	v_mfma_f32_16x16x32_bf16 v[88:91], v[120:123], v[170:173], v[96:99]
	v_mfma_f32_16x16x32_bf16 v[32:35], v[162:165], v[170:173], v[32:35]
	v_mfma_f32_16x16x32_bf16 v[36:39], v[120:123], v[178:181], v[36:39]
	v_mfma_f32_16x16x32_bf16 v[40:43], v[162:165], v[178:181], v[40:43]
	v_mfma_f32_16x16x32_bf16 v[44:47], v[120:123], v[186:189], v[44:47]
	v_mfma_f32_16x16x32_bf16 v[48:51], v[162:165], v[186:189], v[48:51]
	v_mfma_f32_16x16x32_bf16 v[52:55], v[120:123], v[216:219], v[52:55]
	v_mfma_f32_16x16x32_bf16 v[56:59], v[162:165], v[216:219], v[56:59]
	v_mfma_f32_16x16x32_bf16 v[96:99], v[124:127], v[174:177], v[88:91]
	v_mfma_f32_16x16x32_bf16 v[32:35], v[166:169], v[174:177], v[32:35]
	v_mfma_f32_16x16x32_bf16 v[36:39], v[124:127], v[182:185], v[36:39]
	v_mfma_f32_16x16x32_bf16 v[40:43], v[166:169], v[182:185], v[40:43]
	s_barrier
	v_mfma_f32_16x16x32_bf16 v[44:47], v[124:127], v[212:215], v[44:47]
	v_mfma_f32_16x16x32_bf16 v[48:51], v[166:169], v[212:215], v[48:51]
	v_mfma_f32_16x16x32_bf16 v[52:55], v[124:127], v[232:235], v[52:55]
	v_mfma_f32_16x16x32_bf16 v[56:59], v[166:169], v[232:235], v[56:59]
	s_setprio 0
	s_mov_b32 m0, s62
	v_lshl_add_u64 v[138:139], s[84:85], 0, v[192:193]
	s_add_u32 s76, s84, 0x10000
	ds_read_b128 v[88:91], v141 offset:16384
	ds_read_b128 v[92:95], v141 offset:17408
	ds_read_b128 v[170:173], v141 offset:18432
	ds_read_b128 v[174:177], v141 offset:19456
	ds_read_b128 v[178:181], v141 offset:20480
	ds_read_b128 v[182:185], v141 offset:21504
	ds_read_b128 v[186:189], v141 offset:22528
	ds_read_b128 v[212:215], v141 offset:23552
	global_load_lds_dwordx4 v[138:139], off
	v_lshl_add_u64 v[190:191], s[84:85], 0, v[132:133]
	s_mov_b32 m0, s23
	s_addc_u32 s77, s85, 0
	global_load_lds_dwordx4 v[190:191], off
	v_lshl_add_u64 v[194:195], s[76:77], 0, v[192:193]
	s_mov_b32 m0, s55
	v_lshl_add_u64 v[220:221], s[86:87], 0, v[128:129]
	global_load_lds_dwordx4 v[194:195], off
	v_lshl_add_u64 v[194:195], s[76:77], 0, v[132:133]
	s_mov_b32 m0, s60
	v_lshl_add_u64 v[230:231], s[86:87], 0, v[130:131]
	global_load_lds_dwordx4 v[194:195], off
	s_mov_b32 m0, s35
	s_nop 0
	global_load_lds_dwordx4 v[220:221], off
	s_mov_b32 m0, s38
	s_nop 0
	global_load_lds_dwordx4 v[230:231], off
	s_waitcnt vmcnt(8)
	s_waitcnt lgkmcnt(0)
	s_barrier
	s_setprio 1
	s_waitcnt lgkmcnt(0)
	v_mfma_f32_16x16x32_bf16 v[0:3], v[104:107], v[186:189], v[0:3]
	v_mfma_f32_16x16x32_bf16 v[4:7], v[112:115], v[186:189], v[4:7]
	v_mfma_f32_16x16x32_bf16 v[134:137], v[104:107], v[88:91], v[134:137]
	v_mfma_f32_16x16x32_bf16 v[142:145], v[112:115], v[88:91], v[142:145]
	v_mfma_f32_16x16x32_bf16 v[146:149], v[104:107], v[170:173], v[146:149]
	v_mfma_f32_16x16x32_bf16 v[150:153], v[112:115], v[170:173], v[150:153]
	v_mfma_f32_16x16x32_bf16 v[154:157], v[104:107], v[178:181], v[154:157]
	v_mfma_f32_16x16x32_bf16 v[158:161], v[112:115], v[178:181], v[158:161]
	v_mfma_f32_16x16x32_bf16 v[0:3], v[108:111], v[212:215], v[0:3]
	v_mfma_f32_16x16x32_bf16 v[4:7], v[116:119], v[212:215], v[4:7]
	v_mfma_f32_16x16x32_bf16 v[134:137], v[108:111], v[92:95], v[134:137]
	v_mfma_f32_16x16x32_bf16 v[142:145], v[116:119], v[92:95], v[142:145]
	v_mfma_f32_16x16x32_bf16 v[146:149], v[108:111], v[174:177], v[146:149]
	v_mfma_f32_16x16x32_bf16 v[150:153], v[116:119], v[174:177], v[150:153]
	v_mfma_f32_16x16x32_bf16 v[154:157], v[108:111], v[182:185], v[154:157]
	v_mfma_f32_16x16x32_bf16 v[158:161], v[116:119], v[182:185], v[158:161]
	s_setprio 0
	s_setprio 1
	v_mfma_f32_16x16x32_bf16 v[8:11], v[120:123], v[88:91], v[8:11]
	v_mfma_f32_16x16x32_bf16 v[216:219], v[124:127], v[92:95], v[8:11]
	v_mfma_f32_16x16x32_bf16 v[8:11], v[162:165], v[88:91], v[12:15]
	v_mfma_f32_16x16x32_bf16 v[232:235], v[166:169], v[92:95], v[8:11]
	v_mfma_f32_16x16x32_bf16 v[8:11], v[120:123], v[170:173], v[24:27]
	v_mfma_f32_16x16x32_bf16 v[244:247], v[124:127], v[174:177], v[8:11]
	v_mfma_f32_16x16x32_bf16 v[8:11], v[162:165], v[170:173], v[28:31]
	v_mfma_f32_16x16x32_bf16 v[170:173], v[166:169], v[174:177], v[8:11]
	v_mfma_f32_16x16x32_bf16 v[8:11], v[120:123], v[178:181], v[60:63]
	v_mfma_f32_16x16x32_bf16 v[174:177], v[124:127], v[182:185], v[8:11]
	v_mfma_f32_16x16x32_bf16 v[8:11], v[162:165], v[178:181], v[100:103]
	v_mfma_f32_16x16x32_bf16 v[178:181], v[166:169], v[182:185], v[8:11]
	s_barrier
; #define PG8_STAGE(bufoff, gbase, voff) do { _Pragma("unroll") for (int _i = 0; _i < 2; ++_i) \
;         __builtin_amdgcn_global_load_lds((const unsigned*)((const char*)(gbase) + (voff)[_i]), (PG8_LAS unsigned*)(lds + (bufoff) + ldsw + _i * 8192), 16, 0, 0); } while (0)
; #define PG8_LDA(dst, b, h) do { _Pragma("unroll") for (int m = 0; m < 4; ++m) _Pragma("unroll") for (int k = 0; k < 2; ++k) dst[m][k] = *(const PG8_LAS bf16x8*)(lds + PG8_SA(b, h) + aoff + m * 2048 + k * 1024); } while (0)
; #define PG8_MMA(ai, bj, At, Bt) do { __builtin_amdgcn_s_setprio(1); _Pragma("unroll") for (int m = 0; m < 4; ++m) _Pragma("unroll") for (int n = 0; n < 2; ++n) _Pragma("unroll") for (int k = 0; k < 2; ++k) \
;         acc[ai][bj][m][n] = __builtin_amdgcn_mfma_f32_16x16x32_bf16(Bt[n][k], At[m][k], acc[ai][bj][m][n], 0, 0, 0); __builtin_amdgcn_s_setprio(0); } while (0)
; #define PG8_WAIT_V(n) asm volatile("s_waitcnt vmcnt(" #n ")" ::: "memory")
; #define PG8_WAIT_L(n) asm volatile("s_waitcnt lgkmcnt(" #n ")" ::: "memory")
; #define PG8_BAR __builtin_amdgcn_s_barrier()
; #define PG8_SCHED __builtin_amdgcn_sched_barrier(0)
; template <class Epi, class Sched, bool ALIGN_EPI = false, bool SP2 = false>
; __device__ __forceinline__ void gemm_phase(PG8_LAS unsigned char* lds, const Gemm g, const Sched& S, const Epi& E, const int tid) {
;     ...
;             PG8_WAIT_V(8); PG8_WAIT_L(0); PG8_BAR; PG8_MMA(0, 0, At, B0); PG8_MMA(0, 1, At, B1); PG8_BAR; PG8_SCHED;
;             PG8_LDA(At, 1, 1); PG8_STAGE(PG8_SB(1, 0), b3, voffB); PG8_STAGE(PG8_SB(1, 1), b3 + hstep, voffB); PG8_STAGE(PG8_SA(1, 0), a3, voffA);
;             PG8_WAIT_V(8); PG8_WAIT_L(0); PG8_BAR; PG8_MMA(1, 0, At, B0); PG8_MMA(1, 1, At, B1); PG8_BAR; PG8_SCHED;
;     ...
;         }
;         if constexpr (ALIGN_EPI) { if (wr == 0) PG8_BAR; }
;         if constexpr (!Epi::AFTER_DRAIN) { E(acc, cur, wr, wc, fr, fq); S.done(cur); }
;         if (!has_next) break;
	v_mfma_f32_16x16x32_bf16 v[8:11], v[120:123], v[186:189], v[16:19]
	v_mfma_f32_16x16x32_bf16 v[182:185], v[124:127], v[212:215], v[8:11]
	v_mfma_f32_16x16x32_bf16 v[8:11], v[162:165], v[186:189], v[20:23]
	v_mfma_f32_16x16x32_bf16 v[162:165], v[166:169], v[212:215], v[8:11]
	s_setprio 0
	s_nop 4
	ds_read_b128 v[8:11], v206
	ds_read_b128 v[12:15], v206 offset:1024
	ds_read_b128 v[16:19], v206 offset:2048
	ds_read_b128 v[20:23], v206 offset:3072
	ds_read_b128 v[166:169], v207
	ds_read_b128 v[186:189], v207 offset:1024
	ds_read_b128 v[212:215], v207 offset:2048
	ds_read_b128 v[248:251], v207 offset:3072
	s_add_u32 s76, s86, 0x10000
	s_addc_u32 s77, s87, 0
	s_mov_b32 m0, s40
	v_lshl_add_u64 v[88:89], s[76:77], 0, v[128:129]
	ds_read_b128 v[24:27], v141 offset:32768
	ds_read_b128 v[28:31], v141 offset:33792
	ds_read_b128 v[60:63], v141 offset:34816
	ds_read_b128 v[100:103], v141 offset:35840
	ds_read_b128 v[224:227], v141 offset:36864
	ds_read_b128 v[194:197], v141 offset:37888
	ds_read_b128 v[202:205], v141 offset:38912
	ds_read_b128 v[206:209], v141 offset:39936
	global_load_lds_dwordx4 v[88:89], off
	v_lshl_add_u64 v[88:89], s[76:77], 0, v[130:131]
	s_mov_b32 m0, s41
	s_nop 0
	global_load_lds_dwordx4 v[88:89], off
	s_waitcnt vmcnt(8)
	s_waitcnt lgkmcnt(0)
	s_barrier
	s_setprio 1
	s_waitcnt lgkmcnt(0)
	v_mfma_f32_16x16x32_bf16 v[64:67], v[8:11], v[24:27], v[64:67]
	v_mfma_f32_16x16x32_bf16 v[124:127], v[12:15], v[28:31], v[64:67]
	v_mfma_f32_16x16x32_bf16 v[64:67], v[16:19], v[24:27], v[68:71]
	v_mfma_f32_16x16x32_bf16 v[120:123], v[20:23], v[28:31], v[64:67]
	v_mfma_f32_16x16x32_bf16 v[64:67], v[8:11], v[60:63], v[72:75]
	v_mfma_f32_16x16x32_bf16 v[108:111], v[12:15], v[100:103], v[64:67]
	v_mfma_f32_16x16x32_bf16 v[64:67], v[16:19], v[60:63], v[76:79]
	v_mfma_f32_16x16x32_bf16 v[104:107], v[20:23], v[100:103], v[64:67]
	v_mfma_f32_16x16x32_bf16 v[64:67], v[8:11], v[224:227], v[80:83]
	v_mfma_f32_16x16x32_bf16 v[92:95], v[12:15], v[194:197], v[64:67]
	v_mfma_f32_16x16x32_bf16 v[64:67], v[16:19], v[224:227], v[84:87]
	v_mfma_f32_16x16x32_bf16 v[88:91], v[20:23], v[194:197], v[64:67]
	v_mfma_f32_16x16x32_bf16 v[64:67], v[8:11], v[202:205], v[236:239]
	v_mfma_f32_16x16x32_bf16 v[76:79], v[12:15], v[206:209], v[64:67]
	v_mfma_f32_16x16x32_bf16 v[64:67], v[16:19], v[202:205], v[240:243]
	v_mfma_f32_16x16x32_bf16 v[72:75], v[20:23], v[206:209], v[64:67]
	s_setprio 0
	s_setprio 1
	v_mfma_f32_16x16x32_bf16 v[64:67], v[166:169], v[24:27], v[96:99]
	v_mfma_f32_16x16x32_bf16 v[24:27], v[212:215], v[24:27], v[32:35]
	v_mfma_f32_16x16x32_bf16 v[116:119], v[248:251], v[28:31], v[24:27]
	v_mfma_f32_16x16x32_bf16 v[24:27], v[166:169], v[60:63], v[36:39]
	v_mfma_f32_16x16x32_bf16 v[96:99], v[186:189], v[100:103], v[24:27]
	v_mfma_f32_16x16x32_bf16 v[24:27], v[212:215], v[60:63], v[40:43]
	v_mfma_f32_16x16x32_bf16 v[100:103], v[248:251], v[100:103], v[24:27]
	v_mfma_f32_16x16x32_bf16 v[24:27], v[166:169], v[224:227], v[44:47]
	v_mfma_f32_16x16x32_bf16 v[80:83], v[186:189], v[194:197], v[24:27]
	v_mfma_f32_16x16x32_bf16 v[24:27], v[212:215], v[224:227], v[48:51]
	v_mfma_f32_16x16x32_bf16 v[84:87], v[248:251], v[194:197], v[24:27]
	v_mfma_f32_16x16x32_bf16 v[24:27], v[166:169], v[202:205], v[52:55]
	s_barrier
	v_mfma_f32_16x16x32_bf16 v[60:63], v[186:189], v[206:209], v[24:27]
	v_mfma_f32_16x16x32_bf16 v[24:27], v[212:215], v[202:205], v[56:59]
	v_mfma_f32_16x16x32_bf16 v[112:115], v[186:189], v[28:31], v[64:67]
	v_mfma_f32_16x16x32_bf16 v[64:67], v[248:251], v[206:209], v[24:27]
	s_setprio 0
	s_mov_b32 m0, s74
	s_nop 2
	v_lshl_add_u64 v[24:25], v[138:139], 0, s[36:37]
	ds_read_b128 v[32:35], v141 offset:49152
	ds_read_b128 v[36:39], v141 offset:50176
	ds_read_b128 v[194:197], v141 offset:51200
	ds_read_b128 v[202:205], v141 offset:52224
	ds_read_b128 v[206:209], v141 offset:53248
	ds_read_b128 v[224:227], v141 offset:54272
	ds_read_b128 v[236:239], v141 offset:55296
	ds_read_b128 v[240:243], v141 offset:56320
	global_load_lds_dwordx4 v[24:25], off
	s_mov_b32 m0, s70
	s_add_u32 s70, s84, 0x10080
	v_lshl_add_u64 v[24:25], v[190:191], 0, s[36:37]
	s_addc_u32 s71, s85, 0
	global_load_lds_dwordx4 v[24:25], off
	v_lshl_add_u64 v[24:25], s[70:71], 0, v[192:193]
	s_mov_b32 m0, s72
	s_nop 0
	global_load_lds_dwordx4 v[24:25], off
	v_lshl_add_u64 v[24:25], s[70:71], 0, v[132:133]
	s_mov_b32 m0, s73
	s_nop 0
	global_load_lds_dwordx4 v[24:25], off
	v_lshl_add_u64 v[24:25], v[220:221], 0, s[36:37]
	s_mov_b32 m0, s46
	s_nop 0
	global_load_lds_dwordx4 v[24:25], off
	v_lshl_add_u64 v[24:25], v[230:231], 0, s[36:37]
	s_mov_b32 m0, s47
	s_nop 0
	global_load_lds_dwordx4 v[24:25], off
	s_waitcnt vmcnt(8)
	s_waitcnt lgkmcnt(0)
	s_barrier
	s_setprio 1
	s_waitcnt lgkmcnt(0)
	v_mfma_f32_16x16x32_bf16 v[24:27], v[8:11], v[32:35], v[134:137]
	v_mfma_f32_16x16x32_bf16 v[68:71], v[12:15], v[36:39], v[24:27]
	v_mfma_f32_16x16x32_bf16 v[24:27], v[16:19], v[32:35], v[142:145]
	v_mfma_f32_16x16x32_bf16 v[56:59], v[20:23], v[36:39], v[24:27]
	v_mfma_f32_16x16x32_bf16 v[24:27], v[8:11], v[194:197], v[146:149]
	v_mfma_f32_16x16x32_bf16 v[44:47], v[12:15], v[202:205], v[24:27]
	v_mfma_f32_16x16x32_bf16 v[24:27], v[16:19], v[194:197], v[150:153]
	v_mfma_f32_16x16x32_bf16 v[40:43], v[20:23], v[202:205], v[24:27]
	v_mfma_f32_16x16x32_bf16 v[24:27], v[8:11], v[206:209], v[154:157]
	v_mfma_f32_16x16x32_bf16 v[0:3], v[8:11], v[236:239], v[0:3]
	v_mfma_f32_16x16x32_bf16 v[28:31], v[12:15], v[224:227], v[24:27]
	v_mfma_f32_16x16x32_bf16 v[24:27], v[16:19], v[206:209], v[158:161]
	v_mfma_f32_16x16x32_bf16 v[12:15], v[12:15], v[240:243], v[0:3]
	v_mfma_f32_16x16x32_bf16 v[0:3], v[16:19], v[236:239], v[4:7]
	v_mfma_f32_16x16x32_bf16 v[24:27], v[20:23], v[224:227], v[24:27]
	v_mfma_f32_16x16x32_bf16 v[8:11], v[20:23], v[240:243], v[0:3]
	s_setprio 0
	s_setprio 1
	v_mfma_f32_16x16x32_bf16 v[0:3], v[166:169], v[32:35], v[216:219]
	v_mfma_f32_16x16x32_bf16 v[48:51], v[186:189], v[36:39], v[0:3]
	v_mfma_f32_16x16x32_bf16 v[0:3], v[212:215], v[32:35], v[232:235]
	v_mfma_f32_16x16x32_bf16 v[52:55], v[248:251], v[36:39], v[0:3]
	v_mfma_f32_16x16x32_bf16 v[0:3], v[166:169], v[194:197], v[244:247]
	v_mfma_f32_16x16x32_bf16 v[32:35], v[186:189], v[202:205], v[0:3]
	v_mfma_f32_16x16x32_bf16 v[0:3], v[212:215], v[194:197], v[170:173]
	v_mfma_f32_16x16x32_bf16 v[36:39], v[248:251], v[202:205], v[0:3]
	v_mfma_f32_16x16x32_bf16 v[0:3], v[166:169], v[206:209], v[174:177]
	v_mfma_f32_16x16x32_bf16 v[16:19], v[186:189], v[224:227], v[0:3]
	v_mfma_f32_16x16x32_bf16 v[0:3], v[212:215], v[206:209], v[178:181]
	v_mfma_f32_16x16x32_bf16 v[20:23], v[248:251], v[224:227], v[0:3]
	s_barrier
	v_mfma_f32_16x16x32_bf16 v[0:3], v[166:169], v[236:239], v[182:185]
	v_mfma_f32_16x16x32_bf16 v[4:7], v[212:215], v[236:239], v[162:165]
	v_mfma_f32_16x16x32_bf16 v[0:3], v[186:189], v[240:243], v[0:3]
	v_mfma_f32_16x16x32_bf16 v[4:7], v[248:251], v[240:243], v[4:7]
	s_setprio 0
	s_andn2_b64 vcc, exec, s[16:17]
	s_nop 7
	s_cbranch_vccnz .LBB0_63
	s_barrier

; #define PG8_STAGE(bufoff, gbase, voff) do { _Pragma("unroll") for (int _i = 0; _i < 2; ++_i) \
;         __builtin_amdgcn_global_load_lds((const unsigned*)((const char*)(gbase) + (voff)[_i]), (PG8_LAS unsigned*)(lds + (bufoff) + ldsw + _i * 8192), 16, 0, 0); } while (0)
; #define PG8_LDA(dst, b, h) do { _Pragma("unroll") for (int m = 0; m < 4; ++m) _Pragma("unroll") for (int k = 0; k < 2; ++k) dst[m][k] = *(const PG8_LAS bf16x8*)(lds + PG8_SA(b, h) + aoff + m * 2048 + k * 1024); } while (0)
; #define PG8_LDB(dst, b, h) do { _Pragma("unroll") for (int n = 0; n < 2; ++n) _Pragma("unroll") for (int k = 0; k < 2; ++k) dst[n][k] = *(const PG8_LAS bf16x8*)(lds + PG8_SB(b, h) + boff + n * 2048 + k * 1024); } while (0)
; #define PG8_MMA(ai, bj, At, Bt) do { __builtin_amdgcn_s_setprio(1); _Pragma("unroll") for (int m = 0; m < 4; ++m) _Pragma("unroll") for (int n = 0; n < 2; ++n) _Pragma("unroll") for (int k = 0; k < 2; ++k) \
;         acc[ai][bj][m][n] = __builtin_amdgcn_mfma_f32_16x16x32_bf16(Bt[n][k], At[m][k], acc[ai][bj][m][n], 0, 0, 0); __builtin_amdgcn_s_setprio(0); } while (0)
; #define PG8_WAIT_V(n) asm volatile("s_waitcnt vmcnt(" #n ")" ::: "memory")
; #define PG8_WAIT_L(n) asm volatile("s_waitcnt lgkmcnt(" #n ")" ::: "memory")
; template <class Epi, class Sched, bool ALIGN_EPI = false, bool SP2 = false>
; __device__ __forceinline__ void gemm_phase(PG8_LAS unsigned char* lds, const Gemm g, const Sched& S, const Epi& E, const int tid) {
;     ...
;             const bool last = (t == nt - 2);
;             const char* a1 = cA + (size_t)(t + 1) * kstep;
;             const char* a2 = last ? nA : cA + (size_t)(t + 2) * kstep; const char* b2 = last ? nB : cB + (size_t)(t + 2) * kstep;
;             const char* a3 = a2 + kstep; const char* b3 = b2 + kstep;
;             if (last && has_next) S.a_ready(nxt);
;             if constexpr (SP2) {
;             PG8_LDB(B0, 0, 0); PG8_LDB(B1, 0, 1); PG8_SCHED; PG8_LDA(At, 0, 0); PG8_STAGE(PG8_SA(1, 1), a1 + hstep, voffA);
;             PG8_WAIT_V(8); PG8_WAIT_L(0); PG8_BAR; PG8_MMA(0, 0, At, B0); PG8_MMA(0, 1, At, B1); PG8_BAR; PG8_SCHED;
;             PG8_LDA(At, 0, 1); PG8_STAGE(PG8_SB(0, 0), b2, voffB); PG8_STAGE(PG8_SB(0, 1), b2 + hstep, voffB); PG8_STAGE(PG8_SA(0, 0), a2, voffA);
;             PG8_WAIT_V(8); PG8_WAIT_L(0); PG8_BAR; PG8_MMA(1, 0, At, B0); PG8_MMA(1, 1, At, B1); PG8_BAR; PG8_SCHED;
.LBB0_99:
	s_add_u32 s20, s18, 0x100
	s_addc_u32 s21, s19, 0
	s_add_i32 s73, 0, 0x10000
	s_cmp_eq_u32 s72, 40
	s_cselect_b32 s45, s9, s21
	s_cselect_b32 s44, s8, s20
	s_cselect_b32 s23, s17, s71
	s_cselect_b32 s22, s16, s62
	s_add_i32 s74, 0, 0x14000
	v_add_u32_e32 v152, s73, v138
	v_add_u32_e32 v168, s74, v138
	ds_read_b128 v[140:143], v152
	ds_read_b128 v[144:147], v152 offset:1024
	ds_read_b128 v[148:151], v152 offset:2048
	ds_read_b128 v[152:155], v152 offset:3072
	ds_read_b128 v[156:159], v168
	ds_read_b128 v[160:163], v168 offset:1024
	ds_read_b128 v[164:167], v168 offset:2048
	ds_read_b128 v[168:171], v168 offset:3072
	v_lshl_add_u64 v[194:195], s[18:19], 0, v[134:135]
	s_add_i32 m0, s38, 0xc000
	ds_read_b128 v[172:175], v139
	ds_read_b128 v[176:179], v139 offset:1024
	ds_read_b128 v[180:183], v139 offset:2048
	ds_read_b128 v[184:187], v139 offset:3072
	ds_read_b128 v[188:191], v139 offset:4096
	ds_read_b128 v[212:215], v139 offset:5120
	ds_read_b128 v[216:219], v139 offset:6144
	ds_read_b128 v[232:235], v139 offset:7168
	global_load_lds_dwordx4 v[194:195], off
	v_lshl_add_u64 v[194:195], s[18:19], 0, v[136:137]
	s_add_i32 m0, s38, 0xe000
	s_nop 0
	global_load_lds_dwordx4 v[194:195], off
	s_waitcnt vmcnt(8)
	s_waitcnt lgkmcnt(0)
	s_barrier
	s_setprio 1
	s_waitcnt lgkmcnt(0)
	v_mfma_f32_16x16x32_bf16 v[124:127], v[140:143], v[172:175], v[124:127]
	v_mfma_f32_16x16x32_bf16 v[120:123], v[148:151], v[172:175], v[120:123]
	v_mfma_f32_16x16x32_bf16 v[116:119], v[140:143], v[180:183], v[116:119]
	v_mfma_f32_16x16x32_bf16 v[112:115], v[148:151], v[180:183], v[112:115]
	v_mfma_f32_16x16x32_bf16 v[100:103], v[140:143], v[188:191], v[100:103]
	v_mfma_f32_16x16x32_bf16 v[96:99], v[148:151], v[188:191], v[96:99]
	v_mfma_f32_16x16x32_bf16 v[84:87], v[140:143], v[216:219], v[84:87]
	v_mfma_f32_16x16x32_bf16 v[80:83], v[148:151], v[216:219], v[80:83]
	v_mfma_f32_16x16x32_bf16 v[124:127], v[144:147], v[176:179], v[124:127]
	v_mfma_f32_16x16x32_bf16 v[120:123], v[152:155], v[176:179], v[120:123]
	v_mfma_f32_16x16x32_bf16 v[116:119], v[144:147], v[184:187], v[116:119]
	v_mfma_f32_16x16x32_bf16 v[112:115], v[152:155], v[184:187], v[112:115]
	v_mfma_f32_16x16x32_bf16 v[100:103], v[144:147], v[212:215], v[100:103]
	v_mfma_f32_16x16x32_bf16 v[96:99], v[152:155], v[212:215], v[96:99]
	v_mfma_f32_16x16x32_bf16 v[84:87], v[144:147], v[232:235], v[84:87]
	v_mfma_f32_16x16x32_bf16 v[80:83], v[152:155], v[232:235], v[80:83]
	s_setprio 0
	s_setprio 1
	v_mfma_f32_16x16x32_bf16 v[108:111], v[156:159], v[172:175], v[108:111]
	v_mfma_f32_16x16x32_bf16 v[104:107], v[164:167], v[172:175], v[104:107]
	v_mfma_f32_16x16x32_bf16 v[92:95], v[156:159], v[180:183], v[92:95]
	v_mfma_f32_16x16x32_bf16 v[88:91], v[164:167], v[180:183], v[88:91]
	v_mfma_f32_16x16x32_bf16 v[76:79], v[156:159], v[188:191], v[76:79]
	v_mfma_f32_16x16x32_bf16 v[72:75], v[164:167], v[188:191], v[72:75]
	v_mfma_f32_16x16x32_bf16 v[68:71], v[156:159], v[216:219], v[68:71]
	v_mfma_f32_16x16x32_bf16 v[64:67], v[164:167], v[216:219], v[64:67]
	v_mfma_f32_16x16x32_bf16 v[108:111], v[160:163], v[176:179], v[108:111]
	v_mfma_f32_16x16x32_bf16 v[104:107], v[168:171], v[176:179], v[104:107]
	v_mfma_f32_16x16x32_bf16 v[92:95], v[160:163], v[184:187], v[92:95]
	v_mfma_f32_16x16x32_bf16 v[88:91], v[168:171], v[184:187], v[88:91]
	s_barrier
	v_mfma_f32_16x16x32_bf16 v[76:79], v[160:163], v[212:215], v[76:79]
	v_mfma_f32_16x16x32_bf16 v[72:75], v[168:171], v[212:215], v[72:75]
	v_mfma_f32_16x16x32_bf16 v[68:71], v[160:163], v[232:235], v[68:71]
	v_mfma_f32_16x16x32_bf16 v[64:67], v[168:171], v[232:235], v[64:67]
	s_setprio 0
	s_add_i32 s18, s73, s35
	v_lshl_add_u64 v[194:195], s[22:23], 0, v[192:193]
	s_mov_b32 m0, s18
	ds_read_b128 v[172:175], v139 offset:16384
	ds_read_b128 v[176:179], v139 offset:17408
	ds_read_b128 v[180:183], v139 offset:18432
	ds_read_b128 v[184:187], v139 offset:19456
	ds_read_b128 v[188:191], v139 offset:20480
	ds_read_b128 v[212:215], v139 offset:21504
	ds_read_b128 v[216:219], v139 offset:22528
	ds_read_b128 v[232:235], v139 offset:23552
	global_load_lds_dwordx4 v[194:195], off
	s_add_i32 m0, s18, 0x2000
	s_add_u32 s18, s22, 0xb0000
	v_lshl_add_u64 v[196:197], s[22:23], 0, v[132:133]
	s_addc_u32 s19, s23, 0
	s_add_i32 s73, s74, s35
	global_load_lds_dwordx4 v[196:197], off
	v_lshl_add_u64 v[202:203], s[18:19], 0, v[192:193]
	s_mov_b32 m0, s73
	v_lshl_add_u64 v[204:205], s[44:45], 0, v[130:131]
	global_load_lds_dwordx4 v[202:203], off
	v_lshl_add_u64 v[202:203], s[18:19], 0, v[132:133]
	s_add_i32 m0, s73, 0x2000
	s_nop 0
	global_load_lds_dwordx4 v[202:203], off
	v_lshl_add_u64 v[202:203], s[44:45], 0, v[128:129]
	s_mov_b32 m0, s38
	s_nop 0
	global_load_lds_dwordx4 v[202:203], off
	s_mov_b32 m0, s40
	s_nop 0
	global_load_lds_dwordx4 v[204:205], off
	s_waitcnt vmcnt(8)
	s_waitcnt lgkmcnt(0)
	s_barrier
; #define PG8_STAGE(bufoff, gbase, voff) do { _Pragma("unroll") for (int _i = 0; _i < 2; ++_i) \
;         __builtin_amdgcn_global_load_lds((const unsigned*)((const char*)(gbase) + (voff)[_i]), (PG8_LAS unsigned*)(lds + (bufoff) + ldsw + _i * 8192), 16, 0, 0); } while (0)
; #define PG8_LDA(dst, b, h) do { _Pragma("unroll") for (int m = 0; m < 4; ++m) _Pragma("unroll") for (int k = 0; k < 2; ++k) dst[m][k] = *(const PG8_LAS bf16x8*)(lds + PG8_SA(b, h) + aoff + m * 2048 + k * 1024); } while (0)
; #define PG8_LDB(dst, b, h) do { _Pragma("unroll") for (int n = 0; n < 2; ++n) _Pragma("unroll") for (int k = 0; k < 2; ++k) dst[n][k] = *(const PG8_LAS bf16x8*)(lds + PG8_SB(b, h) + boff + n * 2048 + k * 1024); } while (0)
; #define PG8_MMA(ai, bj, At, Bt) do { __builtin_amdgcn_s_setprio(1); _Pragma("unroll") for (int m = 0; m < 4; ++m) _Pragma("unroll") for (int n = 0; n < 2; ++n) _Pragma("unroll") for (int k = 0; k < 2; ++k) \
;         acc[ai][bj][m][n] = __builtin_amdgcn_mfma_f32_16x16x32_bf16(Bt[n][k], At[m][k], acc[ai][bj][m][n], 0, 0, 0); __builtin_amdgcn_s_setprio(0); } while (0)
; #define PG8_WAIT_V(n) asm volatile("s_waitcnt vmcnt(" #n ")" ::: "memory")
; #define PG8_WAIT_L(n) asm volatile("s_waitcnt lgkmcnt(" #n ")" ::: "memory")
; #define PG8_BAR __builtin_amdgcn_s_barrier()
; #define PG8_SCHED __builtin_amdgcn_sched_barrier(0)
; template <class Epi, class Sched, bool ALIGN_EPI = false, bool SP2 = false>
; __device__ __forceinline__ void gemm_phase(PG8_LAS unsigned char* lds, const Gemm g, const Sched& S, const Epi& E, const int tid) {
;     ...
;             PG8_WAIT_V(8); PG8_WAIT_L(0); PG8_BAR; PG8_MMA(1, 0, At, B0); PG8_MMA(1, 1, At, B1); PG8_BAR; PG8_SCHED;
;             PG8_LDB(B0, 1, 0); PG8_LDB(B1, 1, 1); PG8_SCHED; PG8_LDA(At, 1, 0); PG8_STAGE(PG8_SA(0, 1), a2 + hstep, voffA);
;             PG8_WAIT_V(8); PG8_WAIT_L(0); PG8_BAR; PG8_MMA(0, 0, At, B0); PG8_MMA(0, 1, At, B1); PG8_BAR; PG8_SCHED;
;             PG8_LDA(At, 1, 1); PG8_STAGE(PG8_SB(1, 0), b3, voffB); PG8_STAGE(PG8_SB(1, 1), b3 + hstep, voffB); PG8_STAGE(PG8_SA(1, 0), a3, voffA);
	s_setprio 1
	s_waitcnt lgkmcnt(0)
	v_mfma_f32_16x16x32_bf16 v[60:63], v[140:143], v[172:175], v[60:63]
	v_mfma_f32_16x16x32_bf16 v[56:59], v[148:151], v[172:175], v[56:59]
	v_mfma_f32_16x16x32_bf16 v[52:55], v[140:143], v[180:183], v[52:55]
	v_mfma_f32_16x16x32_bf16 v[48:51], v[148:151], v[180:183], v[48:51]
	v_mfma_f32_16x16x32_bf16 v[36:39], v[140:143], v[188:191], v[36:39]
	v_mfma_f32_16x16x32_bf16 v[32:35], v[148:151], v[188:191], v[32:35]
	v_mfma_f32_16x16x32_bf16 v[20:23], v[140:143], v[216:219], v[20:23]
	v_mfma_f32_16x16x32_bf16 v[16:19], v[148:151], v[216:219], v[16:19]
	v_mfma_f32_16x16x32_bf16 v[60:63], v[144:147], v[176:179], v[60:63]
	v_mfma_f32_16x16x32_bf16 v[56:59], v[152:155], v[176:179], v[56:59]
	v_mfma_f32_16x16x32_bf16 v[52:55], v[144:147], v[184:187], v[52:55]
	v_mfma_f32_16x16x32_bf16 v[48:51], v[152:155], v[184:187], v[48:51]
	v_mfma_f32_16x16x32_bf16 v[36:39], v[144:147], v[212:215], v[36:39]
	v_mfma_f32_16x16x32_bf16 v[32:35], v[152:155], v[212:215], v[32:35]
	v_mfma_f32_16x16x32_bf16 v[20:23], v[144:147], v[232:235], v[20:23]
	v_mfma_f32_16x16x32_bf16 v[16:19], v[152:155], v[232:235], v[16:19]
	s_setprio 0
	s_setprio 1
	v_mfma_f32_16x16x32_bf16 v[44:47], v[156:159], v[172:175], v[44:47]
	v_mfma_f32_16x16x32_bf16 v[40:43], v[164:167], v[172:175], v[40:43]
	v_mfma_f32_16x16x32_bf16 v[28:31], v[156:159], v[180:183], v[28:31]
	v_mfma_f32_16x16x32_bf16 v[24:27], v[164:167], v[180:183], v[24:27]
	v_mfma_f32_16x16x32_bf16 v[12:15], v[156:159], v[188:191], v[12:15]
	v_mfma_f32_16x16x32_bf16 v[8:11], v[164:167], v[188:191], v[8:11]
	v_mfma_f32_16x16x32_bf16 v[4:7], v[156:159], v[216:219], v[4:7]
	v_mfma_f32_16x16x32_bf16 v[0:3], v[164:167], v[216:219], v[0:3]
	v_mfma_f32_16x16x32_bf16 v[44:47], v[160:163], v[176:179], v[44:47]
	v_mfma_f32_16x16x32_bf16 v[40:43], v[168:171], v[176:179], v[40:43]
	v_mfma_f32_16x16x32_bf16 v[28:31], v[160:163], v[184:187], v[28:31]
	v_mfma_f32_16x16x32_bf16 v[24:27], v[168:171], v[184:187], v[24:27]
	s_barrier
	v_mfma_f32_16x16x32_bf16 v[12:15], v[160:163], v[212:215], v[12:15]
	v_mfma_f32_16x16x32_bf16 v[8:11], v[168:171], v[212:215], v[8:11]
	v_mfma_f32_16x16x32_bf16 v[4:7], v[160:163], v[232:235], v[4:7]
	v_mfma_f32_16x16x32_bf16 v[0:3], v[168:171], v[232:235], v[0:3]
	s_setprio 0
	s_add_i32 s73, 0, 0x18000
	s_add_i32 s74, 0, 0x1c000
	v_add_u32_e32 v152, s73, v138
	v_add_u32_e32 v168, s74, v138
	ds_read_b128 v[140:143], v152
	ds_read_b128 v[144:147], v152 offset:1024
	ds_read_b128 v[148:151], v152 offset:2048
	ds_read_b128 v[152:155], v152 offset:3072
	ds_read_b128 v[156:159], v168
	ds_read_b128 v[160:163], v168 offset:1024
	ds_read_b128 v[164:167], v168 offset:2048
	ds_read_b128 v[168:171], v168 offset:3072
	s_add_u32 s18, s44, 0xb0000
	s_addc_u32 s19, s45, 0
	s_mov_b32 m0, s41
	v_lshl_add_u64 v[206:207], s[18:19], 0, v[128:129]
	ds_read_b128 v[172:175], v139 offset:32768
	ds_read_b128 v[176:179], v139 offset:33792
	ds_read_b128 v[180:183], v139 offset:34816
	ds_read_b128 v[184:187], v139 offset:35840
	ds_read_b128 v[188:191], v139 offset:36864
	ds_read_b128 v[212:215], v139 offset:37888
	ds_read_b128 v[216:219], v139 offset:38912
	ds_read_b128 v[232:235], v139 offset:39936
	global_load_lds_dwordx4 v[206:207], off
	v_lshl_add_u64 v[206:207], s[18:19], 0, v[130:131]
	s_mov_b32 m0, s46
	s_nop 0
	global_load_lds_dwordx4 v[206:207], off
	s_waitcnt vmcnt(8)
	s_waitcnt lgkmcnt(0)
	s_barrier
	s_setprio 1
	s_waitcnt lgkmcnt(0)
	v_mfma_f32_16x16x32_bf16 v[124:127], v[140:143], v[172:175], v[124:127]
	v_mfma_f32_16x16x32_bf16 v[120:123], v[148:151], v[172:175], v[120:123]
	v_mfma_f32_16x16x32_bf16 v[116:119], v[140:143], v[180:183], v[116:119]
	v_mfma_f32_16x16x32_bf16 v[112:115], v[148:151], v[180:183], v[112:115]
	v_mfma_f32_16x16x32_bf16 v[100:103], v[140:143], v[188:191], v[100:103]
	v_mfma_f32_16x16x32_bf16 v[96:99], v[148:151], v[188:191], v[96:99]
	v_mfma_f32_16x16x32_bf16 v[84:87], v[140:143], v[216:219], v[84:87]
	v_mfma_f32_16x16x32_bf16 v[80:83], v[148:151], v[216:219], v[80:83]
	v_mfma_f32_16x16x32_bf16 v[124:127], v[144:147], v[176:179], v[124:127]
	v_mfma_f32_16x16x32_bf16 v[120:123], v[152:155], v[176:179], v[120:123]
	v_mfma_f32_16x16x32_bf16 v[116:119], v[144:147], v[184:187], v[116:119]
	v_mfma_f32_16x16x32_bf16 v[112:115], v[152:155], v[184:187], v[112:115]
	v_mfma_f32_16x16x32_bf16 v[100:103], v[144:147], v[212:215], v[100:103]
	v_mfma_f32_16x16x32_bf16 v[96:99], v[152:155], v[212:215], v[96:99]
	v_mfma_f32_16x16x32_bf16 v[84:87], v[144:147], v[232:235], v[84:87]
	v_mfma_f32_16x16x32_bf16 v[80:83], v[152:155], v[232:235], v[80:83]
	s_setprio 0
	s_setprio 1
	v_mfma_f32_16x16x32_bf16 v[108:111], v[156:159], v[172:175], v[108:111]
	v_mfma_f32_16x16x32_bf16 v[104:107], v[164:167], v[172:175], v[104:107]
	v_mfma_f32_16x16x32_bf16 v[92:95], v[156:159], v[180:183], v[92:95]
	v_mfma_f32_16x16x32_bf16 v[88:91], v[164:167], v[180:183], v[88:91]
	v_mfma_f32_16x16x32_bf16 v[76:79], v[156:159], v[188:191], v[76:79]
	v_mfma_f32_16x16x32_bf16 v[72:75], v[164:167], v[188:191], v[72:75]
	v_mfma_f32_16x16x32_bf16 v[68:71], v[156:159], v[216:219], v[68:71]
	v_mfma_f32_16x16x32_bf16 v[64:67], v[164:167], v[216:219], v[64:67]
	v_mfma_f32_16x16x32_bf16 v[108:111], v[160:163], v[176:179], v[108:111]
	v_mfma_f32_16x16x32_bf16 v[104:107], v[168:171], v[176:179], v[104:107]
	v_mfma_f32_16x16x32_bf16 v[92:95], v[160:163], v[184:187], v[92:95]
	v_mfma_f32_16x16x32_bf16 v[88:91], v[168:171], v[184:187], v[88:91]
	s_barrier
; #define PG8_STAGE(bufoff, gbase, voff) do { _Pragma("unroll") for (int _i = 0; _i < 2; ++_i) \
;         __builtin_amdgcn_global_load_lds((const unsigned*)((const char*)(gbase) + (voff)[_i]), (PG8_LAS unsigned*)(lds + (bufoff) + ldsw + _i * 8192), 16, 0, 0); } while (0)
; #define PG8_LDA(dst, b, h) do { _Pragma("unroll") for (int m = 0; m < 4; ++m) _Pragma("unroll") for (int k = 0; k < 2; ++k) dst[m][k] = *(const PG8_LAS bf16x8*)(lds + PG8_SA(b, h) + aoff + m * 2048 + k * 1024); } while (0)
; #define PG8_MMA(ai, bj, At, Bt) do { __builtin_amdgcn_s_setprio(1); _Pragma("unroll") for (int m = 0; m < 4; ++m) _Pragma("unroll") for (int n = 0; n < 2; ++n) _Pragma("unroll") for (int k = 0; k < 2; ++k) \
;         acc[ai][bj][m][n] = __builtin_amdgcn_mfma_f32_16x16x32_bf16(Bt[n][k], At[m][k], acc[ai][bj][m][n], 0, 0, 0); __builtin_amdgcn_s_setprio(0); } while (0)
; #define PG8_WAIT_V(n) asm volatile("s_waitcnt vmcnt(" #n ")" ::: "memory")
; #define PG8_WAIT_L(n) asm volatile("s_waitcnt lgkmcnt(" #n ")" ::: "memory")
; #define PG8_BAR __builtin_amdgcn_s_barrier()
; #define PG8_SCHED __builtin_amdgcn_sched_barrier(0)
; template <class Epi, class Sched, bool ALIGN_EPI = false, bool SP2 = false>
; __device__ __forceinline__ void gemm_phase(PG8_LAS unsigned char* lds, const Gemm g, const Sched& S, const Epi& E, const int tid) {
;     ...
;             PG8_WAIT_V(8); PG8_WAIT_L(0); PG8_BAR; PG8_MMA(0, 0, At, B0); PG8_MMA(0, 1, At, B1); PG8_BAR; PG8_SCHED;
;             PG8_LDA(At, 1, 1); PG8_STAGE(PG8_SB(1, 0), b3, voffB); PG8_STAGE(PG8_SB(1, 1), b3 + hstep, voffB); PG8_STAGE(PG8_SA(1, 0), a3, voffA);
;             PG8_WAIT_V(8); PG8_WAIT_L(0); PG8_BAR; PG8_MMA(1, 0, At, B0); PG8_MMA(1, 1, At, B1); PG8_BAR; PG8_SCHED;
;     ...
;         }
;         if constexpr (ALIGN_EPI) { if (wr == 0) PG8_BAR; }
	v_mfma_f32_16x16x32_bf16 v[76:79], v[160:163], v[212:215], v[76:79]
	v_mfma_f32_16x16x32_bf16 v[72:75], v[168:171], v[212:215], v[72:75]
	v_mfma_f32_16x16x32_bf16 v[68:71], v[160:163], v[232:235], v[68:71]
	v_mfma_f32_16x16x32_bf16 v[64:67], v[168:171], v[232:235], v[64:67]
	s_setprio 0
	s_add_i32 s18, s73, s35
	v_lshl_add_u64 v[194:195], v[194:195], 0, s[36:37]
	s_mov_b32 m0, s18
	ds_read_b128 v[172:175], v139 offset:49152
	ds_read_b128 v[176:179], v139 offset:50176
	ds_read_b128 v[180:183], v139 offset:51200
	ds_read_b128 v[184:187], v139 offset:52224
	ds_read_b128 v[188:191], v139 offset:53248
	ds_read_b128 v[212:215], v139 offset:54272
	ds_read_b128 v[216:219], v139 offset:55296
	ds_read_b128 v[232:235], v139 offset:56320
	global_load_lds_dwordx4 v[194:195], off
	s_add_i32 m0, s18, 0x2000
	s_add_u32 s18, s22, 0xb0080
	v_lshl_add_u64 v[194:195], v[196:197], 0, s[36:37]
	s_addc_u32 s19, s23, 0
	s_add_i32 s22, s74, s35
	global_load_lds_dwordx4 v[194:195], off
	v_lshl_add_u64 v[194:195], s[18:19], 0, v[192:193]
	s_mov_b32 m0, s22
	s_nop 0
	global_load_lds_dwordx4 v[194:195], off
	v_lshl_add_u64 v[194:195], s[18:19], 0, v[132:133]
	s_add_i32 m0, s22, 0x2000
	s_nop 0
	global_load_lds_dwordx4 v[194:195], off
	v_lshl_add_u64 v[194:195], v[202:203], 0, s[36:37]
	s_mov_b32 m0, s47
	s_nop 0
	global_load_lds_dwordx4 v[194:195], off
	v_lshl_add_u64 v[194:195], v[204:205], 0, s[36:37]
	s_mov_b32 m0, s53
	s_nop 0
	global_load_lds_dwordx4 v[194:195], off
	s_waitcnt vmcnt(8)
	s_waitcnt lgkmcnt(0)
	s_barrier
	s_setprio 1
	s_waitcnt lgkmcnt(0)
	v_mfma_f32_16x16x32_bf16 v[60:63], v[140:143], v[172:175], v[60:63]
	v_mfma_f32_16x16x32_bf16 v[56:59], v[148:151], v[172:175], v[56:59]
	v_mfma_f32_16x16x32_bf16 v[52:55], v[140:143], v[180:183], v[52:55]
	v_mfma_f32_16x16x32_bf16 v[48:51], v[148:151], v[180:183], v[48:51]
	v_mfma_f32_16x16x32_bf16 v[36:39], v[140:143], v[188:191], v[36:39]
	v_mfma_f32_16x16x32_bf16 v[32:35], v[148:151], v[188:191], v[32:35]
	v_mfma_f32_16x16x32_bf16 v[20:23], v[140:143], v[216:219], v[20:23]
	v_mfma_f32_16x16x32_bf16 v[16:19], v[148:151], v[216:219], v[16:19]
	v_mfma_f32_16x16x32_bf16 v[60:63], v[144:147], v[176:179], v[60:63]
	v_mfma_f32_16x16x32_bf16 v[56:59], v[152:155], v[176:179], v[56:59]
	v_mfma_f32_16x16x32_bf16 v[52:55], v[144:147], v[184:187], v[52:55]
	v_mfma_f32_16x16x32_bf16 v[48:51], v[152:155], v[184:187], v[48:51]
	v_mfma_f32_16x16x32_bf16 v[36:39], v[144:147], v[212:215], v[36:39]
	v_mfma_f32_16x16x32_bf16 v[32:35], v[152:155], v[212:215], v[32:35]
	v_mfma_f32_16x16x32_bf16 v[20:23], v[144:147], v[232:235], v[20:23]
	v_mfma_f32_16x16x32_bf16 v[16:19], v[152:155], v[232:235], v[16:19]
	s_setprio 0
	s_setprio 1
	v_mfma_f32_16x16x32_bf16 v[44:47], v[156:159], v[172:175], v[44:47]
	v_mfma_f32_16x16x32_bf16 v[40:43], v[164:167], v[172:175], v[40:43]
	v_mfma_f32_16x16x32_bf16 v[28:31], v[156:159], v[180:183], v[28:31]
	v_mfma_f32_16x16x32_bf16 v[24:27], v[164:167], v[180:183], v[24:27]
	v_mfma_f32_16x16x32_bf16 v[12:15], v[156:159], v[188:191], v[12:15]
	v_mfma_f32_16x16x32_bf16 v[8:11], v[164:167], v[188:191], v[8:11]
	v_mfma_f32_16x16x32_bf16 v[4:7], v[156:159], v[216:219], v[4:7]
	v_mfma_f32_16x16x32_bf16 v[0:3], v[164:167], v[216:219], v[0:3]
	v_mfma_f32_16x16x32_bf16 v[44:47], v[160:163], v[176:179], v[44:47]
	v_mfma_f32_16x16x32_bf16 v[40:43], v[168:171], v[176:179], v[40:43]
	v_mfma_f32_16x16x32_bf16 v[28:31], v[160:163], v[184:187], v[28:31]
	v_mfma_f32_16x16x32_bf16 v[24:27], v[168:171], v[184:187], v[24:27]
	s_barrier
	v_mfma_f32_16x16x32_bf16 v[12:15], v[160:163], v[212:215], v[12:15]
	v_mfma_f32_16x16x32_bf16 v[8:11], v[168:171], v[212:215], v[8:11]
	v_mfma_f32_16x16x32_bf16 v[4:7], v[160:163], v[232:235], v[4:7]
	v_mfma_f32_16x16x32_bf16 v[0:3], v[168:171], v[232:235], v[0:3]
	s_setprio 0
	s_add_i32 s72, s72, 2
	s_add_u32 s62, s62, 0x100
	s_addc_u32 s71, s71, 0
	s_cmp_gt_u32 s72, 41
	s_mov_b64 s[18:19], s[20:21]
	s_cbranch_scc0 .LBB0_99
	s_nop 7
	s_and_b64 vcc, exec, s[14:15]
	s_cbranch_vccz .LBB0_102
	s_barrier

; #define PG8_STAGE(bufoff, gbase, voff) do { _Pragma("unroll") for (int _i = 0; _i < 2; ++_i) \
;         __builtin_amdgcn_global_load_lds((const unsigned*)((const char*)(gbase) + (voff)[_i]), (PG8_LAS unsigned*)(lds + (bufoff) + ldsw + _i * 8192), 16, 0, 0); } while (0)
; #define PG8_LDA(dst, b, h) do { _Pragma("unroll") for (int m = 0; m < 4; ++m) _Pragma("unroll") for (int k = 0; k < 2; ++k) dst[m][k] = *(const PG8_LAS bf16x8*)(lds + PG8_SA(b, h) + aoff + m * 2048 + k * 1024); } while (0)
; #define PG8_LDB(dst, b, h) do { _Pragma("unroll") for (int n = 0; n < 2; ++n) _Pragma("unroll") for (int k = 0; k < 2; ++k) dst[n][k] = *(const PG8_LAS bf16x8*)(lds + PG8_SB(b, h) + boff + n * 2048 + k * 1024); } while (0)
; #define PG8_MMA(ai, bj, At, Bt) do { __builtin_amdgcn_s_setprio(1); _Pragma("unroll") for (int m = 0; m < 4; ++m) _Pragma("unroll") for (int n = 0; n < 2; ++n) _Pragma("unroll") for (int k = 0; k < 2; ++k) \
;         acc[ai][bj][m][n] = __builtin_amdgcn_mfma_f32_16x16x32_bf16(Bt[n][k], At[m][k], acc[ai][bj][m][n], 0, 0, 0); __builtin_amdgcn_s_setprio(0); } while (0)
; #define PG8_WAIT_V(n) asm volatile("s_waitcnt vmcnt(" #n ")" ::: "memory")
; #define PG8_WAIT_L(n) asm volatile("s_waitcnt lgkmcnt(" #n ")" ::: "memory")
; template <class Epi, class Sched, bool ALIGN_EPI = false, bool SP2 = false>
; __device__ __forceinline__ void gemm_phase(PG8_LAS unsigned char* lds, const Gemm g, const Sched& S, const Epi& E, const int tid) {
;     ...
;             const bool last = (t == nt - 2);
;             const char* a1 = cA + (size_t)(t + 1) * kstep;
;             const char* a2 = last ? nA : cA + (size_t)(t + 2) * kstep; const char* b2 = last ? nB : cB + (size_t)(t + 2) * kstep;
;             const char* a3 = a2 + kstep; const char* b3 = b2 + kstep;
;             if (last && has_next) S.a_ready(nxt);
;             if constexpr (SP2) {
;             PG8_LDB(B0, 0, 0); PG8_LDB(B1, 0, 1); PG8_SCHED; PG8_LDA(At, 0, 0); PG8_STAGE(PG8_SA(1, 1), a1 + hstep, voffA);
;             PG8_WAIT_V(8); PG8_WAIT_L(0); PG8_BAR; PG8_MMA(0, 0, At, B0); PG8_MMA(0, 1, At, B1); PG8_BAR; PG8_SCHED;
;             PG8_LDA(At, 0, 1); PG8_STAGE(PG8_SB(0, 0), b2, voffB); PG8_STAGE(PG8_SB(0, 1), b2 + hstep, voffB); PG8_STAGE(PG8_SA(0, 0), a2, voffA);
;             PG8_WAIT_V(8); PG8_WAIT_L(0); PG8_BAR; PG8_MMA(1, 0, At, B0); PG8_MMA(1, 1, At, B1); PG8_BAR; PG8_SCHED;
.LBB0_127:
	s_add_u32 s44, s16, s22
	s_addc_u32 s45, s17, s23
	s_add_u32 s44, s44, 0x100
	s_addc_u32 s45, s45, 0
	s_waitcnt lgkmcnt(0)
	s_add_u32 s75, s19, s22
	s_addc_u32 s76, s62, s23
	s_add_i32 s77, 0, 0x10000
	s_cmpk_eq_i32 s22, 0x1500
	s_cselect_b32 s59, s21, s45
	s_cselect_b32 s58, s20, s44
	s_cselect_b32 s45, s11, s76
	s_cselect_b32 s44, s10, s75
	s_add_i32 s75, 0, 0x14000
	v_add_u32_e32 v156, s77, v142
	v_add_u32_e32 v172, s75, v142
	ds_read_b128 v[144:147], v156
	ds_read_b128 v[148:151], v156 offset:1024
	ds_read_b128 v[152:155], v156 offset:2048
	ds_read_b128 v[156:159], v156 offset:3072
	ds_read_b128 v[160:163], v172
	ds_read_b128 v[164:167], v172 offset:1024
	ds_read_b128 v[168:171], v172 offset:2048
	ds_read_b128 v[172:175], v172 offset:3072
	v_lshl_add_u64 v[194:195], v[138:139], 0, s[22:23]
	s_add_i32 m0, s47, 0xc000
	ds_read_b128 v[176:179], v143
	ds_read_b128 v[180:183], v143 offset:1024
	ds_read_b128 v[184:187], v143 offset:2048
	ds_read_b128 v[188:191], v143 offset:3072
	ds_read_b128 v[212:215], v143 offset:4096
	ds_read_b128 v[216:219], v143 offset:5120
	ds_read_b128 v[232:235], v143 offset:6144
	ds_read_b128 v[236:239], v143 offset:7168
	global_load_lds_dwordx4 v[194:195], off
	v_lshl_add_u64 v[194:195], v[140:141], 0, s[22:23]
	s_add_i32 m0, s47, 0xe000
	s_nop 0
	global_load_lds_dwordx4 v[194:195], off
	s_waitcnt vmcnt(8)
	s_waitcnt lgkmcnt(0)
	s_barrier
	s_setprio 1
	s_waitcnt lgkmcnt(0)
	v_mfma_f32_16x16x32_bf16 v[124:127], v[144:147], v[176:179], v[124:127]
	v_mfma_f32_16x16x32_bf16 v[120:123], v[152:155], v[176:179], v[120:123]
	v_mfma_f32_16x16x32_bf16 v[108:111], v[144:147], v[184:187], v[108:111]
	v_mfma_f32_16x16x32_bf16 v[104:107], v[152:155], v[184:187], v[104:107]
	v_mfma_f32_16x16x32_bf16 v[92:95], v[144:147], v[212:215], v[92:95]
	v_mfma_f32_16x16x32_bf16 v[88:91], v[152:155], v[212:215], v[88:91]
	v_mfma_f32_16x16x32_bf16 v[76:79], v[144:147], v[232:235], v[76:79]
	v_mfma_f32_16x16x32_bf16 v[72:75], v[152:155], v[232:235], v[72:75]
	v_mfma_f32_16x16x32_bf16 v[124:127], v[148:151], v[180:183], v[124:127]
	v_mfma_f32_16x16x32_bf16 v[120:123], v[156:159], v[180:183], v[120:123]
	v_mfma_f32_16x16x32_bf16 v[108:111], v[148:151], v[188:191], v[108:111]
	v_mfma_f32_16x16x32_bf16 v[104:107], v[156:159], v[188:191], v[104:107]
	v_mfma_f32_16x16x32_bf16 v[92:95], v[148:151], v[216:219], v[92:95]
	v_mfma_f32_16x16x32_bf16 v[88:91], v[156:159], v[216:219], v[88:91]
	v_mfma_f32_16x16x32_bf16 v[76:79], v[148:151], v[236:239], v[76:79]
	v_mfma_f32_16x16x32_bf16 v[72:75], v[156:159], v[236:239], v[72:75]
	s_setprio 0
	s_setprio 1
	v_mfma_f32_16x16x32_bf16 v[116:119], v[160:163], v[176:179], v[116:119]
	v_mfma_f32_16x16x32_bf16 v[112:115], v[168:171], v[176:179], v[112:115]
	v_mfma_f32_16x16x32_bf16 v[100:103], v[160:163], v[184:187], v[100:103]
	v_mfma_f32_16x16x32_bf16 v[96:99], v[168:171], v[184:187], v[96:99]
	v_mfma_f32_16x16x32_bf16 v[84:87], v[160:163], v[212:215], v[84:87]
	v_mfma_f32_16x16x32_bf16 v[80:83], v[168:171], v[212:215], v[80:83]
	v_mfma_f32_16x16x32_bf16 v[68:71], v[160:163], v[232:235], v[68:71]
	v_mfma_f32_16x16x32_bf16 v[64:67], v[168:171], v[232:235], v[64:67]
	v_mfma_f32_16x16x32_bf16 v[116:119], v[164:167], v[180:183], v[116:119]
	v_mfma_f32_16x16x32_bf16 v[112:115], v[172:175], v[180:183], v[112:115]
	v_mfma_f32_16x16x32_bf16 v[100:103], v[164:167], v[188:191], v[100:103]
	v_mfma_f32_16x16x32_bf16 v[96:99], v[172:175], v[188:191], v[96:99]
	s_barrier
	v_mfma_f32_16x16x32_bf16 v[84:87], v[164:167], v[216:219], v[84:87]
	v_mfma_f32_16x16x32_bf16 v[80:83], v[172:175], v[216:219], v[80:83]
	v_mfma_f32_16x16x32_bf16 v[68:71], v[164:167], v[236:239], v[68:71]
	v_mfma_f32_16x16x32_bf16 v[64:67], v[172:175], v[236:239], v[64:67]
	s_setprio 0
	s_add_i32 s76, s77, s46
	v_lshl_add_u64 v[194:195], s[44:45], 0, v[192:193]
	s_mov_b32 m0, s76
	ds_read_b128 v[176:179], v143 offset:16384
	ds_read_b128 v[180:183], v143 offset:17408
	ds_read_b128 v[184:187], v143 offset:18432
	ds_read_b128 v[188:191], v143 offset:19456
	ds_read_b128 v[212:215], v143 offset:20480
	ds_read_b128 v[216:219], v143 offset:21504
	ds_read_b128 v[232:235], v143 offset:22528
	ds_read_b128 v[236:239], v143 offset:23552
	global_load_lds_dwordx4 v[194:195], off
	s_add_i32 m0, s76, 0x2000
	s_add_u32 s76, s44, 0xb0000
	v_lshl_add_u64 v[196:197], s[44:45], 0, v[132:133]
	s_addc_u32 s77, s45, 0
	s_add_i32 s75, s75, s46
	global_load_lds_dwordx4 v[196:197], off
	v_lshl_add_u64 v[202:203], s[76:77], 0, v[192:193]
	s_mov_b32 m0, s75
	v_lshl_add_u64 v[204:205], s[58:59], 0, v[130:131]
	global_load_lds_dwordx4 v[202:203], off
	v_lshl_add_u64 v[202:203], s[76:77], 0, v[132:133]
	s_add_i32 m0, s75, 0x2000
	s_nop 0
	global_load_lds_dwordx4 v[202:203], off
	v_lshl_add_u64 v[202:203], s[58:59], 0, v[128:129]
	s_mov_b32 m0, s47
	s_nop 0
	global_load_lds_dwordx4 v[202:203], off
	s_mov_b32 m0, s53
	s_nop 0
	global_load_lds_dwordx4 v[204:205], off
	s_waitcnt vmcnt(8)
	s_waitcnt lgkmcnt(0)
	s_barrier
; #define PG8_STAGE(bufoff, gbase, voff) do { _Pragma("unroll") for (int _i = 0; _i < 2; ++_i) \
;         __builtin_amdgcn_global_load_lds((const unsigned*)((const char*)(gbase) + (voff)[_i]), (PG8_LAS unsigned*)(lds + (bufoff) + ldsw + _i * 8192), 16, 0, 0); } while (0)
; #define PG8_LDA(dst, b, h) do { _Pragma("unroll") for (int m = 0; m < 4; ++m) _Pragma("unroll") for (int k = 0; k < 2; ++k) dst[m][k] = *(const PG8_LAS bf16x8*)(lds + PG8_SA(b, h) + aoff + m * 2048 + k * 1024); } while (0)
; #define PG8_LDB(dst, b, h) do { _Pragma("unroll") for (int n = 0; n < 2; ++n) _Pragma("unroll") for (int k = 0; k < 2; ++k) dst[n][k] = *(const PG8_LAS bf16x8*)(lds + PG8_SB(b, h) + boff + n * 2048 + k * 1024); } while (0)
; #define PG8_MMA(ai, bj, At, Bt) do { __builtin_amdgcn_s_setprio(1); _Pragma("unroll") for (int m = 0; m < 4; ++m) _Pragma("unroll") for (int n = 0; n < 2; ++n) _Pragma("unroll") for (int k = 0; k < 2; ++k) \
;         acc[ai][bj][m][n] = __builtin_amdgcn_mfma_f32_16x16x32_bf16(Bt[n][k], At[m][k], acc[ai][bj][m][n], 0, 0, 0); __builtin_amdgcn_s_setprio(0); } while (0)
; #define PG8_WAIT_V(n) asm volatile("s_waitcnt vmcnt(" #n ")" ::: "memory")
; #define PG8_WAIT_L(n) asm volatile("s_waitcnt lgkmcnt(" #n ")" ::: "memory")
; #define PG8_BAR __builtin_amdgcn_s_barrier()
; #define PG8_SCHED __builtin_amdgcn_sched_barrier(0)
; template <class Epi, class Sched, bool ALIGN_EPI = false, bool SP2 = false>
; __device__ __forceinline__ void gemm_phase(PG8_LAS unsigned char* lds, const Gemm g, const Sched& S, const Epi& E, const int tid) {
;     ...
;             PG8_WAIT_V(8); PG8_WAIT_L(0); PG8_BAR; PG8_MMA(1, 0, At, B0); PG8_MMA(1, 1, At, B1); PG8_BAR; PG8_SCHED;
;             PG8_LDB(B0, 1, 0); PG8_LDB(B1, 1, 1); PG8_SCHED; PG8_LDA(At, 1, 0); PG8_STAGE(PG8_SA(0, 1), a2 + hstep, voffA);
;             PG8_WAIT_V(8); PG8_WAIT_L(0); PG8_BAR; PG8_MMA(0, 0, At, B0); PG8_MMA(0, 1, At, B1); PG8_BAR; PG8_SCHED;
;             PG8_LDA(At, 1, 1); PG8_STAGE(PG8_SB(1, 0), b3, voffB); PG8_STAGE(PG8_SB(1, 1), b3 + hstep, voffB); PG8_STAGE(PG8_SA(1, 0), a3, voffA);
	s_setprio 1
	s_waitcnt lgkmcnt(0)
	v_mfma_f32_16x16x32_bf16 v[60:63], v[144:147], v[176:179], v[60:63]
	v_mfma_f32_16x16x32_bf16 v[56:59], v[152:155], v[176:179], v[56:59]
	v_mfma_f32_16x16x32_bf16 v[44:47], v[144:147], v[184:187], v[44:47]
	v_mfma_f32_16x16x32_bf16 v[40:43], v[152:155], v[184:187], v[40:43]
	v_mfma_f32_16x16x32_bf16 v[28:31], v[144:147], v[212:215], v[28:31]
	v_mfma_f32_16x16x32_bf16 v[24:27], v[152:155], v[212:215], v[24:27]
	v_mfma_f32_16x16x32_bf16 v[12:15], v[144:147], v[232:235], v[12:15]
	v_mfma_f32_16x16x32_bf16 v[8:11], v[152:155], v[232:235], v[8:11]
	v_mfma_f32_16x16x32_bf16 v[60:63], v[148:151], v[180:183], v[60:63]
	v_mfma_f32_16x16x32_bf16 v[56:59], v[156:159], v[180:183], v[56:59]
	v_mfma_f32_16x16x32_bf16 v[44:47], v[148:151], v[188:191], v[44:47]
	v_mfma_f32_16x16x32_bf16 v[40:43], v[156:159], v[188:191], v[40:43]
	v_mfma_f32_16x16x32_bf16 v[28:31], v[148:151], v[216:219], v[28:31]
	v_mfma_f32_16x16x32_bf16 v[24:27], v[156:159], v[216:219], v[24:27]
	v_mfma_f32_16x16x32_bf16 v[12:15], v[148:151], v[236:239], v[12:15]
	v_mfma_f32_16x16x32_bf16 v[8:11], v[156:159], v[236:239], v[8:11]
	s_setprio 0
	s_setprio 1
	v_mfma_f32_16x16x32_bf16 v[52:55], v[160:163], v[176:179], v[52:55]
	v_mfma_f32_16x16x32_bf16 v[48:51], v[168:171], v[176:179], v[48:51]
	v_mfma_f32_16x16x32_bf16 v[36:39], v[160:163], v[184:187], v[36:39]
	v_mfma_f32_16x16x32_bf16 v[32:35], v[168:171], v[184:187], v[32:35]
	v_mfma_f32_16x16x32_bf16 v[20:23], v[160:163], v[212:215], v[20:23]
	v_mfma_f32_16x16x32_bf16 v[16:19], v[168:171], v[212:215], v[16:19]
	v_mfma_f32_16x16x32_bf16 v[4:7], v[160:163], v[232:235], v[4:7]
	v_mfma_f32_16x16x32_bf16 v[0:3], v[168:171], v[232:235], v[0:3]
	v_mfma_f32_16x16x32_bf16 v[52:55], v[164:167], v[180:183], v[52:55]
	v_mfma_f32_16x16x32_bf16 v[48:51], v[172:175], v[180:183], v[48:51]
	v_mfma_f32_16x16x32_bf16 v[36:39], v[164:167], v[188:191], v[36:39]
	v_mfma_f32_16x16x32_bf16 v[32:35], v[172:175], v[188:191], v[32:35]
	s_barrier
	v_mfma_f32_16x16x32_bf16 v[20:23], v[164:167], v[216:219], v[20:23]
	v_mfma_f32_16x16x32_bf16 v[16:19], v[172:175], v[216:219], v[16:19]
	v_mfma_f32_16x16x32_bf16 v[4:7], v[164:167], v[236:239], v[4:7]
	v_mfma_f32_16x16x32_bf16 v[0:3], v[172:175], v[236:239], v[0:3]
	s_setprio 0
	s_add_i32 s75, 0, 0x18000
	s_add_i32 s76, 0, 0x1c000
	v_add_u32_e32 v156, s75, v142
	v_add_u32_e32 v172, s76, v142
	ds_read_b128 v[144:147], v156
	ds_read_b128 v[148:151], v156 offset:1024
	ds_read_b128 v[152:155], v156 offset:2048
	ds_read_b128 v[156:159], v156 offset:3072
	ds_read_b128 v[160:163], v172
	ds_read_b128 v[164:167], v172 offset:1024
	ds_read_b128 v[168:171], v172 offset:2048
	ds_read_b128 v[172:175], v172 offset:3072
	s_add_u32 s58, s58, 0xb0000
	s_addc_u32 s59, s59, 0
	s_mov_b32 m0, s54
	v_lshl_add_u64 v[206:207], s[58:59], 0, v[128:129]
	ds_read_b128 v[176:179], v143 offset:32768
	ds_read_b128 v[180:183], v143 offset:33792
	ds_read_b128 v[184:187], v143 offset:34816
	ds_read_b128 v[188:191], v143 offset:35840
	ds_read_b128 v[212:215], v143 offset:36864
	ds_read_b128 v[216:219], v143 offset:37888
	ds_read_b128 v[232:235], v143 offset:38912
	ds_read_b128 v[236:239], v143 offset:39936
	global_load_lds_dwordx4 v[206:207], off
	v_lshl_add_u64 v[206:207], s[58:59], 0, v[130:131]
	s_mov_b32 m0, s55
	s_nop 0
	global_load_lds_dwordx4 v[206:207], off
	s_waitcnt vmcnt(8)
	s_waitcnt lgkmcnt(0)
	s_barrier
	s_setprio 1
	s_waitcnt lgkmcnt(0)
	v_mfma_f32_16x16x32_bf16 v[124:127], v[144:147], v[176:179], v[124:127]
	v_mfma_f32_16x16x32_bf16 v[120:123], v[152:155], v[176:179], v[120:123]
	v_mfma_f32_16x16x32_bf16 v[108:111], v[144:147], v[184:187], v[108:111]
	v_mfma_f32_16x16x32_bf16 v[104:107], v[152:155], v[184:187], v[104:107]
	v_mfma_f32_16x16x32_bf16 v[92:95], v[144:147], v[212:215], v[92:95]
	v_mfma_f32_16x16x32_bf16 v[88:91], v[152:155], v[212:215], v[88:91]
	v_mfma_f32_16x16x32_bf16 v[76:79], v[144:147], v[232:235], v[76:79]
	v_mfma_f32_16x16x32_bf16 v[72:75], v[152:155], v[232:235], v[72:75]
	v_mfma_f32_16x16x32_bf16 v[124:127], v[148:151], v[180:183], v[124:127]
	v_mfma_f32_16x16x32_bf16 v[120:123], v[156:159], v[180:183], v[120:123]
	v_mfma_f32_16x16x32_bf16 v[108:111], v[148:151], v[188:191], v[108:111]
	v_mfma_f32_16x16x32_bf16 v[104:107], v[156:159], v[188:191], v[104:107]
	v_mfma_f32_16x16x32_bf16 v[92:95], v[148:151], v[216:219], v[92:95]
	v_mfma_f32_16x16x32_bf16 v[88:91], v[156:159], v[216:219], v[88:91]
	v_mfma_f32_16x16x32_bf16 v[76:79], v[148:151], v[236:239], v[76:79]
	v_mfma_f32_16x16x32_bf16 v[72:75], v[156:159], v[236:239], v[72:75]
	s_setprio 0
	s_setprio 1
	v_mfma_f32_16x16x32_bf16 v[116:119], v[160:163], v[176:179], v[116:119]
	v_mfma_f32_16x16x32_bf16 v[112:115], v[168:171], v[176:179], v[112:115]
	v_mfma_f32_16x16x32_bf16 v[100:103], v[160:163], v[184:187], v[100:103]
	v_mfma_f32_16x16x32_bf16 v[96:99], v[168:171], v[184:187], v[96:99]
	v_mfma_f32_16x16x32_bf16 v[84:87], v[160:163], v[212:215], v[84:87]
	v_mfma_f32_16x16x32_bf16 v[80:83], v[168:171], v[212:215], v[80:83]
	v_mfma_f32_16x16x32_bf16 v[68:71], v[160:163], v[232:235], v[68:71]
	v_mfma_f32_16x16x32_bf16 v[64:67], v[168:171], v[232:235], v[64:67]
	v_mfma_f32_16x16x32_bf16 v[116:119], v[164:167], v[180:183], v[116:119]
	v_mfma_f32_16x16x32_bf16 v[112:115], v[172:175], v[180:183], v[112:115]
	v_mfma_f32_16x16x32_bf16 v[100:103], v[164:167], v[188:191], v[100:103]
	v_mfma_f32_16x16x32_bf16 v[96:99], v[172:175], v[188:191], v[96:99]
	s_barrier
; #define PG8_STAGE(bufoff, gbase, voff) do { _Pragma("unroll") for (int _i = 0; _i < 2; ++_i) \
;         __builtin_amdgcn_global_load_lds((const unsigned*)((const char*)(gbase) + (voff)[_i]), (PG8_LAS unsigned*)(lds + (bufoff) + ldsw + _i * 8192), 16, 0, 0); } while (0)
; #define PG8_LDA(dst, b, h) do { _Pragma("unroll") for (int m = 0; m < 4; ++m) _Pragma("unroll") for (int k = 0; k < 2; ++k) dst[m][k] = *(const PG8_LAS bf16x8*)(lds + PG8_SA(b, h) + aoff + m * 2048 + k * 1024); } while (0)
; #define PG8_MMA(ai, bj, At, Bt) do { __builtin_amdgcn_s_setprio(1); _Pragma("unroll") for (int m = 0; m < 4; ++m) _Pragma("unroll") for (int n = 0; n < 2; ++n) _Pragma("unroll") for (int k = 0; k < 2; ++k) \
;         acc[ai][bj][m][n] = __builtin_amdgcn_mfma_f32_16x16x32_bf16(Bt[n][k], At[m][k], acc[ai][bj][m][n], 0, 0, 0); __builtin_amdgcn_s_setprio(0); } while (0)
; #define PG8_WAIT_V(n) asm volatile("s_waitcnt vmcnt(" #n ")" ::: "memory")
; #define PG8_WAIT_L(n) asm volatile("s_waitcnt lgkmcnt(" #n ")" ::: "memory")
; #define PG8_BAR __builtin_amdgcn_s_barrier()
; #define PG8_SCHED __builtin_amdgcn_sched_barrier(0)
; template <class Epi, class Sched, bool ALIGN_EPI = false, bool SP2 = false>
; __device__ __forceinline__ void gemm_phase(PG8_LAS unsigned char* lds, const Gemm g, const Sched& S, const Epi& E, const int tid) {
;     ...
;             PG8_WAIT_V(8); PG8_WAIT_L(0); PG8_BAR; PG8_MMA(0, 0, At, B0); PG8_MMA(0, 1, At, B1); PG8_BAR; PG8_SCHED;
;             PG8_LDA(At, 1, 1); PG8_STAGE(PG8_SB(1, 0), b3, voffB); PG8_STAGE(PG8_SB(1, 1), b3 + hstep, voffB); PG8_STAGE(PG8_SA(1, 0), a3, voffA);
	v_mfma_f32_16x16x32_bf16 v[84:87], v[164:167], v[216:219], v[84:87]
	v_mfma_f32_16x16x32_bf16 v[80:83], v[172:175], v[216:219], v[80:83]
	v_mfma_f32_16x16x32_bf16 v[68:71], v[164:167], v[236:239], v[68:71]
	v_mfma_f32_16x16x32_bf16 v[64:67], v[172:175], v[236:239], v[64:67]
	s_setprio 0
	s_add_i32 s58, s75, s46
	v_lshl_add_u64 v[194:195], v[194:195], 0, s[36:37]
	s_mov_b32 m0, s58
	ds_read_b128 v[176:179], v143 offset:49152
	ds_read_b128 v[180:183], v143 offset:50176
	ds_read_b128 v[184:187], v143 offset:51200
	ds_read_b128 v[188:191], v143 offset:52224
	ds_read_b128 v[212:215], v143 offset:53248
	ds_read_b128 v[216:219], v143 offset:54272
	ds_read_b128 v[232:235], v143 offset:55296
	ds_read_b128 v[236:239], v143 offset:56320
	global_load_lds_dwordx4 v[194:195], off
	s_add_i32 m0, s58, 0x2000
	s_add_u32 s44, s44, 0xb0080
	v_lshl_add_u64 v[194:195], v[196:197], 0, s[36:37]
	s_addc_u32 s45, s45, 0
	s_add_i32 s58, s76, s46
	global_load_lds_dwordx4 v[194:195], off
	v_lshl_add_u64 v[194:195], s[44:45], 0, v[192:193]
	s_mov_b32 m0, s58
	s_nop 0
	global_load_lds_dwordx4 v[194:195], off
	v_lshl_add_u64 v[194:195], s[44:45], 0, v[132:133]
	s_add_i32 m0, s58, 0x2000
	s_nop 0
	global_load_lds_dwordx4 v[194:195], off
	v_lshl_add_u64 v[194:195], v[202:203], 0, s[36:37]
	s_mov_b32 m0, s60
	s_nop 0
	global_load_lds_dwordx4 v[194:195], off
	v_lshl_add_u64 v[194:195], v[204:205], 0, s[36:37]
	s_mov_b32 m0, s70
	s_nop 0
	global_load_lds_dwordx4 v[194:195], off
	s_waitcnt vmcnt(8)
	s_waitcnt lgkmcnt(0)
	s_barrier
	s_setprio 1
	s_waitcnt lgkmcnt(0)
	v_mfma_f32_16x16x32_bf16 v[60:63], v[144:147], v[176:179], v[60:63]
	v_mfma_f32_16x16x32_bf16 v[56:59], v[152:155], v[176:179], v[56:59]
	v_mfma_f32_16x16x32_bf16 v[44:47], v[144:147], v[184:187], v[44:47]
	v_mfma_f32_16x16x32_bf16 v[40:43], v[152:155], v[184:187], v[40:43]
	v_mfma_f32_16x16x32_bf16 v[28:31], v[144:147], v[212:215], v[28:31]
	v_mfma_f32_16x16x32_bf16 v[24:27], v[152:155], v[212:215], v[24:27]
	v_mfma_f32_16x16x32_bf16 v[12:15], v[144:147], v[232:235], v[12:15]
	v_mfma_f32_16x16x32_bf16 v[8:11], v[152:155], v[232:235], v[8:11]
	v_mfma_f32_16x16x32_bf16 v[60:63], v[148:151], v[180:183], v[60:63]
	v_mfma_f32_16x16x32_bf16 v[56:59], v[156:159], v[180:183], v[56:59]
	v_mfma_f32_16x16x32_bf16 v[44:47], v[148:151], v[188:191], v[44:47]
	v_mfma_f32_16x16x32_bf16 v[40:43], v[156:159], v[188:191], v[40:43]
	v_mfma_f32_16x16x32_bf16 v[28:31], v[148:151], v[216:219], v[28:31]
	v_mfma_f32_16x16x32_bf16 v[24:27], v[156:159], v[216:219], v[24:27]
	v_mfma_f32_16x16x32_bf16 v[12:15], v[148:151], v[236:239], v[12:15]
	v_mfma_f32_16x16x32_bf16 v[8:11], v[156:159], v[236:239], v[8:11]
	s_setprio 0
	s_setprio 1
	v_mfma_f32_16x16x32_bf16 v[52:55], v[160:163], v[176:179], v[52:55]
	v_mfma_f32_16x16x32_bf16 v[48:51], v[168:171], v[176:179], v[48:51]
	v_mfma_f32_16x16x32_bf16 v[36:39], v[160:163], v[184:187], v[36:39]
	v_mfma_f32_16x16x32_bf16 v[32:35], v[168:171], v[184:187], v[32:35]
	v_mfma_f32_16x16x32_bf16 v[20:23], v[160:163], v[212:215], v[20:23]
	v_mfma_f32_16x16x32_bf16 v[16:19], v[168:171], v[212:215], v[16:19]
	v_mfma_f32_16x16x32_bf16 v[4:7], v[160:163], v[232:235], v[4:7]
	v_mfma_f32_16x16x32_bf16 v[0:3], v[168:171], v[232:235], v[0:3]
	v_mfma_f32_16x16x32_bf16 v[52:55], v[164:167], v[180:183], v[52:55]
	v_mfma_f32_16x16x32_bf16 v[48:51], v[172:175], v[180:183], v[48:51]
	v_mfma_f32_16x16x32_bf16 v[36:39], v[164:167], v[188:191], v[36:39]
	v_mfma_f32_16x16x32_bf16 v[32:35], v[172:175], v[188:191], v[32:35]
	s_barrier
; #define PG8_MMA(ai, bj, At, Bt) do { __builtin_amdgcn_s_setprio(1); _Pragma("unroll") for (int m = 0; m < 4; ++m) _Pragma("unroll") for (int n = 0; n < 2; ++n) _Pragma("unroll") for (int k = 0; k < 2; ++k) \
;         acc[ai][bj][m][n] = __builtin_amdgcn_mfma_f32_16x16x32_bf16(Bt[n][k], At[m][k], acc[ai][bj][m][n], 0, 0, 0); __builtin_amdgcn_s_setprio(0); } while (0)
; #define PG8_WAIT_V(n) asm volatile("s_waitcnt vmcnt(" #n ")" ::: "memory")
; #define PG8_WAIT_L(n) asm volatile("s_waitcnt lgkmcnt(" #n ")" ::: "memory")
; #define PG8_BAR __builtin_amdgcn_s_barrier()
; #define PG8_SCHED __builtin_amdgcn_sched_barrier(0)
; template <class Epi, class Sched, bool ALIGN_EPI = false, bool SP2 = false>
; __device__ __forceinline__ void gemm_phase(PG8_LAS unsigned char* lds, const Gemm g, const Sched& S, const Epi& E, const int tid) {
;     ...
;             PG8_WAIT_V(8); PG8_WAIT_L(0); PG8_BAR; PG8_MMA(1, 0, At, B0); PG8_MMA(1, 1, At, B1); PG8_BAR; PG8_SCHED;
;     ...
;         }
;         if constexpr (ALIGN_EPI) { if (wr == 0) PG8_BAR; }
;         if constexpr (!Epi::AFTER_DRAIN) { E(acc, cur, wr, wc, fr, fq); S.done(cur); }
;         if (!has_next) break;
; #pragma unroll
;         for (int a = 0; a < 2; ++a)
; #pragma unroll
;             for (int b = 0; b < 2; ++b)
; #pragma unroll
;                 for (int m = 0; m < 4; ++m)
; #pragma unroll
;                     for (int n = 0; n < 2; ++n) acc[a][b][m][n] = (f32x4){0.f, 0.f, 0.f, 0.f};
;         cur = nxt; cA = nA; cB = nB; ++ui;
	v_mfma_f32_16x16x32_bf16 v[20:23], v[164:167], v[216:219], v[20:23]
	v_mfma_f32_16x16x32_bf16 v[16:19], v[172:175], v[216:219], v[16:19]
	v_mfma_f32_16x16x32_bf16 v[4:7], v[164:167], v[236:239], v[4:7]
	v_mfma_f32_16x16x32_bf16 v[0:3], v[172:175], v[236:239], v[0:3]
	s_setprio 0
	s_add_i32 s74, s74, 2
	s_add_u32 s22, s22, 0x100
	s_addc_u32 s23, s23, 0
	s_cmp_gt_u32 s74, 41
	s_cbranch_scc0 .LBB0_127
	s_nop 7
	s_add_u32 s22, s19, 0xffffff00
	s_addc_u32 s23, s62, -1
	s_and_b64 vcc, exec, s[8:9]
	s_cbranch_vccnz .LBB0_130
	v_mov_b32_e32 v0, 0
	s_mov_b32 s14, s72
	s_mov_b32 s1, s73
	s_mov_b64 s[16:17], s[20:21]
	s_mov_b32 s71, s18
	v_mov_b32_e32 v1, v0
	v_mov_b32_e32 v2, v0
	v_mov_b32_e32 v3, v0
	v_mov_b32_e32 v4, v0
	v_mov_b32_e32 v5, v0
	v_mov_b32_e32 v6, v0
	v_mov_b32_e32 v7, v0
	v_mov_b32_e32 v16, v0
	v_mov_b32_e32 v17, v0
	v_mov_b32_e32 v18, v0
	v_mov_b32_e32 v19, v0
	v_mov_b32_e32 v20, v0
	v_mov_b32_e32 v21, v0
	v_mov_b32_e32 v22, v0
	v_mov_b32_e32 v23, v0
	v_mov_b32_e32 v32, v0
	v_mov_b32_e32 v33, v0
	v_mov_b32_e32 v34, v0
	v_mov_b32_e32 v35, v0
	v_mov_b32_e32 v36, v0
	v_mov_b32_e32 v37, v0
	v_mov_b32_e32 v38, v0
	v_mov_b32_e32 v39, v0
	v_mov_b32_e32 v48, v0
	v_mov_b32_e32 v49, v0
	v_mov_b32_e32 v50, v0
	v_mov_b32_e32 v51, v0
	v_mov_b32_e32 v52, v0
	v_mov_b32_e32 v53, v0
	v_mov_b32_e32 v54, v0
	v_mov_b32_e32 v55, v0
	v_mov_b32_e32 v8, v0
	v_mov_b32_e32 v9, v0
	v_mov_b32_e32 v10, v0
	v_mov_b32_e32 v11, v0
	v_mov_b32_e32 v12, v0
	v_mov_b32_e32 v13, v0
	v_mov_b32_e32 v14, v0
	v_mov_b32_e32 v15, v0
	v_mov_b32_e32 v24, v0
	v_mov_b32_e32 v25, v0
	v_mov_b32_e32 v26, v0
	v_mov_b32_e32 v27, v0
	v_mov_b32_e32 v28, v0
	v_mov_b32_e32 v29, v0
	v_mov_b32_e32 v30, v0
	v_mov_b32_e32 v31, v0
	v_mov_b32_e32 v40, v0
	v_mov_b32_e32 v41, v0
	v_mov_b32_e32 v42, v0
	v_mov_b32_e32 v43, v0
	v_mov_b32_e32 v44, v0
	v_mov_b32_e32 v45, v0
	v_mov_b32_e32 v46, v0
	v_mov_b32_e32 v47, v0
	v_mov_b32_e32 v56, v0
	v_mov_b32_e32 v57, v0
	v_mov_b32_e32 v58, v0
	v_mov_b32_e32 v59, v0
	v_mov_b32_e32 v60, v0
	v_mov_b32_e32 v61, v0
	v_mov_b32_e32 v62, v0
	v_mov_b32_e32 v63, v0
	v_mov_b32_e32 v64, v0
	v_mov_b32_e32 v65, v0
	v_mov_b32_e32 v66, v0
	v_mov_b32_e32 v67, v0
	v_mov_b32_e32 v68, v0
	v_mov_b32_e32 v69, v0
	v_mov_b32_e32 v70, v0
	v_mov_b32_e32 v71, v0
	v_mov_b32_e32 v80, v0
	v_mov_b32_e32 v81, v0
	v_mov_b32_e32 v82, v0
	v_mov_b32_e32 v83, v0
	v_mov_b32_e32 v84, v0
	v_mov_b32_e32 v85, v0
	v_mov_b32_e32 v86, v0
	v_mov_b32_e32 v87, v0
	v_mov_b32_e32 v96, v0
	v_mov_b32_e32 v97, v0
	v_mov_b32_e32 v98, v0
	v_mov_b32_e32 v99, v0
	v_mov_b32_e32 v100, v0
	v_mov_b32_e32 v101, v0
	v_mov_b32_e32 v102, v0
	v_mov_b32_e32 v103, v0
	v_mov_b32_e32 v112, v0
	v_mov_b32_e32 v113, v0
	v_mov_b32_e32 v114, v0
	v_mov_b32_e32 v115, v0
	v_mov_b32_e32 v116, v0
	v_mov_b32_e32 v117, v0
	v_mov_b32_e32 v118, v0
	v_mov_b32_e32 v119, v0
	v_mov_b32_e32 v72, v0
	v_mov_b32_e32 v73, v0
	v_mov_b32_e32 v74, v0
	v_mov_b32_e32 v75, v0
	v_mov_b32_e32 v76, v0
	v_mov_b32_e32 v77, v0
	v_mov_b32_e32 v78, v0
	v_mov_b32_e32 v79, v0
	v_mov_b32_e32 v88, v0
	v_mov_b32_e32 v89, v0
	v_mov_b32_e32 v90, v0
	v_mov_b32_e32 v91, v0
	v_mov_b32_e32 v92, v0
	v_mov_b32_e32 v93, v0
	v_mov_b32_e32 v94, v0
	v_mov_b32_e32 v95, v0
	v_mov_b32_e32 v104, v0
	v_mov_b32_e32 v105, v0
	v_mov_b32_e32 v106, v0
	v_mov_b32_e32 v107, v0
	v_mov_b32_e32 v108, v0
	v_mov_b32_e32 v109, v0
	v_mov_b32_e32 v110, v0
	v_mov_b32_e32 v111, v0
	v_mov_b32_e32 v120, v0
	v_mov_b32_e32 v121, v0
	v_mov_b32_e32 v122, v0
	v_mov_b32_e32 v123, v0
	v_mov_b32_e32 v124, v0
	v_mov_b32_e32 v125, v0
	v_mov_b32_e32 v126, v0
	v_mov_b32_e32 v127, v0
	s_load_dword s75, s[96:97], 0x0
	s_andn2_b64 vcc, exec, s[6:7]
	s_cbranch_vccnz .LBB0_131
	s_branch .LBB0_189

; #define PG8_STAGE(bufoff, gbase, voff) do { _Pragma("unroll") for (int _i = 0; _i < 2; ++_i) \
;         __builtin_amdgcn_global_load_lds((const unsigned*)((const char*)(gbase) + (voff)[_i]), (PG8_LAS unsigned*)(lds + (bufoff) + ldsw + _i * 8192), 16, 0, 0); } while (0)
; #define PG8_LDA(dst, b, h) do { _Pragma("unroll") for (int m = 0; m < 4; ++m) _Pragma("unroll") for (int k = 0; k < 2; ++k) dst[m][k] = *(const PG8_LAS bf16x8*)(lds + PG8_SA(b, h) + aoff + m * 2048 + k * 1024); } while (0)
; #define PG8_LDB(dst, b, h) do { _Pragma("unroll") for (int n = 0; n < 2; ++n) _Pragma("unroll") for (int k = 0; k < 2; ++k) dst[n][k] = *(const PG8_LAS bf16x8*)(lds + PG8_SB(b, h) + boff + n * 2048 + k * 1024); } while (0)
; #define PG8_MMA(ai, bj, At, Bt) do { __builtin_amdgcn_s_setprio(1); _Pragma("unroll") for (int m = 0; m < 4; ++m) _Pragma("unroll") for (int n = 0; n < 2; ++n) _Pragma("unroll") for (int k = 0; k < 2; ++k) \
;         acc[ai][bj][m][n] = __builtin_amdgcn_mfma_f32_16x16x32_bf16(Bt[n][k], At[m][k], acc[ai][bj][m][n], 0, 0, 0); __builtin_amdgcn_s_setprio(0); } while (0)
; #define PG8_WAIT_V(n) asm volatile("s_waitcnt vmcnt(" #n ")" ::: "memory")
; #define PG8_WAIT_L(n) asm volatile("s_waitcnt lgkmcnt(" #n ")" ::: "memory")
; template <class Epi, class Sched, bool ALIGN_EPI = false, bool SP2 = false>
; __device__ __forceinline__ void gemm_phase(PG8_LAS unsigned char* lds, const Gemm g, const Sched& S, const Epi& E, const int tid) {
;     ...
;             const bool last = (t == nt - 2);
;             const char* a1 = cA + (size_t)(t + 1) * kstep;
;             const char* a2 = last ? nA : cA + (size_t)(t + 2) * kstep; const char* b2 = last ? nB : cB + (size_t)(t + 2) * kstep;
;             const char* a3 = a2 + kstep; const char* b3 = b2 + kstep;
;             if (last && has_next) S.a_ready(nxt);
;             if constexpr (SP2) {
;             PG8_LDB(B0, 0, 0); PG8_LDB(B1, 0, 1); PG8_SCHED; PG8_LDA(At, 0, 0); PG8_STAGE(PG8_SA(1, 1), a1 + hstep, voffA);
;             PG8_WAIT_V(8); PG8_WAIT_L(0); PG8_BAR; PG8_MMA(0, 0, At, B0); PG8_MMA(0, 1, At, B1); PG8_BAR; PG8_SCHED;
;             PG8_LDA(At, 0, 1); PG8_STAGE(PG8_SB(0, 0), b2, voffB); PG8_STAGE(PG8_SB(0, 1), b2 + hstep, voffB); PG8_STAGE(PG8_SA(0, 0), a2, voffA);
;             PG8_WAIT_V(8); PG8_WAIT_L(0); PG8_BAR; PG8_MMA(1, 0, At, B0); PG8_MMA(1, 1, At, B1); PG8_BAR; PG8_SCHED;
.LBB0_143:
	s_add_u32 s58, s44, 0xfffc0080
	s_addc_u32 s59, s45, -1
	s_add_i32 s72, 0, 0x10000
	s_cmp_eq_u32 s71, 12
	s_cselect_b32 s79, s17, s59
	s_cselect_b32 s78, s55, s58
	v_add_u32_e32 v138, s72, v140
	s_cselect_b32 s59, s15, s70
	s_cselect_b32 s58, s60, s62
	s_add_i32 s74, 0, 0x14000
	ds_read_b128 v[142:145], v138
	ds_read_b128 v[146:149], v138 offset:1024
	ds_read_b128 v[150:153], v138 offset:2048
	ds_read_b128 v[154:157], v138 offset:3072
	v_add_u32_e32 v138, s74, v140
	ds_read_b128 v[158:161], v138
	ds_read_b128 v[162:165], v138 offset:1024
	ds_read_b128 v[166:169], v138 offset:2048
	ds_read_b128 v[170:173], v138 offset:3072
	v_lshl_add_u64 v[138:139], s[44:45], 0, v[134:135]
	s_add_i32 m0, s38, 0xc000
	ds_read_b128 v[174:177], v141
	ds_read_b128 v[178:181], v141 offset:1024
	ds_read_b128 v[182:185], v141 offset:2048
	ds_read_b128 v[186:189], v141 offset:3072
	ds_read_b128 v[212:215], v141 offset:4096
	ds_read_b128 v[216:219], v141 offset:5120
	ds_read_b128 v[232:235], v141 offset:6144
	ds_read_b128 v[236:239], v141 offset:7168
	global_load_lds_dwordx4 v[138:139], off
	v_lshl_add_u64 v[138:139], s[44:45], 0, v[136:137]
	s_add_i32 m0, s38, 0xe000
	s_nop 0
	global_load_lds_dwordx4 v[138:139], off
	s_waitcnt vmcnt(8)
	s_waitcnt lgkmcnt(0)
	s_barrier
	s_setprio 1
	s_waitcnt lgkmcnt(0)
	v_mfma_f32_16x16x32_bf16 v[124:127], v[142:145], v[174:177], v[124:127]
	v_mfma_f32_16x16x32_bf16 v[116:119], v[150:153], v[174:177], v[116:119]
	v_mfma_f32_16x16x32_bf16 v[108:111], v[142:145], v[182:185], v[108:111]
	v_mfma_f32_16x16x32_bf16 v[100:103], v[150:153], v[182:185], v[100:103]
	v_mfma_f32_16x16x32_bf16 v[92:95], v[142:145], v[212:215], v[92:95]
	v_mfma_f32_16x16x32_bf16 v[84:87], v[150:153], v[212:215], v[84:87]
	v_mfma_f32_16x16x32_bf16 v[76:79], v[142:145], v[232:235], v[76:79]
	v_mfma_f32_16x16x32_bf16 v[68:71], v[150:153], v[232:235], v[68:71]
	v_mfma_f32_16x16x32_bf16 v[124:127], v[146:149], v[178:181], v[124:127]
	v_mfma_f32_16x16x32_bf16 v[116:119], v[154:157], v[178:181], v[116:119]
	v_mfma_f32_16x16x32_bf16 v[108:111], v[146:149], v[186:189], v[108:111]
	v_mfma_f32_16x16x32_bf16 v[100:103], v[154:157], v[186:189], v[100:103]
	v_mfma_f32_16x16x32_bf16 v[92:95], v[146:149], v[216:219], v[92:95]
	v_mfma_f32_16x16x32_bf16 v[84:87], v[154:157], v[216:219], v[84:87]
	v_mfma_f32_16x16x32_bf16 v[76:79], v[146:149], v[236:239], v[76:79]
	v_mfma_f32_16x16x32_bf16 v[68:71], v[154:157], v[236:239], v[68:71]
	s_setprio 0
	s_setprio 1
	v_mfma_f32_16x16x32_bf16 v[120:123], v[158:161], v[174:177], v[120:123]
	v_mfma_f32_16x16x32_bf16 v[112:115], v[166:169], v[174:177], v[112:115]
	v_mfma_f32_16x16x32_bf16 v[104:107], v[158:161], v[182:185], v[104:107]
	v_mfma_f32_16x16x32_bf16 v[96:99], v[166:169], v[182:185], v[96:99]
	v_mfma_f32_16x16x32_bf16 v[88:91], v[158:161], v[212:215], v[88:91]
	v_mfma_f32_16x16x32_bf16 v[80:83], v[166:169], v[212:215], v[80:83]
	v_mfma_f32_16x16x32_bf16 v[72:75], v[158:161], v[232:235], v[72:75]
	v_mfma_f32_16x16x32_bf16 v[64:67], v[166:169], v[232:235], v[64:67]
	v_mfma_f32_16x16x32_bf16 v[120:123], v[162:165], v[178:181], v[120:123]
	v_mfma_f32_16x16x32_bf16 v[112:115], v[170:173], v[178:181], v[112:115]
	v_mfma_f32_16x16x32_bf16 v[104:107], v[162:165], v[186:189], v[104:107]
	v_mfma_f32_16x16x32_bf16 v[96:99], v[170:173], v[186:189], v[96:99]
	s_barrier
	v_mfma_f32_16x16x32_bf16 v[88:91], v[162:165], v[216:219], v[88:91]
	v_mfma_f32_16x16x32_bf16 v[80:83], v[170:173], v[216:219], v[80:83]
	v_mfma_f32_16x16x32_bf16 v[72:75], v[162:165], v[236:239], v[72:75]
	v_mfma_f32_16x16x32_bf16 v[64:67], v[170:173], v[236:239], v[64:67]
	s_setprio 0
	s_add_i32 s72, s72, s34
	v_lshl_add_u64 v[138:139], s[58:59], 0, v[192:193]
	s_mov_b32 m0, s72
	ds_read_b128 v[174:177], v141 offset:16384
	ds_read_b128 v[178:181], v141 offset:17408
	ds_read_b128 v[182:185], v141 offset:18432
	ds_read_b128 v[186:189], v141 offset:19456
	ds_read_b128 v[212:215], v141 offset:20480
	ds_read_b128 v[216:219], v141 offset:21504
	ds_read_b128 v[232:235], v141 offset:22528
	ds_read_b128 v[236:239], v141 offset:23552
	global_load_lds_dwordx4 v[138:139], off
	s_add_i32 m0, s72, 0x2000
	s_add_u32 s72, s58, 0x40000
	v_lshl_add_u64 v[190:191], s[58:59], 0, v[128:129]
	s_addc_u32 s73, s59, 0
	s_add_i32 s74, s74, s34
	global_load_lds_dwordx4 v[190:191], off
	v_lshl_add_u64 v[194:195], s[72:73], 0, v[192:193]
	s_mov_b32 m0, s74
	v_lshl_add_u64 v[196:197], s[78:79], 0, v[130:131]
	global_load_lds_dwordx4 v[194:195], off
	v_lshl_add_u64 v[194:195], s[72:73], 0, v[128:129]
	s_add_i32 m0, s74, 0x2000
	s_nop 0
	global_load_lds_dwordx4 v[194:195], off
	v_lshl_add_u64 v[194:195], s[78:79], 0, v[132:133]
	s_mov_b32 m0, s38
	s_nop 0
	global_load_lds_dwordx4 v[194:195], off
	s_mov_b32 m0, s40
	s_nop 0
	global_load_lds_dwordx4 v[196:197], off
	s_waitcnt vmcnt(8)
	s_waitcnt lgkmcnt(0)
	s_barrier
; #define PG8_STAGE(bufoff, gbase, voff) do { _Pragma("unroll") for (int _i = 0; _i < 2; ++_i) \
;         __builtin_amdgcn_global_load_lds((const unsigned*)((const char*)(gbase) + (voff)[_i]), (PG8_LAS unsigned*)(lds + (bufoff) + ldsw + _i * 8192), 16, 0, 0); } while (0)
; #define PG8_LDA(dst, b, h) do { _Pragma("unroll") for (int m = 0; m < 4; ++m) _Pragma("unroll") for (int k = 0; k < 2; ++k) dst[m][k] = *(const PG8_LAS bf16x8*)(lds + PG8_SA(b, h) + aoff + m * 2048 + k * 1024); } while (0)
; #define PG8_LDB(dst, b, h) do { _Pragma("unroll") for (int n = 0; n < 2; ++n) _Pragma("unroll") for (int k = 0; k < 2; ++k) dst[n][k] = *(const PG8_LAS bf16x8*)(lds + PG8_SB(b, h) + boff + n * 2048 + k * 1024); } while (0)
; #define PG8_MMA(ai, bj, At, Bt) do { __builtin_amdgcn_s_setprio(1); _Pragma("unroll") for (int m = 0; m < 4; ++m) _Pragma("unroll") for (int n = 0; n < 2; ++n) _Pragma("unroll") for (int k = 0; k < 2; ++k) \
;         acc[ai][bj][m][n] = __builtin_amdgcn_mfma_f32_16x16x32_bf16(Bt[n][k], At[m][k], acc[ai][bj][m][n], 0, 0, 0); __builtin_amdgcn_s_setprio(0); } while (0)
; #define PG8_WAIT_V(n) asm volatile("s_waitcnt vmcnt(" #n ")" ::: "memory")
; #define PG8_WAIT_L(n) asm volatile("s_waitcnt lgkmcnt(" #n ")" ::: "memory")
; #define PG8_BAR __builtin_amdgcn_s_barrier()
; #define PG8_SCHED __builtin_amdgcn_sched_barrier(0)
; template <class Epi, class Sched, bool ALIGN_EPI = false, bool SP2 = false>
; __device__ __forceinline__ void gemm_phase(PG8_LAS unsigned char* lds, const Gemm g, const Sched& S, const Epi& E, const int tid) {
;     ...
;             PG8_WAIT_V(8); PG8_WAIT_L(0); PG8_BAR; PG8_MMA(1, 0, At, B0); PG8_MMA(1, 1, At, B1); PG8_BAR; PG8_SCHED;
;             PG8_LDB(B0, 1, 0); PG8_LDB(B1, 1, 1); PG8_SCHED; PG8_LDA(At, 1, 0); PG8_STAGE(PG8_SA(0, 1), a2 + hstep, voffA);
;             PG8_WAIT_V(8); PG8_WAIT_L(0); PG8_BAR; PG8_MMA(0, 0, At, B0); PG8_MMA(0, 1, At, B1); PG8_BAR; PG8_SCHED;
;             PG8_LDA(At, 1, 1); PG8_STAGE(PG8_SB(1, 0), b3, voffB); PG8_STAGE(PG8_SB(1, 1), b3 + hstep, voffB); PG8_STAGE(PG8_SA(1, 0), a3, voffA);
	s_setprio 1
	s_waitcnt lgkmcnt(0)
	v_mfma_f32_16x16x32_bf16 v[60:63], v[142:145], v[174:177], v[60:63]
	v_mfma_f32_16x16x32_bf16 v[52:55], v[150:153], v[174:177], v[52:55]
	v_mfma_f32_16x16x32_bf16 v[44:47], v[142:145], v[182:185], v[44:47]
	v_mfma_f32_16x16x32_bf16 v[36:39], v[150:153], v[182:185], v[36:39]
	v_mfma_f32_16x16x32_bf16 v[28:31], v[142:145], v[212:215], v[28:31]
	v_mfma_f32_16x16x32_bf16 v[20:23], v[150:153], v[212:215], v[20:23]
	v_mfma_f32_16x16x32_bf16 v[12:15], v[142:145], v[232:235], v[12:15]
	v_mfma_f32_16x16x32_bf16 v[4:7], v[150:153], v[232:235], v[4:7]
	v_mfma_f32_16x16x32_bf16 v[60:63], v[146:149], v[178:181], v[60:63]
	v_mfma_f32_16x16x32_bf16 v[52:55], v[154:157], v[178:181], v[52:55]
	v_mfma_f32_16x16x32_bf16 v[44:47], v[146:149], v[186:189], v[44:47]
	v_mfma_f32_16x16x32_bf16 v[36:39], v[154:157], v[186:189], v[36:39]
	v_mfma_f32_16x16x32_bf16 v[28:31], v[146:149], v[216:219], v[28:31]
	v_mfma_f32_16x16x32_bf16 v[20:23], v[154:157], v[216:219], v[20:23]
	v_mfma_f32_16x16x32_bf16 v[12:15], v[146:149], v[236:239], v[12:15]
	v_mfma_f32_16x16x32_bf16 v[4:7], v[154:157], v[236:239], v[4:7]
	s_setprio 0
	s_setprio 1
	v_mfma_f32_16x16x32_bf16 v[56:59], v[158:161], v[174:177], v[56:59]
	v_mfma_f32_16x16x32_bf16 v[48:51], v[166:169], v[174:177], v[48:51]
	v_mfma_f32_16x16x32_bf16 v[40:43], v[158:161], v[182:185], v[40:43]
	v_mfma_f32_16x16x32_bf16 v[32:35], v[166:169], v[182:185], v[32:35]
	v_mfma_f32_16x16x32_bf16 v[24:27], v[158:161], v[212:215], v[24:27]
	v_mfma_f32_16x16x32_bf16 v[16:19], v[166:169], v[212:215], v[16:19]
	v_mfma_f32_16x16x32_bf16 v[8:11], v[158:161], v[232:235], v[8:11]
	v_mfma_f32_16x16x32_bf16 v[0:3], v[166:169], v[232:235], v[0:3]
	v_mfma_f32_16x16x32_bf16 v[56:59], v[162:165], v[178:181], v[56:59]
	v_mfma_f32_16x16x32_bf16 v[48:51], v[170:173], v[178:181], v[48:51]
	v_mfma_f32_16x16x32_bf16 v[40:43], v[162:165], v[186:189], v[40:43]
	v_mfma_f32_16x16x32_bf16 v[32:35], v[170:173], v[186:189], v[32:35]
	s_barrier
	v_mfma_f32_16x16x32_bf16 v[24:27], v[162:165], v[216:219], v[24:27]
	v_mfma_f32_16x16x32_bf16 v[16:19], v[170:173], v[216:219], v[16:19]
	v_mfma_f32_16x16x32_bf16 v[8:11], v[162:165], v[236:239], v[8:11]
	v_mfma_f32_16x16x32_bf16 v[0:3], v[170:173], v[236:239], v[0:3]
	s_setprio 0
	s_add_i32 s74, 0, 0x18000
	s_add_i32 s75, 0, 0x1c000
	v_add_u32_e32 v154, s74, v140
	v_add_u32_e32 v170, s75, v140
	ds_read_b128 v[142:145], v154
	ds_read_b128 v[146:149], v154 offset:1024
	ds_read_b128 v[150:153], v154 offset:2048
	ds_read_b128 v[154:157], v154 offset:3072
	ds_read_b128 v[158:161], v170
	ds_read_b128 v[162:165], v170 offset:1024
	ds_read_b128 v[166:169], v170 offset:2048
	ds_read_b128 v[170:173], v170 offset:3072
	s_add_u32 s72, s78, 0x40000
	s_addc_u32 s73, s79, 0
	s_mov_b32 m0, s41
	v_lshl_add_u64 v[202:203], s[72:73], 0, v[132:133]
	ds_read_b128 v[174:177], v141 offset:32768
	ds_read_b128 v[178:181], v141 offset:33792
	ds_read_b128 v[182:185], v141 offset:34816
	ds_read_b128 v[186:189], v141 offset:35840
	ds_read_b128 v[212:215], v141 offset:36864
	ds_read_b128 v[216:219], v141 offset:37888
	ds_read_b128 v[232:235], v141 offset:38912
	ds_read_b128 v[236:239], v141 offset:39936
	global_load_lds_dwordx4 v[202:203], off
	v_lshl_add_u64 v[202:203], s[72:73], 0, v[130:131]
	s_mov_b32 m0, s46
	s_nop 0
	global_load_lds_dwordx4 v[202:203], off
	s_waitcnt vmcnt(8)
	s_waitcnt lgkmcnt(0)
	s_barrier
	s_setprio 1
	s_waitcnt lgkmcnt(0)
	v_mfma_f32_16x16x32_bf16 v[124:127], v[142:145], v[174:177], v[124:127]
	v_mfma_f32_16x16x32_bf16 v[116:119], v[150:153], v[174:177], v[116:119]
	v_mfma_f32_16x16x32_bf16 v[108:111], v[142:145], v[182:185], v[108:111]
	v_mfma_f32_16x16x32_bf16 v[100:103], v[150:153], v[182:185], v[100:103]
	v_mfma_f32_16x16x32_bf16 v[92:95], v[142:145], v[212:215], v[92:95]
	v_mfma_f32_16x16x32_bf16 v[84:87], v[150:153], v[212:215], v[84:87]
	v_mfma_f32_16x16x32_bf16 v[76:79], v[142:145], v[232:235], v[76:79]
	v_mfma_f32_16x16x32_bf16 v[68:71], v[150:153], v[232:235], v[68:71]
	v_mfma_f32_16x16x32_bf16 v[124:127], v[146:149], v[178:181], v[124:127]
	v_mfma_f32_16x16x32_bf16 v[116:119], v[154:157], v[178:181], v[116:119]
	v_mfma_f32_16x16x32_bf16 v[108:111], v[146:149], v[186:189], v[108:111]
	v_mfma_f32_16x16x32_bf16 v[100:103], v[154:157], v[186:189], v[100:103]
	v_mfma_f32_16x16x32_bf16 v[92:95], v[146:149], v[216:219], v[92:95]
	v_mfma_f32_16x16x32_bf16 v[84:87], v[154:157], v[216:219], v[84:87]
	v_mfma_f32_16x16x32_bf16 v[76:79], v[146:149], v[236:239], v[76:79]
	v_mfma_f32_16x16x32_bf16 v[68:71], v[154:157], v[236:239], v[68:71]
	s_setprio 0
	s_setprio 1
	v_mfma_f32_16x16x32_bf16 v[120:123], v[158:161], v[174:177], v[120:123]
	v_mfma_f32_16x16x32_bf16 v[112:115], v[166:169], v[174:177], v[112:115]
	v_mfma_f32_16x16x32_bf16 v[104:107], v[158:161], v[182:185], v[104:107]
	v_mfma_f32_16x16x32_bf16 v[96:99], v[166:169], v[182:185], v[96:99]
	v_mfma_f32_16x16x32_bf16 v[88:91], v[158:161], v[212:215], v[88:91]
	v_mfma_f32_16x16x32_bf16 v[80:83], v[166:169], v[212:215], v[80:83]
	v_mfma_f32_16x16x32_bf16 v[72:75], v[158:161], v[232:235], v[72:75]
	v_mfma_f32_16x16x32_bf16 v[64:67], v[166:169], v[232:235], v[64:67]
	v_mfma_f32_16x16x32_bf16 v[120:123], v[162:165], v[178:181], v[120:123]
	v_mfma_f32_16x16x32_bf16 v[112:115], v[170:173], v[178:181], v[112:115]
	v_mfma_f32_16x16x32_bf16 v[104:107], v[162:165], v[186:189], v[104:107]
	v_mfma_f32_16x16x32_bf16 v[96:99], v[170:173], v[186:189], v[96:99]
	s_barrier
; #define PG8_STAGE(bufoff, gbase, voff) do { _Pragma("unroll") for (int _i = 0; _i < 2; ++_i) \
;         __builtin_amdgcn_global_load_lds((const unsigned*)((const char*)(gbase) + (voff)[_i]), (PG8_LAS unsigned*)(lds + (bufoff) + ldsw + _i * 8192), 16, 0, 0); } while (0)
; #define PG8_LDA(dst, b, h) do { _Pragma("unroll") for (int m = 0; m < 4; ++m) _Pragma("unroll") for (int k = 0; k < 2; ++k) dst[m][k] = *(const PG8_LAS bf16x8*)(lds + PG8_SA(b, h) + aoff + m * 2048 + k * 1024); } while (0)
; #define PG8_MMA(ai, bj, At, Bt) do { __builtin_amdgcn_s_setprio(1); _Pragma("unroll") for (int m = 0; m < 4; ++m) _Pragma("unroll") for (int n = 0; n < 2; ++n) _Pragma("unroll") for (int k = 0; k < 2; ++k) \
;         acc[ai][bj][m][n] = __builtin_amdgcn_mfma_f32_16x16x32_bf16(Bt[n][k], At[m][k], acc[ai][bj][m][n], 0, 0, 0); __builtin_amdgcn_s_setprio(0); } while (0)
; #define PG8_WAIT_V(n) asm volatile("s_waitcnt vmcnt(" #n ")" ::: "memory")
; #define PG8_WAIT_L(n) asm volatile("s_waitcnt lgkmcnt(" #n ")" ::: "memory")
; #define PG8_BAR __builtin_amdgcn_s_barrier()
; #define PG8_SCHED __builtin_amdgcn_sched_barrier(0)
; template <class Epi, class Sched, bool ALIGN_EPI = false, bool SP2 = false>
; __device__ __forceinline__ void gemm_phase(PG8_LAS unsigned char* lds, const Gemm g, const Sched& S, const Epi& E, const int tid) {
;     ...
;             PG8_WAIT_V(8); PG8_WAIT_L(0); PG8_BAR; PG8_MMA(0, 0, At, B0); PG8_MMA(0, 1, At, B1); PG8_BAR; PG8_SCHED;
;             PG8_LDA(At, 1, 1); PG8_STAGE(PG8_SB(1, 0), b3, voffB); PG8_STAGE(PG8_SB(1, 1), b3 + hstep, voffB); PG8_STAGE(PG8_SA(1, 0), a3, voffA);
;             PG8_WAIT_V(8); PG8_WAIT_L(0); PG8_BAR; PG8_MMA(1, 0, At, B0); PG8_MMA(1, 1, At, B1); PG8_BAR; PG8_SCHED;
;     ...
;         }
;         if constexpr (ALIGN_EPI) { if (wr == 0) PG8_BAR; }
	v_mfma_f32_16x16x32_bf16 v[88:91], v[162:165], v[216:219], v[88:91]
	v_mfma_f32_16x16x32_bf16 v[80:83], v[170:173], v[216:219], v[80:83]
	v_mfma_f32_16x16x32_bf16 v[72:75], v[162:165], v[236:239], v[72:75]
	v_mfma_f32_16x16x32_bf16 v[64:67], v[170:173], v[236:239], v[64:67]
	s_setprio 0
	s_add_i32 s72, s74, s34
	v_lshl_add_u64 v[138:139], v[138:139], 0, s[36:37]
	s_mov_b32 m0, s72
	ds_read_b128 v[174:177], v141 offset:49152
	ds_read_b128 v[178:181], v141 offset:50176
	ds_read_b128 v[182:185], v141 offset:51200
	ds_read_b128 v[186:189], v141 offset:52224
	ds_read_b128 v[212:215], v141 offset:53248
	ds_read_b128 v[216:219], v141 offset:54272
	ds_read_b128 v[232:235], v141 offset:55296
	ds_read_b128 v[236:239], v141 offset:56320
	global_load_lds_dwordx4 v[138:139], off
	s_add_i32 m0, s72, 0x2000
	s_add_u32 s58, s58, 0x40080
	v_lshl_add_u64 v[138:139], v[190:191], 0, s[36:37]
	s_addc_u32 s59, s59, 0
	s_add_i32 s72, s75, s34
	global_load_lds_dwordx4 v[138:139], off
	v_lshl_add_u64 v[138:139], s[58:59], 0, v[192:193]
	s_mov_b32 m0, s72
	s_nop 0
	global_load_lds_dwordx4 v[138:139], off
	v_lshl_add_u64 v[138:139], s[58:59], 0, v[128:129]
	s_add_i32 m0, s72, 0x2000
	s_nop 0
	global_load_lds_dwordx4 v[138:139], off
	v_lshl_add_u64 v[138:139], v[194:195], 0, s[36:37]
	s_mov_b32 m0, s47
	s_nop 0
	global_load_lds_dwordx4 v[138:139], off
	v_lshl_add_u64 v[138:139], v[196:197], 0, s[36:37]
	s_mov_b32 m0, s52
	s_nop 0
	global_load_lds_dwordx4 v[138:139], off
	s_waitcnt vmcnt(8)
	s_waitcnt lgkmcnt(0)
	s_barrier
	s_setprio 1
	s_waitcnt lgkmcnt(0)
	v_mfma_f32_16x16x32_bf16 v[60:63], v[142:145], v[174:177], v[60:63]
	v_mfma_f32_16x16x32_bf16 v[52:55], v[150:153], v[174:177], v[52:55]
	v_mfma_f32_16x16x32_bf16 v[44:47], v[142:145], v[182:185], v[44:47]
	v_mfma_f32_16x16x32_bf16 v[36:39], v[150:153], v[182:185], v[36:39]
	v_mfma_f32_16x16x32_bf16 v[28:31], v[142:145], v[212:215], v[28:31]
	v_mfma_f32_16x16x32_bf16 v[20:23], v[150:153], v[212:215], v[20:23]
	v_mfma_f32_16x16x32_bf16 v[12:15], v[142:145], v[232:235], v[12:15]
	v_mfma_f32_16x16x32_bf16 v[4:7], v[150:153], v[232:235], v[4:7]
	v_mfma_f32_16x16x32_bf16 v[60:63], v[146:149], v[178:181], v[60:63]
	v_mfma_f32_16x16x32_bf16 v[52:55], v[154:157], v[178:181], v[52:55]
	v_mfma_f32_16x16x32_bf16 v[44:47], v[146:149], v[186:189], v[44:47]
	v_mfma_f32_16x16x32_bf16 v[36:39], v[154:157], v[186:189], v[36:39]
	v_mfma_f32_16x16x32_bf16 v[28:31], v[146:149], v[216:219], v[28:31]
	v_mfma_f32_16x16x32_bf16 v[20:23], v[154:157], v[216:219], v[20:23]
	v_mfma_f32_16x16x32_bf16 v[12:15], v[146:149], v[236:239], v[12:15]
	v_mfma_f32_16x16x32_bf16 v[4:7], v[154:157], v[236:239], v[4:7]
	s_setprio 0
	s_setprio 1
	v_mfma_f32_16x16x32_bf16 v[56:59], v[158:161], v[174:177], v[56:59]
	v_mfma_f32_16x16x32_bf16 v[48:51], v[166:169], v[174:177], v[48:51]
	v_mfma_f32_16x16x32_bf16 v[40:43], v[158:161], v[182:185], v[40:43]
	v_mfma_f32_16x16x32_bf16 v[32:35], v[166:169], v[182:185], v[32:35]
	v_mfma_f32_16x16x32_bf16 v[24:27], v[158:161], v[212:215], v[24:27]
	v_mfma_f32_16x16x32_bf16 v[16:19], v[166:169], v[212:215], v[16:19]
	v_mfma_f32_16x16x32_bf16 v[8:11], v[158:161], v[232:235], v[8:11]
	v_mfma_f32_16x16x32_bf16 v[0:3], v[166:169], v[232:235], v[0:3]
	v_mfma_f32_16x16x32_bf16 v[56:59], v[162:165], v[178:181], v[56:59]
	v_mfma_f32_16x16x32_bf16 v[48:51], v[170:173], v[178:181], v[48:51]
	v_mfma_f32_16x16x32_bf16 v[40:43], v[162:165], v[186:189], v[40:43]
	v_mfma_f32_16x16x32_bf16 v[32:35], v[170:173], v[186:189], v[32:35]
	s_barrier
	v_mfma_f32_16x16x32_bf16 v[24:27], v[162:165], v[216:219], v[24:27]
	v_mfma_f32_16x16x32_bf16 v[16:19], v[170:173], v[216:219], v[16:19]
	v_mfma_f32_16x16x32_bf16 v[8:11], v[162:165], v[236:239], v[8:11]
	v_mfma_f32_16x16x32_bf16 v[0:3], v[170:173], v[236:239], v[0:3]
	s_setprio 0
	s_add_i32 s71, s71, 2
	s_add_u32 s44, s44, 0x100
	s_addc_u32 s45, s45, 0
	s_add_u32 s62, s62, 0x100
	s_addc_u32 s70, s70, 0
	s_cmp_gt_u32 s71, 13
	s_cbranch_scc0 .LBB0_143
	s_nop 7
	s_and_b64 vcc, exec, s[10:11]
	s_cbranch_vccz .LBB0_146
	s_barrier

; #define PG8_STAGE(bufoff, gbase, voff) do { _Pragma("unroll") for (int _i = 0; _i < 2; ++_i) \
;         __builtin_amdgcn_global_load_lds((const unsigned*)((const char*)(gbase) + (voff)[_i]), (PG8_LAS unsigned*)(lds + (bufoff) + ldsw + _i * 8192), 16, 0, 0); } while (0)
; #define PG8_LDA(dst, b, h) do { _Pragma("unroll") for (int m = 0; m < 4; ++m) _Pragma("unroll") for (int k = 0; k < 2; ++k) dst[m][k] = *(const PG8_LAS bf16x8*)(lds + PG8_SA(b, h) + aoff + m * 2048 + k * 1024); } while (0)
; #define PG8_LDB(dst, b, h) do { _Pragma("unroll") for (int n = 0; n < 2; ++n) _Pragma("unroll") for (int k = 0; k < 2; ++k) dst[n][k] = *(const PG8_LAS bf16x8*)(lds + PG8_SB(b, h) + boff + n * 2048 + k * 1024); } while (0)
; #define PG8_MMA(ai, bj, At, Bt) do { __builtin_amdgcn_s_setprio(1); _Pragma("unroll") for (int m = 0; m < 4; ++m) _Pragma("unroll") for (int n = 0; n < 2; ++n) _Pragma("unroll") for (int k = 0; k < 2; ++k) \
;         acc[ai][bj][m][n] = __builtin_amdgcn_mfma_f32_16x16x32_bf16(Bt[n][k], At[m][k], acc[ai][bj][m][n], 0, 0, 0); __builtin_amdgcn_s_setprio(0); } while (0)
; #define PG8_WAIT_V(n) asm volatile("s_waitcnt vmcnt(" #n ")" ::: "memory")
; #define PG8_WAIT_L(n) asm volatile("s_waitcnt lgkmcnt(" #n ")" ::: "memory")
; template <class Epi, class Sched, bool ALIGN_EPI = false, bool SP2 = false>
; __device__ __forceinline__ void gemm_phase(PG8_LAS unsigned char* lds, const Gemm g, const Sched& S, const Epi& E, const int tid) {
;     ...
;             const bool last = (t == nt - 2);
;             const char* a1 = cA + (size_t)(t + 1) * kstep;
;             const char* a2 = last ? nA : cA + (size_t)(t + 2) * kstep; const char* b2 = last ? nB : cB + (size_t)(t + 2) * kstep;
;             const char* a3 = a2 + kstep; const char* b3 = b2 + kstep;
;             if (last && has_next) S.a_ready(nxt);
;             if constexpr (SP2) {
;             PG8_LDB(B0, 0, 0); PG8_LDB(B1, 0, 1); PG8_SCHED; PG8_LDA(At, 0, 0); PG8_STAGE(PG8_SA(1, 1), a1 + hstep, voffA);
;             PG8_WAIT_V(8); PG8_WAIT_L(0); PG8_BAR; PG8_MMA(0, 0, At, B0); PG8_MMA(0, 1, At, B1); PG8_BAR; PG8_SCHED;
;             PG8_LDA(At, 0, 1); PG8_STAGE(PG8_SB(0, 0), b2, voffB); PG8_STAGE(PG8_SB(0, 1), b2 + hstep, voffB); PG8_STAGE(PG8_SA(0, 0), a2, voffA);
;             PG8_WAIT_V(8); PG8_WAIT_L(0); PG8_BAR; PG8_MMA(1, 0, At, B0); PG8_MMA(1, 1, At, B1); PG8_BAR; PG8_SCHED;
.LBB0_183:
	s_add_u32 s28, s22, 0xfffc0080
	s_addc_u32 s29, s23, -1
	s_add_i32 s71, 0, 0x10000
	s_cmp_eq_u32 s70, 12
	s_cselect_b32 s45, s17, s29
	s_cselect_b32 s44, s58, s28
	s_cselect_b32 s29, s13, s62
	s_cselect_b32 s28, s59, s60
	s_add_i32 s74, 0, 0x14000
	v_add_u32_e32 v154, s71, v140
	v_add_u32_e32 v170, s74, v140
	ds_read_b128 v[142:145], v154
	ds_read_b128 v[146:149], v154 offset:1024
	ds_read_b128 v[150:153], v154 offset:2048
	ds_read_b128 v[154:157], v154 offset:3072
	ds_read_b128 v[158:161], v170
	ds_read_b128 v[162:165], v170 offset:1024
	ds_read_b128 v[166:169], v170 offset:2048
	ds_read_b128 v[170:173], v170 offset:3072
	v_lshl_add_u64 v[190:191], s[22:23], 0, v[136:137]
	s_add_i32 m0, s15, 0xc000
	ds_read_b128 v[174:177], v141
	ds_read_b128 v[178:181], v141 offset:1024
	ds_read_b128 v[182:185], v141 offset:2048
	ds_read_b128 v[186:189], v141 offset:3072
	ds_read_b128 v[212:215], v141 offset:4096
	ds_read_b128 v[216:219], v141 offset:5120
	ds_read_b128 v[232:235], v141 offset:6144
	ds_read_b128 v[236:239], v141 offset:7168
	global_load_lds_dwordx4 v[190:191], off
	v_lshl_add_u64 v[190:191], s[22:23], 0, v[138:139]
	s_add_i32 m0, s15, 0xe000
	s_nop 0
	global_load_lds_dwordx4 v[190:191], off
	s_waitcnt vmcnt(8)
	s_waitcnt lgkmcnt(0)
	s_barrier
	s_setprio 1
	s_waitcnt lgkmcnt(0)
	v_mfma_f32_16x16x32_bf16 v[124:127], v[142:145], v[174:177], v[124:127]
	v_mfma_f32_16x16x32_bf16 v[120:123], v[150:153], v[174:177], v[120:123]
	v_mfma_f32_16x16x32_bf16 v[116:119], v[142:145], v[182:185], v[116:119]
	v_mfma_f32_16x16x32_bf16 v[112:115], v[150:153], v[182:185], v[112:115]
	v_mfma_f32_16x16x32_bf16 v[100:103], v[142:145], v[212:215], v[100:103]
	v_mfma_f32_16x16x32_bf16 v[96:99], v[150:153], v[212:215], v[96:99]
	v_mfma_f32_16x16x32_bf16 v[84:87], v[142:145], v[232:235], v[84:87]
	v_mfma_f32_16x16x32_bf16 v[80:83], v[150:153], v[232:235], v[80:83]
	v_mfma_f32_16x16x32_bf16 v[124:127], v[146:149], v[178:181], v[124:127]
	v_mfma_f32_16x16x32_bf16 v[120:123], v[154:157], v[178:181], v[120:123]
	v_mfma_f32_16x16x32_bf16 v[116:119], v[146:149], v[186:189], v[116:119]
	v_mfma_f32_16x16x32_bf16 v[112:115], v[154:157], v[186:189], v[112:115]
	v_mfma_f32_16x16x32_bf16 v[100:103], v[146:149], v[216:219], v[100:103]
	v_mfma_f32_16x16x32_bf16 v[96:99], v[154:157], v[216:219], v[96:99]
	v_mfma_f32_16x16x32_bf16 v[84:87], v[146:149], v[236:239], v[84:87]
	v_mfma_f32_16x16x32_bf16 v[80:83], v[154:157], v[236:239], v[80:83]
	s_setprio 0
	s_setprio 1
	v_mfma_f32_16x16x32_bf16 v[108:111], v[158:161], v[174:177], v[108:111]
	v_mfma_f32_16x16x32_bf16 v[104:107], v[166:169], v[174:177], v[104:107]
	v_mfma_f32_16x16x32_bf16 v[92:95], v[158:161], v[182:185], v[92:95]
	v_mfma_f32_16x16x32_bf16 v[88:91], v[166:169], v[182:185], v[88:91]
	v_mfma_f32_16x16x32_bf16 v[76:79], v[158:161], v[212:215], v[76:79]
	v_mfma_f32_16x16x32_bf16 v[72:75], v[166:169], v[212:215], v[72:75]
	v_mfma_f32_16x16x32_bf16 v[68:71], v[158:161], v[232:235], v[68:71]
	v_mfma_f32_16x16x32_bf16 v[64:67], v[166:169], v[232:235], v[64:67]
	v_mfma_f32_16x16x32_bf16 v[108:111], v[162:165], v[178:181], v[108:111]
	v_mfma_f32_16x16x32_bf16 v[104:107], v[170:173], v[178:181], v[104:107]
	v_mfma_f32_16x16x32_bf16 v[92:95], v[162:165], v[186:189], v[92:95]
	v_mfma_f32_16x16x32_bf16 v[88:91], v[170:173], v[186:189], v[88:91]
	s_barrier
	v_mfma_f32_16x16x32_bf16 v[76:79], v[162:165], v[216:219], v[76:79]
	v_mfma_f32_16x16x32_bf16 v[72:75], v[170:173], v[216:219], v[72:75]
	v_mfma_f32_16x16x32_bf16 v[68:71], v[162:165], v[236:239], v[68:71]
	v_mfma_f32_16x16x32_bf16 v[64:67], v[170:173], v[236:239], v[64:67]
	s_setprio 0
	s_add_i32 s71, s71, s38
	v_lshl_add_u64 v[190:191], s[28:29], 0, v[192:193]
	s_mov_b32 m0, s71
	ds_read_b128 v[174:177], v141 offset:16384
	ds_read_b128 v[178:181], v141 offset:17408
	ds_read_b128 v[182:185], v141 offset:18432
	ds_read_b128 v[186:189], v141 offset:19456
	ds_read_b128 v[212:215], v141 offset:20480
	ds_read_b128 v[216:219], v141 offset:21504
	ds_read_b128 v[232:235], v141 offset:22528
	ds_read_b128 v[236:239], v141 offset:23552
	global_load_lds_dwordx4 v[190:191], off
	s_add_i32 m0, s71, 0x2000
	s_add_u32 s72, s28, 0x40000
	v_lshl_add_u64 v[194:195], s[28:29], 0, v[132:133]
	s_addc_u32 s73, s29, 0
	s_add_i32 s71, s74, s38
	global_load_lds_dwordx4 v[194:195], off
	v_lshl_add_u64 v[196:197], s[72:73], 0, v[192:193]
	s_mov_b32 m0, s71
	v_lshl_add_u64 v[202:203], s[44:45], 0, v[130:131]
	global_load_lds_dwordx4 v[196:197], off
	v_lshl_add_u64 v[196:197], s[72:73], 0, v[132:133]
	s_add_i32 m0, s71, 0x2000
	s_nop 0
	global_load_lds_dwordx4 v[196:197], off
	v_lshl_add_u64 v[196:197], s[44:45], 0, v[128:129]
	s_mov_b32 m0, s15
	s_nop 0
	global_load_lds_dwordx4 v[196:197], off
	s_mov_b32 m0, s40
	s_nop 0
	global_load_lds_dwordx4 v[202:203], off
	s_waitcnt vmcnt(8)
	s_waitcnt lgkmcnt(0)
	s_barrier
; #define PG8_STAGE(bufoff, gbase, voff) do { _Pragma("unroll") for (int _i = 0; _i < 2; ++_i) \
;         __builtin_amdgcn_global_load_lds((const unsigned*)((const char*)(gbase) + (voff)[_i]), (PG8_LAS unsigned*)(lds + (bufoff) + ldsw + _i * 8192), 16, 0, 0); } while (0)
; #define PG8_LDA(dst, b, h) do { _Pragma("unroll") for (int m = 0; m < 4; ++m) _Pragma("unroll") for (int k = 0; k < 2; ++k) dst[m][k] = *(const PG8_LAS bf16x8*)(lds + PG8_SA(b, h) + aoff + m * 2048 + k * 1024); } while (0)
; #define PG8_LDB(dst, b, h) do { _Pragma("unroll") for (int n = 0; n < 2; ++n) _Pragma("unroll") for (int k = 0; k < 2; ++k) dst[n][k] = *(const PG8_LAS bf16x8*)(lds + PG8_SB(b, h) + boff + n * 2048 + k * 1024); } while (0)
; #define PG8_MMA(ai, bj, At, Bt) do { __builtin_amdgcn_s_setprio(1); _Pragma("unroll") for (int m = 0; m < 4; ++m) _Pragma("unroll") for (int n = 0; n < 2; ++n) _Pragma("unroll") for (int k = 0; k < 2; ++k) \
;         acc[ai][bj][m][n] = __builtin_amdgcn_mfma_f32_16x16x32_bf16(Bt[n][k], At[m][k], acc[ai][bj][m][n], 0, 0, 0); __builtin_amdgcn_s_setprio(0); } while (0)
; #define PG8_WAIT_V(n) asm volatile("s_waitcnt vmcnt(" #n ")" ::: "memory")
; #define PG8_WAIT_L(n) asm volatile("s_waitcnt lgkmcnt(" #n ")" ::: "memory")
; #define PG8_BAR __builtin_amdgcn_s_barrier()
; #define PG8_SCHED __builtin_amdgcn_sched_barrier(0)
; template <class Epi, class Sched, bool ALIGN_EPI = false, bool SP2 = false>
; __device__ __forceinline__ void gemm_phase(PG8_LAS unsigned char* lds, const Gemm g, const Sched& S, const Epi& E, const int tid) {
;     ...
;             PG8_WAIT_V(8); PG8_WAIT_L(0); PG8_BAR; PG8_MMA(1, 0, At, B0); PG8_MMA(1, 1, At, B1); PG8_BAR; PG8_SCHED;
;             PG8_LDB(B0, 1, 0); PG8_LDB(B1, 1, 1); PG8_SCHED; PG8_LDA(At, 1, 0); PG8_STAGE(PG8_SA(0, 1), a2 + hstep, voffA);
;             PG8_WAIT_V(8); PG8_WAIT_L(0); PG8_BAR; PG8_MMA(0, 0, At, B0); PG8_MMA(0, 1, At, B1); PG8_BAR; PG8_SCHED;
;             PG8_LDA(At, 1, 1); PG8_STAGE(PG8_SB(1, 0), b3, voffB); PG8_STAGE(PG8_SB(1, 1), b3 + hstep, voffB); PG8_STAGE(PG8_SA(1, 0), a3, voffA);
	s_setprio 1
	s_waitcnt lgkmcnt(0)
	v_mfma_f32_16x16x32_bf16 v[60:63], v[142:145], v[174:177], v[60:63]
	v_mfma_f32_16x16x32_bf16 v[56:59], v[150:153], v[174:177], v[56:59]
	v_mfma_f32_16x16x32_bf16 v[52:55], v[142:145], v[182:185], v[52:55]
	v_mfma_f32_16x16x32_bf16 v[48:51], v[150:153], v[182:185], v[48:51]
	v_mfma_f32_16x16x32_bf16 v[36:39], v[142:145], v[212:215], v[36:39]
	v_mfma_f32_16x16x32_bf16 v[32:35], v[150:153], v[212:215], v[32:35]
	v_mfma_f32_16x16x32_bf16 v[20:23], v[142:145], v[232:235], v[20:23]
	v_mfma_f32_16x16x32_bf16 v[16:19], v[150:153], v[232:235], v[16:19]
	v_mfma_f32_16x16x32_bf16 v[60:63], v[146:149], v[178:181], v[60:63]
	v_mfma_f32_16x16x32_bf16 v[56:59], v[154:157], v[178:181], v[56:59]
	v_mfma_f32_16x16x32_bf16 v[52:55], v[146:149], v[186:189], v[52:55]
	v_mfma_f32_16x16x32_bf16 v[48:51], v[154:157], v[186:189], v[48:51]
	v_mfma_f32_16x16x32_bf16 v[36:39], v[146:149], v[216:219], v[36:39]
	v_mfma_f32_16x16x32_bf16 v[32:35], v[154:157], v[216:219], v[32:35]
	v_mfma_f32_16x16x32_bf16 v[20:23], v[146:149], v[236:239], v[20:23]
	v_mfma_f32_16x16x32_bf16 v[16:19], v[154:157], v[236:239], v[16:19]
	s_setprio 0
	s_setprio 1
	v_mfma_f32_16x16x32_bf16 v[44:47], v[158:161], v[174:177], v[44:47]
	v_mfma_f32_16x16x32_bf16 v[40:43], v[166:169], v[174:177], v[40:43]
	v_mfma_f32_16x16x32_bf16 v[28:31], v[158:161], v[182:185], v[28:31]
	v_mfma_f32_16x16x32_bf16 v[24:27], v[166:169], v[182:185], v[24:27]
	v_mfma_f32_16x16x32_bf16 v[12:15], v[158:161], v[212:215], v[12:15]
	v_mfma_f32_16x16x32_bf16 v[8:11], v[166:169], v[212:215], v[8:11]
	v_mfma_f32_16x16x32_bf16 v[4:7], v[158:161], v[232:235], v[4:7]
	v_mfma_f32_16x16x32_bf16 v[0:3], v[166:169], v[232:235], v[0:3]
	v_mfma_f32_16x16x32_bf16 v[44:47], v[162:165], v[178:181], v[44:47]
	v_mfma_f32_16x16x32_bf16 v[40:43], v[170:173], v[178:181], v[40:43]
	v_mfma_f32_16x16x32_bf16 v[28:31], v[162:165], v[186:189], v[28:31]
	v_mfma_f32_16x16x32_bf16 v[24:27], v[170:173], v[186:189], v[24:27]
	s_barrier
	v_mfma_f32_16x16x32_bf16 v[12:15], v[162:165], v[216:219], v[12:15]
	v_mfma_f32_16x16x32_bf16 v[8:11], v[170:173], v[216:219], v[8:11]
	v_mfma_f32_16x16x32_bf16 v[4:7], v[162:165], v[236:239], v[4:7]
	v_mfma_f32_16x16x32_bf16 v[0:3], v[170:173], v[236:239], v[0:3]
	s_setprio 0
	s_add_i32 s71, 0, 0x18000
	s_add_i32 s72, 0, 0x1c000
	v_add_u32_e32 v154, s71, v140
	v_add_u32_e32 v170, s72, v140
	ds_read_b128 v[142:145], v154
	ds_read_b128 v[146:149], v154 offset:1024
	ds_read_b128 v[150:153], v154 offset:2048
	ds_read_b128 v[154:157], v154 offset:3072
	ds_read_b128 v[158:161], v170
	ds_read_b128 v[162:165], v170 offset:1024
	ds_read_b128 v[166:169], v170 offset:2048
	ds_read_b128 v[170:173], v170 offset:3072
	s_add_u32 s44, s44, 0x40000
	s_addc_u32 s45, s45, 0
	s_mov_b32 m0, s41
	v_lshl_add_u64 v[204:205], s[44:45], 0, v[128:129]
	ds_read_b128 v[174:177], v141 offset:32768
	ds_read_b128 v[178:181], v141 offset:33792
	ds_read_b128 v[182:185], v141 offset:34816
	ds_read_b128 v[186:189], v141 offset:35840
	ds_read_b128 v[212:215], v141 offset:36864
	ds_read_b128 v[216:219], v141 offset:37888
	ds_read_b128 v[232:235], v141 offset:38912
	ds_read_b128 v[236:239], v141 offset:39936
	global_load_lds_dwordx4 v[204:205], off
	v_lshl_add_u64 v[204:205], s[44:45], 0, v[130:131]
	s_mov_b32 m0, s46
	s_nop 0
	global_load_lds_dwordx4 v[204:205], off
	s_waitcnt vmcnt(8)
	s_waitcnt lgkmcnt(0)
	s_barrier
	s_setprio 1
	s_waitcnt lgkmcnt(0)
	v_mfma_f32_16x16x32_bf16 v[124:127], v[142:145], v[174:177], v[124:127]
	v_mfma_f32_16x16x32_bf16 v[120:123], v[150:153], v[174:177], v[120:123]
	v_mfma_f32_16x16x32_bf16 v[116:119], v[142:145], v[182:185], v[116:119]
	v_mfma_f32_16x16x32_bf16 v[112:115], v[150:153], v[182:185], v[112:115]
	v_mfma_f32_16x16x32_bf16 v[100:103], v[142:145], v[212:215], v[100:103]
	v_mfma_f32_16x16x32_bf16 v[96:99], v[150:153], v[212:215], v[96:99]
	v_mfma_f32_16x16x32_bf16 v[84:87], v[142:145], v[232:235], v[84:87]
	v_mfma_f32_16x16x32_bf16 v[80:83], v[150:153], v[232:235], v[80:83]
	v_mfma_f32_16x16x32_bf16 v[124:127], v[146:149], v[178:181], v[124:127]
	v_mfma_f32_16x16x32_bf16 v[120:123], v[154:157], v[178:181], v[120:123]
	v_mfma_f32_16x16x32_bf16 v[116:119], v[146:149], v[186:189], v[116:119]
	v_mfma_f32_16x16x32_bf16 v[112:115], v[154:157], v[186:189], v[112:115]
	v_mfma_f32_16x16x32_bf16 v[100:103], v[146:149], v[216:219], v[100:103]
	v_mfma_f32_16x16x32_bf16 v[96:99], v[154:157], v[216:219], v[96:99]
	v_mfma_f32_16x16x32_bf16 v[84:87], v[146:149], v[236:239], v[84:87]
	v_mfma_f32_16x16x32_bf16 v[80:83], v[154:157], v[236:239], v[80:83]
	s_setprio 0
	s_setprio 1
	v_mfma_f32_16x16x32_bf16 v[108:111], v[158:161], v[174:177], v[108:111]
	v_mfma_f32_16x16x32_bf16 v[104:107], v[166:169], v[174:177], v[104:107]
	v_mfma_f32_16x16x32_bf16 v[92:95], v[158:161], v[182:185], v[92:95]
	v_mfma_f32_16x16x32_bf16 v[88:91], v[166:169], v[182:185], v[88:91]
	v_mfma_f32_16x16x32_bf16 v[76:79], v[158:161], v[212:215], v[76:79]
	v_mfma_f32_16x16x32_bf16 v[72:75], v[166:169], v[212:215], v[72:75]
	v_mfma_f32_16x16x32_bf16 v[68:71], v[158:161], v[232:235], v[68:71]
	v_mfma_f32_16x16x32_bf16 v[64:67], v[166:169], v[232:235], v[64:67]
	v_mfma_f32_16x16x32_bf16 v[108:111], v[162:165], v[178:181], v[108:111]
	v_mfma_f32_16x16x32_bf16 v[104:107], v[170:173], v[178:181], v[104:107]
	v_mfma_f32_16x16x32_bf16 v[92:95], v[162:165], v[186:189], v[92:95]
	v_mfma_f32_16x16x32_bf16 v[88:91], v[170:173], v[186:189], v[88:91]
	s_barrier
; #define PG8_STAGE(bufoff, gbase, voff) do { _Pragma("unroll") for (int _i = 0; _i < 2; ++_i) \
;         __builtin_amdgcn_global_load_lds((const unsigned*)((const char*)(gbase) + (voff)[_i]), (PG8_LAS unsigned*)(lds + (bufoff) + ldsw + _i * 8192), 16, 0, 0); } while (0)
; #define PG8_LDA(dst, b, h) do { _Pragma("unroll") for (int m = 0; m < 4; ++m) _Pragma("unroll") for (int k = 0; k < 2; ++k) dst[m][k] = *(const PG8_LAS bf16x8*)(lds + PG8_SA(b, h) + aoff + m * 2048 + k * 1024); } while (0)
; #define PG8_MMA(ai, bj, At, Bt) do { __builtin_amdgcn_s_setprio(1); _Pragma("unroll") for (int m = 0; m < 4; ++m) _Pragma("unroll") for (int n = 0; n < 2; ++n) _Pragma("unroll") for (int k = 0; k < 2; ++k) \
;         acc[ai][bj][m][n] = __builtin_amdgcn_mfma_f32_16x16x32_bf16(Bt[n][k], At[m][k], acc[ai][bj][m][n], 0, 0, 0); __builtin_amdgcn_s_setprio(0); } while (0)
; #define PG8_WAIT_V(n) asm volatile("s_waitcnt vmcnt(" #n ")" ::: "memory")
; #define PG8_WAIT_L(n) asm volatile("s_waitcnt lgkmcnt(" #n ")" ::: "memory")
; #define PG8_BAR __builtin_amdgcn_s_barrier()
; #define PG8_SCHED __builtin_amdgcn_sched_barrier(0)
; template <class Epi, class Sched, bool ALIGN_EPI = false, bool SP2 = false>
; __device__ __forceinline__ void gemm_phase(PG8_LAS unsigned char* lds, const Gemm g, const Sched& S, const Epi& E, const int tid) {
;     ...
;             PG8_WAIT_V(8); PG8_WAIT_L(0); PG8_BAR; PG8_MMA(0, 0, At, B0); PG8_MMA(0, 1, At, B1); PG8_BAR; PG8_SCHED;
;             PG8_LDA(At, 1, 1); PG8_STAGE(PG8_SB(1, 0), b3, voffB); PG8_STAGE(PG8_SB(1, 1), b3 + hstep, voffB); PG8_STAGE(PG8_SA(1, 0), a3, voffA);
;             PG8_WAIT_V(8); PG8_WAIT_L(0); PG8_BAR; PG8_MMA(1, 0, At, B0); PG8_MMA(1, 1, At, B1); PG8_BAR; PG8_SCHED;
;     ...
;         }
;         if constexpr (ALIGN_EPI) { if (wr == 0) PG8_BAR; }
	v_mfma_f32_16x16x32_bf16 v[76:79], v[162:165], v[216:219], v[76:79]
	v_mfma_f32_16x16x32_bf16 v[72:75], v[170:173], v[216:219], v[72:75]
	v_mfma_f32_16x16x32_bf16 v[68:71], v[162:165], v[236:239], v[68:71]
	v_mfma_f32_16x16x32_bf16 v[64:67], v[170:173], v[236:239], v[64:67]
	s_setprio 0
	s_add_i32 s44, s71, s38
	v_lshl_add_u64 v[190:191], v[190:191], 0, s[36:37]
	s_mov_b32 m0, s44
	ds_read_b128 v[174:177], v141 offset:49152
	ds_read_b128 v[178:181], v141 offset:50176
	ds_read_b128 v[182:185], v141 offset:51200
	ds_read_b128 v[186:189], v141 offset:52224
	ds_read_b128 v[212:215], v141 offset:53248
	ds_read_b128 v[216:219], v141 offset:54272
	ds_read_b128 v[232:235], v141 offset:55296
	ds_read_b128 v[236:239], v141 offset:56320
	global_load_lds_dwordx4 v[190:191], off
	s_add_i32 m0, s44, 0x2000
	s_add_u32 s28, s28, 0x40080
	v_lshl_add_u64 v[190:191], v[194:195], 0, s[36:37]
	s_addc_u32 s29, s29, 0
	s_add_i32 s44, s72, s38
	global_load_lds_dwordx4 v[190:191], off
	v_lshl_add_u64 v[190:191], s[28:29], 0, v[192:193]
	s_mov_b32 m0, s44
	s_nop 0
	global_load_lds_dwordx4 v[190:191], off
	v_lshl_add_u64 v[190:191], s[28:29], 0, v[132:133]
	s_add_i32 m0, s44, 0x2000
	s_nop 0
	global_load_lds_dwordx4 v[190:191], off
	v_lshl_add_u64 v[190:191], v[196:197], 0, s[36:37]
	s_mov_b32 m0, s47
	s_nop 0
	global_load_lds_dwordx4 v[190:191], off
	v_lshl_add_u64 v[190:191], v[202:203], 0, s[36:37]
	s_mov_b32 m0, s52
	s_nop 0
	global_load_lds_dwordx4 v[190:191], off
	s_waitcnt vmcnt(8)
	s_waitcnt lgkmcnt(0)
	s_barrier
	s_setprio 1
	s_waitcnt lgkmcnt(0)
	v_mfma_f32_16x16x32_bf16 v[60:63], v[142:145], v[174:177], v[60:63]
	v_mfma_f32_16x16x32_bf16 v[56:59], v[150:153], v[174:177], v[56:59]
	v_mfma_f32_16x16x32_bf16 v[52:55], v[142:145], v[182:185], v[52:55]
	v_mfma_f32_16x16x32_bf16 v[48:51], v[150:153], v[182:185], v[48:51]
	v_mfma_f32_16x16x32_bf16 v[36:39], v[142:145], v[212:215], v[36:39]
	v_mfma_f32_16x16x32_bf16 v[32:35], v[150:153], v[212:215], v[32:35]
	v_mfma_f32_16x16x32_bf16 v[20:23], v[142:145], v[232:235], v[20:23]
	v_mfma_f32_16x16x32_bf16 v[16:19], v[150:153], v[232:235], v[16:19]
	v_mfma_f32_16x16x32_bf16 v[60:63], v[146:149], v[178:181], v[60:63]
	v_mfma_f32_16x16x32_bf16 v[56:59], v[154:157], v[178:181], v[56:59]
	v_mfma_f32_16x16x32_bf16 v[52:55], v[146:149], v[186:189], v[52:55]
	v_mfma_f32_16x16x32_bf16 v[48:51], v[154:157], v[186:189], v[48:51]
	v_mfma_f32_16x16x32_bf16 v[36:39], v[146:149], v[216:219], v[36:39]
	v_mfma_f32_16x16x32_bf16 v[32:35], v[154:157], v[216:219], v[32:35]
	v_mfma_f32_16x16x32_bf16 v[20:23], v[146:149], v[236:239], v[20:23]
	v_mfma_f32_16x16x32_bf16 v[16:19], v[154:157], v[236:239], v[16:19]
	s_setprio 0
	s_setprio 1
	v_mfma_f32_16x16x32_bf16 v[44:47], v[158:161], v[174:177], v[44:47]
	v_mfma_f32_16x16x32_bf16 v[40:43], v[166:169], v[174:177], v[40:43]
	v_mfma_f32_16x16x32_bf16 v[28:31], v[158:161], v[182:185], v[28:31]
	v_mfma_f32_16x16x32_bf16 v[24:27], v[166:169], v[182:185], v[24:27]
	v_mfma_f32_16x16x32_bf16 v[12:15], v[158:161], v[212:215], v[12:15]
	v_mfma_f32_16x16x32_bf16 v[8:11], v[166:169], v[212:215], v[8:11]
	v_mfma_f32_16x16x32_bf16 v[4:7], v[158:161], v[232:235], v[4:7]
	v_mfma_f32_16x16x32_bf16 v[0:3], v[166:169], v[232:235], v[0:3]
	v_mfma_f32_16x16x32_bf16 v[44:47], v[162:165], v[178:181], v[44:47]
	v_mfma_f32_16x16x32_bf16 v[40:43], v[170:173], v[178:181], v[40:43]
	v_mfma_f32_16x16x32_bf16 v[28:31], v[162:165], v[186:189], v[28:31]
	v_mfma_f32_16x16x32_bf16 v[24:27], v[170:173], v[186:189], v[24:27]
	s_barrier
	v_mfma_f32_16x16x32_bf16 v[12:15], v[162:165], v[216:219], v[12:15]
	v_mfma_f32_16x16x32_bf16 v[8:11], v[170:173], v[216:219], v[8:11]
	v_mfma_f32_16x16x32_bf16 v[4:7], v[162:165], v[236:239], v[4:7]
	v_mfma_f32_16x16x32_bf16 v[0:3], v[170:173], v[236:239], v[0:3]
	s_setprio 0
	s_add_i32 s70, s70, 2
	s_add_u32 s22, s22, 0x100
	s_addc_u32 s23, s23, 0
	s_add_u32 s60, s60, 0x100
	s_addc_u32 s62, s62, 0
	s_cmp_gt_u32 s70, 13
	s_cbranch_scc0 .LBB0_183
	s_nop 7
	s_and_b64 vcc, exec, s[10:11]
	s_cbranch_vccz .LBB0_186
	s_barrier

; #define PG8_STAGE(bufoff, gbase, voff) do { _Pragma("unroll") for (int _i = 0; _i < 2; ++_i) \
;         __builtin_amdgcn_global_load_lds((const unsigned*)((const char*)(gbase) + (voff)[_i]), (PG8_LAS unsigned*)(lds + (bufoff) + ldsw + _i * 8192), 16, 0, 0); } while (0)
; #define PG8_LDA(dst, b, h) do { _Pragma("unroll") for (int m = 0; m < 4; ++m) _Pragma("unroll") for (int k = 0; k < 2; ++k) dst[m][k] = *(const PG8_LAS bf16x8*)(lds + PG8_SA(b, h) + aoff + m * 2048 + k * 1024); } while (0)
; #define PG8_LDB(dst, b, h) do { _Pragma("unroll") for (int n = 0; n < 2; ++n) _Pragma("unroll") for (int k = 0; k < 2; ++k) dst[n][k] = *(const PG8_LAS bf16x8*)(lds + PG8_SB(b, h) + boff + n * 2048 + k * 1024); } while (0)
; #define PG8_MMA(ai, bj, At, Bt) do { __builtin_amdgcn_s_setprio(1); _Pragma("unroll") for (int m = 0; m < 4; ++m) _Pragma("unroll") for (int n = 0; n < 2; ++n) _Pragma("unroll") for (int k = 0; k < 2; ++k) \
;         acc[ai][bj][m][n] = __builtin_amdgcn_mfma_f32_16x16x32_bf16(Bt[n][k], At[m][k], acc[ai][bj][m][n], 0, 0, 0); __builtin_amdgcn_s_setprio(0); } while (0)
; #define PG8_WAIT_V(n) asm volatile("s_waitcnt vmcnt(" #n ")" ::: "memory")
; #define PG8_WAIT_L(n) asm volatile("s_waitcnt lgkmcnt(" #n ")" ::: "memory")
; template <class Epi, class Sched, bool ALIGN_EPI = false, bool SP2 = false>
; __device__ __forceinline__ void gemm_phase(PG8_LAS unsigned char* lds, const Gemm g, const Sched& S, const Epi& E, const int tid) {
;     ...
;             const bool last = (t == nt - 2);
;             const char* a1 = cA + (size_t)(t + 1) * kstep;
;             const char* a2 = last ? nA : cA + (size_t)(t + 2) * kstep; const char* b2 = last ? nB : cB + (size_t)(t + 2) * kstep;
;             const char* a3 = a2 + kstep; const char* b3 = b2 + kstep;
;             if (last && has_next) S.a_ready(nxt);
;             if constexpr (SP2) {
;             PG8_LDB(B0, 0, 0); PG8_LDB(B1, 0, 1); PG8_SCHED; PG8_LDA(At, 0, 0); PG8_STAGE(PG8_SA(1, 1), a1 + hstep, voffA);
;             PG8_WAIT_V(8); PG8_WAIT_L(0); PG8_BAR; PG8_MMA(0, 0, At, B0); PG8_MMA(0, 1, At, B1); PG8_BAR; PG8_SCHED;
;             PG8_LDA(At, 0, 1); PG8_STAGE(PG8_SB(0, 0), b2, voffB); PG8_STAGE(PG8_SB(0, 1), b2 + hstep, voffB); PG8_STAGE(PG8_SA(0, 0), a2, voffA);
;             PG8_WAIT_V(8); PG8_WAIT_L(0); PG8_BAR; PG8_MMA(1, 0, At, B0); PG8_MMA(1, 1, At, B1); PG8_BAR; PG8_SCHED;
.LBB0_239:
	s_add_u32 s58, s10, s44
	s_addc_u32 s59, s11, s45
	s_add_u32 s58, s58, 0x100
	s_addc_u32 s59, s59, 0
	s_add_u32 s73, s19, s44
	s_addc_u32 s74, s62, s45
	s_waitcnt lgkmcnt(0)
	s_add_i32 s75, 0, 0x10000
	s_cmpk_eq_i32 s44, 0x700
	s_cselect_b32 s79, s15, s59
	s_cselect_b32 s78, s70, s58
	s_cselect_b32 s59, s13, s74
	s_cselect_b32 s58, s71, s73
	s_add_i32 s73, 0, 0x14000
	v_add_u32_e32 v156, s75, v142
	v_add_u32_e32 v172, s73, v142
	ds_read_b128 v[144:147], v156
	ds_read_b128 v[148:151], v156 offset:1024
	ds_read_b128 v[152:155], v156 offset:2048
	ds_read_b128 v[156:159], v156 offset:3072
	ds_read_b128 v[160:163], v172
	ds_read_b128 v[164:167], v172 offset:1024
	ds_read_b128 v[168:171], v172 offset:2048
	ds_read_b128 v[172:175], v172 offset:3072
	v_lshl_add_u64 v[194:195], v[138:139], 0, s[44:45]
	s_add_i32 m0, s46, 0xc000
	ds_read_b128 v[176:179], v143
	ds_read_b128 v[180:183], v143 offset:1024
	ds_read_b128 v[184:187], v143 offset:2048
	ds_read_b128 v[188:191], v143 offset:3072
	ds_read_b128 v[212:215], v143 offset:4096
	ds_read_b128 v[216:219], v143 offset:5120
	ds_read_b128 v[234:237], v143 offset:6144
	ds_read_b128 v[238:241], v143 offset:7168
	global_load_lds_dwordx4 v[194:195], off
	v_lshl_add_u64 v[194:195], v[140:141], 0, s[44:45]
	s_add_i32 m0, s46, 0xe000
	s_nop 0
	global_load_lds_dwordx4 v[194:195], off
	s_waitcnt vmcnt(8)
	s_waitcnt lgkmcnt(0)
	s_barrier
	s_setprio 1
	s_waitcnt lgkmcnt(0)
	v_mfma_f32_16x16x32_bf16 v[76:79], v[144:147], v[176:179], v[76:79]
	v_mfma_f32_16x16x32_bf16 v[72:75], v[152:155], v[176:179], v[72:75]
	v_mfma_f32_16x16x32_bf16 v[100:103], v[144:147], v[184:187], v[100:103]
	v_mfma_f32_16x16x32_bf16 v[96:99], v[152:155], v[184:187], v[96:99]
	v_mfma_f32_16x16x32_bf16 v[124:127], v[144:147], v[212:215], v[124:127]
	v_mfma_f32_16x16x32_bf16 v[120:123], v[152:155], v[212:215], v[120:123]
	v_mfma_f32_16x16x32_bf16 v[92:95], v[144:147], v[234:237], v[92:95]
	v_mfma_f32_16x16x32_bf16 v[84:87], v[152:155], v[234:237], v[84:87]
	v_mfma_f32_16x16x32_bf16 v[76:79], v[148:151], v[180:183], v[76:79]
	v_mfma_f32_16x16x32_bf16 v[72:75], v[156:159], v[180:183], v[72:75]
	v_mfma_f32_16x16x32_bf16 v[100:103], v[148:151], v[188:191], v[100:103]
	v_mfma_f32_16x16x32_bf16 v[96:99], v[156:159], v[188:191], v[96:99]
	v_mfma_f32_16x16x32_bf16 v[124:127], v[148:151], v[216:219], v[124:127]
	v_mfma_f32_16x16x32_bf16 v[120:123], v[156:159], v[216:219], v[120:123]
	v_mfma_f32_16x16x32_bf16 v[92:95], v[148:151], v[238:241], v[92:95]
	v_mfma_f32_16x16x32_bf16 v[84:87], v[156:159], v[238:241], v[84:87]
	s_setprio 0
	s_setprio 1
	v_mfma_f32_16x16x32_bf16 v[80:83], v[160:163], v[176:179], v[80:83]
	v_mfma_f32_16x16x32_bf16 v[88:91], v[168:171], v[176:179], v[88:91]
	v_mfma_f32_16x16x32_bf16 v[108:111], v[160:163], v[184:187], v[108:111]
	v_mfma_f32_16x16x32_bf16 v[116:119], v[168:171], v[184:187], v[116:119]
	v_mfma_f32_16x16x32_bf16 v[112:115], v[160:163], v[212:215], v[112:115]
	v_mfma_f32_16x16x32_bf16 v[104:107], v[168:171], v[212:215], v[104:107]
	v_mfma_f32_16x16x32_bf16 v[68:71], v[160:163], v[234:237], v[68:71]
	v_mfma_f32_16x16x32_bf16 v[64:67], v[168:171], v[234:237], v[64:67]
	v_mfma_f32_16x16x32_bf16 v[80:83], v[164:167], v[180:183], v[80:83]
	v_mfma_f32_16x16x32_bf16 v[88:91], v[172:175], v[180:183], v[88:91]
	v_mfma_f32_16x16x32_bf16 v[108:111], v[164:167], v[188:191], v[108:111]
	v_mfma_f32_16x16x32_bf16 v[116:119], v[172:175], v[188:191], v[116:119]
	s_barrier
	v_mfma_f32_16x16x32_bf16 v[112:115], v[164:167], v[216:219], v[112:115]
	v_mfma_f32_16x16x32_bf16 v[104:107], v[172:175], v[216:219], v[104:107]
	v_mfma_f32_16x16x32_bf16 v[68:71], v[164:167], v[238:241], v[68:71]
	v_mfma_f32_16x16x32_bf16 v[64:67], v[172:175], v[238:241], v[64:67]
	s_setprio 0
	s_add_i32 s74, s75, s41
	v_lshl_add_u64 v[194:195], s[58:59], 0, v[192:193]
	s_mov_b32 m0, s74
	ds_read_b128 v[176:179], v143 offset:16384
	ds_read_b128 v[180:183], v143 offset:17408
	ds_read_b128 v[184:187], v143 offset:18432
	ds_read_b128 v[188:191], v143 offset:19456
	ds_read_b128 v[212:215], v143 offset:20480
	ds_read_b128 v[216:219], v143 offset:21504
	ds_read_b128 v[234:237], v143 offset:22528
	ds_read_b128 v[238:241], v143 offset:23552
	global_load_lds_dwordx4 v[194:195], off
	s_add_i32 m0, s74, 0x2000
	s_add_u32 s74, s58, 0x40000
	v_lshl_add_u64 v[196:197], s[58:59], 0, v[132:133]
	s_addc_u32 s75, s59, 0
	s_add_i32 s73, s73, s41
	global_load_lds_dwordx4 v[196:197], off
	v_lshl_add_u64 v[202:203], s[74:75], 0, v[192:193]
	s_mov_b32 m0, s73
	v_lshl_add_u64 v[204:205], s[78:79], 0, v[130:131]
	global_load_lds_dwordx4 v[202:203], off
	v_lshl_add_u64 v[202:203], s[74:75], 0, v[132:133]
	s_add_i32 m0, s73, 0x2000
	s_nop 0
	global_load_lds_dwordx4 v[202:203], off
	v_lshl_add_u64 v[202:203], s[78:79], 0, v[128:129]
	s_mov_b32 m0, s46
	s_nop 0
	global_load_lds_dwordx4 v[202:203], off
	s_mov_b32 m0, s47
	s_nop 0
	global_load_lds_dwordx4 v[204:205], off
	s_waitcnt vmcnt(8)
	s_waitcnt lgkmcnt(0)
	s_barrier
; #define PG8_STAGE(bufoff, gbase, voff) do { _Pragma("unroll") for (int _i = 0; _i < 2; ++_i) \
;         __builtin_amdgcn_global_load_lds((const unsigned*)((const char*)(gbase) + (voff)[_i]), (PG8_LAS unsigned*)(lds + (bufoff) + ldsw + _i * 8192), 16, 0, 0); } while (0)
; #define PG8_LDA(dst, b, h) do { _Pragma("unroll") for (int m = 0; m < 4; ++m) _Pragma("unroll") for (int k = 0; k < 2; ++k) dst[m][k] = *(const PG8_LAS bf16x8*)(lds + PG8_SA(b, h) + aoff + m * 2048 + k * 1024); } while (0)
; #define PG8_LDB(dst, b, h) do { _Pragma("unroll") for (int n = 0; n < 2; ++n) _Pragma("unroll") for (int k = 0; k < 2; ++k) dst[n][k] = *(const PG8_LAS bf16x8*)(lds + PG8_SB(b, h) + boff + n * 2048 + k * 1024); } while (0)
; #define PG8_MMA(ai, bj, At, Bt) do { __builtin_amdgcn_s_setprio(1); _Pragma("unroll") for (int m = 0; m < 4; ++m) _Pragma("unroll") for (int n = 0; n < 2; ++n) _Pragma("unroll") for (int k = 0; k < 2; ++k) \
;         acc[ai][bj][m][n] = __builtin_amdgcn_mfma_f32_16x16x32_bf16(Bt[n][k], At[m][k], acc[ai][bj][m][n], 0, 0, 0); __builtin_amdgcn_s_setprio(0); } while (0)
; #define PG8_WAIT_V(n) asm volatile("s_waitcnt vmcnt(" #n ")" ::: "memory")
; #define PG8_WAIT_L(n) asm volatile("s_waitcnt lgkmcnt(" #n ")" ::: "memory")
; #define PG8_BAR __builtin_amdgcn_s_barrier()
; #define PG8_SCHED __builtin_amdgcn_sched_barrier(0)
; template <class Epi, class Sched, bool ALIGN_EPI = false, bool SP2 = false>
; __device__ __forceinline__ void gemm_phase(PG8_LAS unsigned char* lds, const Gemm g, const Sched& S, const Epi& E, const int tid) {
;     ...
;             PG8_WAIT_V(8); PG8_WAIT_L(0); PG8_BAR; PG8_MMA(1, 0, At, B0); PG8_MMA(1, 1, At, B1); PG8_BAR; PG8_SCHED;
;             PG8_LDB(B0, 1, 0); PG8_LDB(B1, 1, 1); PG8_SCHED; PG8_LDA(At, 1, 0); PG8_STAGE(PG8_SA(0, 1), a2 + hstep, voffA);
;             PG8_WAIT_V(8); PG8_WAIT_L(0); PG8_BAR; PG8_MMA(0, 0, At, B0); PG8_MMA(0, 1, At, B1); PG8_BAR; PG8_SCHED;
;             PG8_LDA(At, 1, 1); PG8_STAGE(PG8_SB(1, 0), b3, voffB); PG8_STAGE(PG8_SB(1, 1), b3 + hstep, voffB); PG8_STAGE(PG8_SA(1, 0), a3, voffA);
	s_setprio 1
	s_waitcnt lgkmcnt(0)
	v_mfma_f32_16x16x32_bf16 v[60:63], v[144:147], v[176:179], v[60:63]
	v_mfma_f32_16x16x32_bf16 v[56:59], v[152:155], v[176:179], v[56:59]
	v_mfma_f32_16x16x32_bf16 v[44:47], v[144:147], v[184:187], v[44:47]
	v_mfma_f32_16x16x32_bf16 v[40:43], v[152:155], v[184:187], v[40:43]
	v_mfma_f32_16x16x32_bf16 v[28:31], v[144:147], v[212:215], v[28:31]
	v_mfma_f32_16x16x32_bf16 v[24:27], v[152:155], v[212:215], v[24:27]
	v_mfma_f32_16x16x32_bf16 v[12:15], v[144:147], v[234:237], v[12:15]
	v_mfma_f32_16x16x32_bf16 v[8:11], v[152:155], v[234:237], v[8:11]
	v_mfma_f32_16x16x32_bf16 v[60:63], v[148:151], v[180:183], v[60:63]
	v_mfma_f32_16x16x32_bf16 v[56:59], v[156:159], v[180:183], v[56:59]
	v_mfma_f32_16x16x32_bf16 v[44:47], v[148:151], v[188:191], v[44:47]
	v_mfma_f32_16x16x32_bf16 v[40:43], v[156:159], v[188:191], v[40:43]
	v_mfma_f32_16x16x32_bf16 v[28:31], v[148:151], v[216:219], v[28:31]
	v_mfma_f32_16x16x32_bf16 v[24:27], v[156:159], v[216:219], v[24:27]
	v_mfma_f32_16x16x32_bf16 v[12:15], v[148:151], v[238:241], v[12:15]
	v_mfma_f32_16x16x32_bf16 v[8:11], v[156:159], v[238:241], v[8:11]
	s_setprio 0
	s_setprio 1
	v_mfma_f32_16x16x32_bf16 v[52:55], v[160:163], v[176:179], v[52:55]
	v_mfma_f32_16x16x32_bf16 v[48:51], v[168:171], v[176:179], v[48:51]
	v_mfma_f32_16x16x32_bf16 v[36:39], v[160:163], v[184:187], v[36:39]
	v_mfma_f32_16x16x32_bf16 v[32:35], v[168:171], v[184:187], v[32:35]
	v_mfma_f32_16x16x32_bf16 v[20:23], v[160:163], v[212:215], v[20:23]
	v_mfma_f32_16x16x32_bf16 v[16:19], v[168:171], v[212:215], v[16:19]
	v_mfma_f32_16x16x32_bf16 v[4:7], v[160:163], v[234:237], v[4:7]
	v_mfma_f32_16x16x32_bf16 v[0:3], v[168:171], v[234:237], v[0:3]
	v_mfma_f32_16x16x32_bf16 v[52:55], v[164:167], v[180:183], v[52:55]
	v_mfma_f32_16x16x32_bf16 v[48:51], v[172:175], v[180:183], v[48:51]
	v_mfma_f32_16x16x32_bf16 v[36:39], v[164:167], v[188:191], v[36:39]
	v_mfma_f32_16x16x32_bf16 v[32:35], v[172:175], v[188:191], v[32:35]
	s_barrier
	v_mfma_f32_16x16x32_bf16 v[20:23], v[164:167], v[216:219], v[20:23]
	v_mfma_f32_16x16x32_bf16 v[16:19], v[172:175], v[216:219], v[16:19]
	v_mfma_f32_16x16x32_bf16 v[4:7], v[164:167], v[238:241], v[4:7]
	v_mfma_f32_16x16x32_bf16 v[0:3], v[172:175], v[238:241], v[0:3]
	s_setprio 0
	s_add_i32 s73, 0, 0x18000
	s_add_i32 s76, 0, 0x1c000
	v_add_u32_e32 v156, s73, v142
	v_add_u32_e32 v172, s76, v142
	ds_read_b128 v[144:147], v156
	ds_read_b128 v[148:151], v156 offset:1024
	ds_read_b128 v[152:155], v156 offset:2048
	ds_read_b128 v[156:159], v156 offset:3072
	ds_read_b128 v[160:163], v172
	ds_read_b128 v[164:167], v172 offset:1024
	ds_read_b128 v[168:171], v172 offset:2048
	ds_read_b128 v[172:175], v172 offset:3072
	s_add_u32 s74, s78, 0x40000
	s_addc_u32 s75, s79, 0
	s_mov_b32 m0, s52
	v_lshl_add_u64 v[206:207], s[74:75], 0, v[128:129]
	ds_read_b128 v[176:179], v143 offset:32768
	ds_read_b128 v[180:183], v143 offset:33792
	ds_read_b128 v[184:187], v143 offset:34816
	ds_read_b128 v[188:191], v143 offset:35840
	ds_read_b128 v[212:215], v143 offset:36864
	ds_read_b128 v[216:219], v143 offset:37888
	ds_read_b128 v[234:237], v143 offset:38912
	ds_read_b128 v[238:241], v143 offset:39936
	global_load_lds_dwordx4 v[206:207], off
	v_lshl_add_u64 v[206:207], s[74:75], 0, v[130:131]
	s_mov_b32 m0, s53
	s_nop 0
	global_load_lds_dwordx4 v[206:207], off
	s_waitcnt vmcnt(8)
	s_waitcnt lgkmcnt(0)
	s_barrier
	s_setprio 1
	s_waitcnt lgkmcnt(0)
	v_mfma_f32_16x16x32_bf16 v[76:79], v[144:147], v[176:179], v[76:79]
	v_mfma_f32_16x16x32_bf16 v[72:75], v[152:155], v[176:179], v[72:75]
	v_mfma_f32_16x16x32_bf16 v[100:103], v[144:147], v[184:187], v[100:103]
	v_mfma_f32_16x16x32_bf16 v[96:99], v[152:155], v[184:187], v[96:99]
	v_mfma_f32_16x16x32_bf16 v[124:127], v[144:147], v[212:215], v[124:127]
	v_mfma_f32_16x16x32_bf16 v[120:123], v[152:155], v[212:215], v[120:123]
	v_mfma_f32_16x16x32_bf16 v[92:95], v[144:147], v[234:237], v[92:95]
	v_mfma_f32_16x16x32_bf16 v[84:87], v[152:155], v[234:237], v[84:87]
	v_mfma_f32_16x16x32_bf16 v[76:79], v[148:151], v[180:183], v[76:79]
	v_mfma_f32_16x16x32_bf16 v[72:75], v[156:159], v[180:183], v[72:75]
	v_mfma_f32_16x16x32_bf16 v[100:103], v[148:151], v[188:191], v[100:103]
	v_mfma_f32_16x16x32_bf16 v[96:99], v[156:159], v[188:191], v[96:99]
	v_mfma_f32_16x16x32_bf16 v[124:127], v[148:151], v[216:219], v[124:127]
	v_mfma_f32_16x16x32_bf16 v[120:123], v[156:159], v[216:219], v[120:123]
	v_mfma_f32_16x16x32_bf16 v[92:95], v[148:151], v[238:241], v[92:95]
	v_mfma_f32_16x16x32_bf16 v[84:87], v[156:159], v[238:241], v[84:87]
	s_setprio 0
	s_setprio 1
	v_mfma_f32_16x16x32_bf16 v[80:83], v[160:163], v[176:179], v[80:83]
	v_mfma_f32_16x16x32_bf16 v[88:91], v[168:171], v[176:179], v[88:91]
	v_mfma_f32_16x16x32_bf16 v[108:111], v[160:163], v[184:187], v[108:111]
	v_mfma_f32_16x16x32_bf16 v[116:119], v[168:171], v[184:187], v[116:119]
	v_mfma_f32_16x16x32_bf16 v[112:115], v[160:163], v[212:215], v[112:115]
	v_mfma_f32_16x16x32_bf16 v[104:107], v[168:171], v[212:215], v[104:107]
	v_mfma_f32_16x16x32_bf16 v[68:71], v[160:163], v[234:237], v[68:71]
	v_mfma_f32_16x16x32_bf16 v[64:67], v[168:171], v[234:237], v[64:67]
	v_mfma_f32_16x16x32_bf16 v[80:83], v[164:167], v[180:183], v[80:83]
	v_mfma_f32_16x16x32_bf16 v[88:91], v[172:175], v[180:183], v[88:91]
	v_mfma_f32_16x16x32_bf16 v[108:111], v[164:167], v[188:191], v[108:111]
	v_mfma_f32_16x16x32_bf16 v[116:119], v[172:175], v[188:191], v[116:119]
	s_barrier
; #define PG8_STAGE(bufoff, gbase, voff) do { _Pragma("unroll") for (int _i = 0; _i < 2; ++_i) \
;         __builtin_amdgcn_global_load_lds((const unsigned*)((const char*)(gbase) + (voff)[_i]), (PG8_LAS unsigned*)(lds + (bufoff) + ldsw + _i * 8192), 16, 0, 0); } while (0)
; #define PG8_LDA(dst, b, h) do { _Pragma("unroll") for (int m = 0; m < 4; ++m) _Pragma("unroll") for (int k = 0; k < 2; ++k) dst[m][k] = *(const PG8_LAS bf16x8*)(lds + PG8_SA(b, h) + aoff + m * 2048 + k * 1024); } while (0)
; #define PG8_MMA(ai, bj, At, Bt) do { __builtin_amdgcn_s_setprio(1); _Pragma("unroll") for (int m = 0; m < 4; ++m) _Pragma("unroll") for (int n = 0; n < 2; ++n) _Pragma("unroll") for (int k = 0; k < 2; ++k) \
;         acc[ai][bj][m][n] = __builtin_amdgcn_mfma_f32_16x16x32_bf16(Bt[n][k], At[m][k], acc[ai][bj][m][n], 0, 0, 0); __builtin_amdgcn_s_setprio(0); } while (0)
; #define PG8_WAIT_V(n) asm volatile("s_waitcnt vmcnt(" #n ")" ::: "memory")
; #define PG8_WAIT_L(n) asm volatile("s_waitcnt lgkmcnt(" #n ")" ::: "memory")
; #define PG8_BAR __builtin_amdgcn_s_barrier()
; #define PG8_SCHED __builtin_amdgcn_sched_barrier(0)
; template <class Epi, class Sched, bool ALIGN_EPI = false, bool SP2 = false>
; __device__ __forceinline__ void gemm_phase(PG8_LAS unsigned char* lds, const Gemm g, const Sched& S, const Epi& E, const int tid) {
;     ...
;             PG8_WAIT_V(8); PG8_WAIT_L(0); PG8_BAR; PG8_MMA(0, 0, At, B0); PG8_MMA(0, 1, At, B1); PG8_BAR; PG8_SCHED;
;             PG8_LDA(At, 1, 1); PG8_STAGE(PG8_SB(1, 0), b3, voffB); PG8_STAGE(PG8_SB(1, 1), b3 + hstep, voffB); PG8_STAGE(PG8_SA(1, 0), a3, voffA);
	v_mfma_f32_16x16x32_bf16 v[112:115], v[164:167], v[216:219], v[112:115]
	v_mfma_f32_16x16x32_bf16 v[104:107], v[172:175], v[216:219], v[104:107]
	v_mfma_f32_16x16x32_bf16 v[68:71], v[164:167], v[238:241], v[68:71]
	v_mfma_f32_16x16x32_bf16 v[64:67], v[172:175], v[238:241], v[64:67]
	s_setprio 0
	s_add_i32 s73, s73, s41
	v_lshl_add_u64 v[194:195], v[194:195], 0, s[36:37]
	s_mov_b32 m0, s73
	ds_read_b128 v[176:179], v143 offset:49152
	ds_read_b128 v[180:183], v143 offset:50176
	ds_read_b128 v[184:187], v143 offset:51200
	ds_read_b128 v[188:191], v143 offset:52224
	ds_read_b128 v[212:215], v143 offset:53248
	ds_read_b128 v[216:219], v143 offset:54272
	ds_read_b128 v[234:237], v143 offset:55296
	ds_read_b128 v[238:241], v143 offset:56320
	global_load_lds_dwordx4 v[194:195], off
	s_add_i32 m0, s73, 0x2000
	s_add_u32 s58, s58, 0x40080
	v_lshl_add_u64 v[194:195], v[196:197], 0, s[36:37]
	s_addc_u32 s59, s59, 0
	s_add_i32 s73, s76, s41
	global_load_lds_dwordx4 v[194:195], off
	v_lshl_add_u64 v[194:195], s[58:59], 0, v[192:193]
	s_mov_b32 m0, s73
	s_nop 0
	global_load_lds_dwordx4 v[194:195], off
	v_lshl_add_u64 v[194:195], s[58:59], 0, v[132:133]
	s_add_i32 m0, s73, 0x2000
	s_nop 0
	global_load_lds_dwordx4 v[194:195], off
	v_lshl_add_u64 v[194:195], v[202:203], 0, s[36:37]
	s_mov_b32 m0, s54
	s_nop 0
	global_load_lds_dwordx4 v[194:195], off
	v_lshl_add_u64 v[194:195], v[204:205], 0, s[36:37]
	s_mov_b32 m0, s55
	s_nop 0
	global_load_lds_dwordx4 v[194:195], off
	s_waitcnt vmcnt(8)
	s_waitcnt lgkmcnt(0)
	s_barrier
	s_setprio 1
	s_waitcnt lgkmcnt(0)
	v_mfma_f32_16x16x32_bf16 v[60:63], v[144:147], v[176:179], v[60:63]
	v_mfma_f32_16x16x32_bf16 v[56:59], v[152:155], v[176:179], v[56:59]
	v_mfma_f32_16x16x32_bf16 v[44:47], v[144:147], v[184:187], v[44:47]
	v_mfma_f32_16x16x32_bf16 v[40:43], v[152:155], v[184:187], v[40:43]
	v_mfma_f32_16x16x32_bf16 v[28:31], v[144:147], v[212:215], v[28:31]
	v_mfma_f32_16x16x32_bf16 v[24:27], v[152:155], v[212:215], v[24:27]
	v_mfma_f32_16x16x32_bf16 v[12:15], v[144:147], v[234:237], v[12:15]
	v_mfma_f32_16x16x32_bf16 v[8:11], v[152:155], v[234:237], v[8:11]
	v_mfma_f32_16x16x32_bf16 v[60:63], v[148:151], v[180:183], v[60:63]
	v_mfma_f32_16x16x32_bf16 v[56:59], v[156:159], v[180:183], v[56:59]
	v_mfma_f32_16x16x32_bf16 v[44:47], v[148:151], v[188:191], v[44:47]
	v_mfma_f32_16x16x32_bf16 v[40:43], v[156:159], v[188:191], v[40:43]
	v_mfma_f32_16x16x32_bf16 v[28:31], v[148:151], v[216:219], v[28:31]
	v_mfma_f32_16x16x32_bf16 v[24:27], v[156:159], v[216:219], v[24:27]
	v_mfma_f32_16x16x32_bf16 v[12:15], v[148:151], v[238:241], v[12:15]
	v_mfma_f32_16x16x32_bf16 v[8:11], v[156:159], v[238:241], v[8:11]
	s_setprio 0
	s_setprio 1
	v_mfma_f32_16x16x32_bf16 v[52:55], v[160:163], v[176:179], v[52:55]
	v_mfma_f32_16x16x32_bf16 v[48:51], v[168:171], v[176:179], v[48:51]
	v_mfma_f32_16x16x32_bf16 v[36:39], v[160:163], v[184:187], v[36:39]
	v_mfma_f32_16x16x32_bf16 v[32:35], v[168:171], v[184:187], v[32:35]
	v_mfma_f32_16x16x32_bf16 v[20:23], v[160:163], v[212:215], v[20:23]
	v_mfma_f32_16x16x32_bf16 v[16:19], v[168:171], v[212:215], v[16:19]
	v_mfma_f32_16x16x32_bf16 v[4:7], v[160:163], v[234:237], v[4:7]
	v_mfma_f32_16x16x32_bf16 v[0:3], v[168:171], v[234:237], v[0:3]
	v_mfma_f32_16x16x32_bf16 v[52:55], v[164:167], v[180:183], v[52:55]
	v_mfma_f32_16x16x32_bf16 v[48:51], v[172:175], v[180:183], v[48:51]
	v_mfma_f32_16x16x32_bf16 v[36:39], v[164:167], v[188:191], v[36:39]
	v_mfma_f32_16x16x32_bf16 v[32:35], v[172:175], v[188:191], v[32:35]
	s_barrier
; #define PG8_MMA(ai, bj, At, Bt) do { __builtin_amdgcn_s_setprio(1); _Pragma("unroll") for (int m = 0; m < 4; ++m) _Pragma("unroll") for (int n = 0; n < 2; ++n) _Pragma("unroll") for (int k = 0; k < 2; ++k) \
;         acc[ai][bj][m][n] = __builtin_amdgcn_mfma_f32_16x16x32_bf16(Bt[n][k], At[m][k], acc[ai][bj][m][n], 0, 0, 0); __builtin_amdgcn_s_setprio(0); } while (0)
; #define PG8_WAIT_V(n) asm volatile("s_waitcnt vmcnt(" #n ")" ::: "memory")
; #define PG8_WAIT_L(n) asm volatile("s_waitcnt lgkmcnt(" #n ")" ::: "memory")
; #define PG8_BAR __builtin_amdgcn_s_barrier()
; #define PG8_SCHED __builtin_amdgcn_sched_barrier(0)
; template <class Epi, class Sched, bool ALIGN_EPI = false, bool SP2 = false>
; __device__ __forceinline__ void gemm_phase(PG8_LAS unsigned char* lds, const Gemm g, const Sched& S, const Epi& E, const int tid) {
;     ...
;             PG8_WAIT_V(8); PG8_WAIT_L(0); PG8_BAR; PG8_MMA(1, 0, At, B0); PG8_MMA(1, 1, At, B1); PG8_BAR; PG8_SCHED;
;     ...
;         }
;         if constexpr (ALIGN_EPI) { if (wr == 0) PG8_BAR; }
;         if constexpr (!Epi::AFTER_DRAIN) { E(acc, cur, wr, wc, fr, fq); S.done(cur); }
;         if (!has_next) break;
; #pragma unroll
;         for (int a = 0; a < 2; ++a)
; #pragma unroll
;             for (int b = 0; b < 2; ++b)
; #pragma unroll
;                 for (int m = 0; m < 4; ++m)
; #pragma unroll
;                     for (int n = 0; n < 2; ++n) acc[a][b][m][n] = (f32x4){0.f, 0.f, 0.f, 0.f};
;         cur = nxt; cA = nA; cB = nB; ++ui;
	v_mfma_f32_16x16x32_bf16 v[20:23], v[164:167], v[216:219], v[20:23]
	v_mfma_f32_16x16x32_bf16 v[16:19], v[172:175], v[216:219], v[16:19]
	v_mfma_f32_16x16x32_bf16 v[4:7], v[164:167], v[238:241], v[4:7]
	v_mfma_f32_16x16x32_bf16 v[0:3], v[172:175], v[238:241], v[0:3]
	s_setprio 0
	s_add_i32 s72, s72, 2
	s_add_u32 s44, s44, 0x100
	s_addc_u32 s45, s45, 0
	s_cmp_gt_u32 s72, 13
	s_cbranch_scc0 .LBB0_239
	s_nop 7
	s_add_u32 s44, s19, 0xffffff00
	s_addc_u32 s45, s62, -1
	s_andn2_b64 vcc, exec, s[8:9]
	s_cbranch_vccnz .LBB0_242
	v_mov_b32_e32 v0, 0
	s_mov_b32 s22, s12
	s_mov_b32 s20, s14
	s_mov_b64 s[10:11], s[28:29]
	s_mov_b32 s60, s18
	v_mov_b32_e32 v1, v0
	v_mov_b32_e32 v2, v0
	v_mov_b32_e32 v3, v0
	v_mov_b32_e32 v4, v0
	v_mov_b32_e32 v5, v0
	v_mov_b32_e32 v6, v0
	v_mov_b32_e32 v7, v0
	v_mov_b32_e32 v16, v0
	v_mov_b32_e32 v17, v0
	v_mov_b32_e32 v18, v0
	v_mov_b32_e32 v19, v0
	v_mov_b32_e32 v20, v0
	v_mov_b32_e32 v21, v0
	v_mov_b32_e32 v22, v0
	v_mov_b32_e32 v23, v0
	v_mov_b32_e32 v32, v0
	v_mov_b32_e32 v33, v0
	v_mov_b32_e32 v34, v0
	v_mov_b32_e32 v35, v0
	v_mov_b32_e32 v36, v0
	v_mov_b32_e32 v37, v0
	v_mov_b32_e32 v38, v0
	v_mov_b32_e32 v39, v0
	v_mov_b32_e32 v48, v0
	v_mov_b32_e32 v49, v0
	v_mov_b32_e32 v50, v0
	v_mov_b32_e32 v51, v0
	v_mov_b32_e32 v52, v0
	v_mov_b32_e32 v53, v0
	v_mov_b32_e32 v54, v0
	v_mov_b32_e32 v55, v0
	v_mov_b32_e32 v8, v0
	v_mov_b32_e32 v9, v0
	v_mov_b32_e32 v10, v0
	v_mov_b32_e32 v11, v0
	v_mov_b32_e32 v12, v0
	v_mov_b32_e32 v13, v0
	v_mov_b32_e32 v14, v0
	v_mov_b32_e32 v15, v0
	v_mov_b32_e32 v24, v0
	v_mov_b32_e32 v25, v0
	v_mov_b32_e32 v26, v0
	v_mov_b32_e32 v27, v0
	v_mov_b32_e32 v28, v0
	v_mov_b32_e32 v29, v0
	v_mov_b32_e32 v30, v0
	v_mov_b32_e32 v31, v0
	v_mov_b32_e32 v40, v0
	v_mov_b32_e32 v41, v0
	v_mov_b32_e32 v42, v0
	v_mov_b32_e32 v43, v0
	v_mov_b32_e32 v44, v0
	v_mov_b32_e32 v45, v0
	v_mov_b32_e32 v46, v0
	v_mov_b32_e32 v47, v0
	v_mov_b32_e32 v56, v0
	v_mov_b32_e32 v57, v0
	v_mov_b32_e32 v58, v0
	v_mov_b32_e32 v59, v0
	v_mov_b32_e32 v60, v0
	v_mov_b32_e32 v61, v0
	v_mov_b32_e32 v62, v0
	v_mov_b32_e32 v63, v0
	v_mov_b32_e32 v64, v0
	v_mov_b32_e32 v65, v0
	v_mov_b32_e32 v66, v0
	v_mov_b32_e32 v67, v0
	v_mov_b32_e32 v68, v0
	v_mov_b32_e32 v69, v0
	v_mov_b32_e32 v70, v0
	v_mov_b32_e32 v71, v0
	v_mov_b32_e32 v104, v0
	v_mov_b32_e32 v105, v0
	v_mov_b32_e32 v106, v0
	v_mov_b32_e32 v107, v0
	v_mov_b32_e32 v112, v0
	v_mov_b32_e32 v113, v0
	v_mov_b32_e32 v114, v0
	v_mov_b32_e32 v115, v0
	v_mov_b32_e32 v116, v0
	v_mov_b32_e32 v117, v0
	v_mov_b32_e32 v118, v0
	v_mov_b32_e32 v119, v0
	v_mov_b32_e32 v108, v0
	v_mov_b32_e32 v109, v0
	v_mov_b32_e32 v110, v0
	v_mov_b32_e32 v111, v0
	v_mov_b32_e32 v88, v0
	v_mov_b32_e32 v89, v0
	v_mov_b32_e32 v90, v0
	v_mov_b32_e32 v91, v0
	v_mov_b32_e32 v80, v0
	v_mov_b32_e32 v81, v0
	v_mov_b32_e32 v82, v0
	v_mov_b32_e32 v83, v0
	v_mov_b32_e32 v84, v0
	v_mov_b32_e32 v85, v0
	v_mov_b32_e32 v86, v0
	v_mov_b32_e32 v87, v0
	v_mov_b32_e32 v92, v0
	v_mov_b32_e32 v93, v0
	v_mov_b32_e32 v94, v0
	v_mov_b32_e32 v95, v0
	v_mov_b32_e32 v120, v0
	v_mov_b32_e32 v121, v0
	v_mov_b32_e32 v122, v0
	v_mov_b32_e32 v123, v0
	v_mov_b32_e32 v124, v0
	v_mov_b32_e32 v125, v0
	v_mov_b32_e32 v126, v0
	v_mov_b32_e32 v127, v0
	v_mov_b32_e32 v96, v0
	v_mov_b32_e32 v97, v0
	v_mov_b32_e32 v98, v0
	v_mov_b32_e32 v99, v0
	v_mov_b32_e32 v100, v0
	v_mov_b32_e32 v101, v0
	v_mov_b32_e32 v102, v0
	v_mov_b32_e32 v103, v0
	v_mov_b32_e32 v72, v0
	v_mov_b32_e32 v73, v0
	v_mov_b32_e32 v74, v0
	v_mov_b32_e32 v75, v0
	v_mov_b32_e32 v76, v0
	v_mov_b32_e32 v77, v0
	v_mov_b32_e32 v78, v0
	v_mov_b32_e32 v79, v0
	s_load_dword s75, s[96:97], 0x0
	s_mov_b64 s[72:73], 0x20000
	s_andn2_b64 vcc, exec, s[6:7]
	s_cbranch_vccnz .LBB0_243
	s_branch .LBB0_244

; #define PG8_STAGE(bufoff, gbase, voff) do { _Pragma("unroll") for (int _i = 0; _i < 2; ++_i) \
;         __builtin_amdgcn_global_load_lds((const unsigned*)((const char*)(gbase) + (voff)[_i]), (PG8_LAS unsigned*)(lds + (bufoff) + ldsw + _i * 8192), 16, 0, 0); } while (0)
; #define PG8_LDA(dst, b, h) do { _Pragma("unroll") for (int m = 0; m < 4; ++m) _Pragma("unroll") for (int k = 0; k < 2; ++k) dst[m][k] = *(const PG8_LAS bf16x8*)(lds + PG8_SA(b, h) + aoff + m * 2048 + k * 1024); } while (0)
; #define PG8_LDB(dst, b, h) do { _Pragma("unroll") for (int n = 0; n < 2; ++n) _Pragma("unroll") for (int k = 0; k < 2; ++k) dst[n][k] = *(const PG8_LAS bf16x8*)(lds + PG8_SB(b, h) + boff + n * 2048 + k * 1024); } while (0)
; #define PG8_MMA(ai, bj, At, Bt) do { __builtin_amdgcn_s_setprio(1); _Pragma("unroll") for (int m = 0; m < 4; ++m) _Pragma("unroll") for (int n = 0; n < 2; ++n) _Pragma("unroll") for (int k = 0; k < 2; ++k) \
;         acc[ai][bj][m][n] = __builtin_amdgcn_mfma_f32_16x16x32_bf16(Bt[n][k], At[m][k], acc[ai][bj][m][n], 0, 0, 0); __builtin_amdgcn_s_setprio(0); } while (0)
; #define PG8_WAIT_V(n) asm volatile("s_waitcnt vmcnt(" #n ")" ::: "memory")
; #define PG8_WAIT_L(n) asm volatile("s_waitcnt lgkmcnt(" #n ")" ::: "memory")
; template <class Epi, class Sched, bool ALIGN_EPI = false, bool SP2 = false>
; __device__ __forceinline__ void gemm_phase(PG8_LAS unsigned char* lds, const Gemm g, const Sched& S, const Epi& E, const int tid) {
;     ...
;             const bool last = (t == nt - 2);
;             const char* a1 = cA + (size_t)(t + 1) * kstep;
;             const char* a2 = last ? nA : cA + (size_t)(t + 2) * kstep; const char* b2 = last ? nB : cB + (size_t)(t + 2) * kstep;
;             const char* a3 = a2 + kstep; const char* b3 = b2 + kstep;
;             if (last && has_next) S.a_ready(nxt);
;             if constexpr (SP2) {
;             PG8_LDB(B0, 0, 0); PG8_LDB(B1, 0, 1); PG8_SCHED; PG8_LDA(At, 0, 0); PG8_STAGE(PG8_SA(1, 1), a1 + hstep, voffA);
;             PG8_WAIT_V(8); PG8_WAIT_L(0); PG8_BAR; PG8_MMA(0, 0, At, B0); PG8_MMA(0, 1, At, B1); PG8_BAR; PG8_SCHED;
;             PG8_LDA(At, 0, 1); PG8_STAGE(PG8_SB(0, 0), b2, voffB); PG8_STAGE(PG8_SB(0, 1), b2 + hstep, voffB); PG8_STAGE(PG8_SA(0, 0), a2, voffA);
;             PG8_WAIT_V(8); PG8_WAIT_L(0); PG8_BAR; PG8_MMA(1, 0, At, B0); PG8_MMA(1, 1, At, B1); PG8_BAR; PG8_SCHED;
.LBB0_324:
	s_add_u32 s28, s22, 0xfffc0080
	s_addc_u32 s29, s23, -1
	s_add_i32 s35, 0, 0x10000
	s_cmp_eq_u32 s34, 12
	s_cselect_b32 s45, s1, s29
	s_cselect_b32 s44, s2, s28
	s_cselect_b32 s29, s13, s26
	s_cselect_b32 s28, s15, s21
	s_add_i32 s38, 0, 0x14000
	v_add_u32_e32 v152, s35, v142
	v_add_u32_e32 v168, s38, v142
	ds_read_b128 v[138:141], v152
	ds_read_b128 v[144:147], v152 offset:1024
	ds_read_b128 v[148:151], v152 offset:2048
	ds_read_b128 v[152:155], v152 offset:3072
	ds_read_b128 v[156:159], v168
	ds_read_b128 v[160:163], v168 offset:1024
	ds_read_b128 v[164:167], v168 offset:2048
	ds_read_b128 v[168:171], v168 offset:3072
	v_lshl_add_u64 v[194:195], s[22:23], 0, v[134:135]
	s_add_i32 m0, s80, 0xc000
	ds_read_b128 v[172:175], v143
	ds_read_b128 v[176:179], v143 offset:1024
	ds_read_b128 v[180:183], v143 offset:2048
	ds_read_b128 v[184:187], v143 offset:3072
	ds_read_b128 v[188:191], v143 offset:4096
	ds_read_b128 v[212:215], v143 offset:5120
	ds_read_b128 v[216:219], v143 offset:6144
	ds_read_b128 v[232:235], v143 offset:7168
	global_load_lds_dwordx4 v[194:195], off
	v_lshl_add_u64 v[194:195], s[22:23], 0, v[136:137]
	s_add_i32 m0, s80, 0xe000
	s_nop 0
	global_load_lds_dwordx4 v[194:195], off
	s_waitcnt vmcnt(8)
	s_waitcnt lgkmcnt(0)
	s_barrier
	s_setprio 1
	s_waitcnt lgkmcnt(0)
	v_mfma_f32_16x16x32_bf16 v[124:127], v[138:141], v[172:175], v[124:127]
	v_mfma_f32_16x16x32_bf16 v[120:123], v[148:151], v[172:175], v[120:123]
	v_mfma_f32_16x16x32_bf16 v[108:111], v[138:141], v[180:183], v[108:111]
	v_mfma_f32_16x16x32_bf16 v[104:107], v[148:151], v[180:183], v[104:107]
	v_mfma_f32_16x16x32_bf16 v[92:95], v[138:141], v[188:191], v[92:95]
	v_mfma_f32_16x16x32_bf16 v[88:91], v[148:151], v[188:191], v[88:91]
	v_mfma_f32_16x16x32_bf16 v[76:79], v[138:141], v[216:219], v[76:79]
	v_mfma_f32_16x16x32_bf16 v[72:75], v[148:151], v[216:219], v[72:75]
	v_mfma_f32_16x16x32_bf16 v[124:127], v[144:147], v[176:179], v[124:127]
	v_mfma_f32_16x16x32_bf16 v[120:123], v[152:155], v[176:179], v[120:123]
	v_mfma_f32_16x16x32_bf16 v[108:111], v[144:147], v[184:187], v[108:111]
	v_mfma_f32_16x16x32_bf16 v[104:107], v[152:155], v[184:187], v[104:107]
	v_mfma_f32_16x16x32_bf16 v[92:95], v[144:147], v[212:215], v[92:95]
	v_mfma_f32_16x16x32_bf16 v[88:91], v[152:155], v[212:215], v[88:91]
	v_mfma_f32_16x16x32_bf16 v[76:79], v[144:147], v[232:235], v[76:79]
	v_mfma_f32_16x16x32_bf16 v[72:75], v[152:155], v[232:235], v[72:75]
	s_setprio 0
	s_setprio 1
	v_mfma_f32_16x16x32_bf16 v[116:119], v[156:159], v[172:175], v[116:119]
	v_mfma_f32_16x16x32_bf16 v[112:115], v[164:167], v[172:175], v[112:115]
	v_mfma_f32_16x16x32_bf16 v[100:103], v[156:159], v[180:183], v[100:103]
	v_mfma_f32_16x16x32_bf16 v[96:99], v[164:167], v[180:183], v[96:99]
	v_mfma_f32_16x16x32_bf16 v[84:87], v[156:159], v[188:191], v[84:87]
	v_mfma_f32_16x16x32_bf16 v[80:83], v[164:167], v[188:191], v[80:83]
	v_mfma_f32_16x16x32_bf16 v[68:71], v[156:159], v[216:219], v[68:71]
	v_mfma_f32_16x16x32_bf16 v[64:67], v[164:167], v[216:219], v[64:67]
	v_mfma_f32_16x16x32_bf16 v[116:119], v[160:163], v[176:179], v[116:119]
	v_mfma_f32_16x16x32_bf16 v[112:115], v[168:171], v[176:179], v[112:115]
	v_mfma_f32_16x16x32_bf16 v[100:103], v[160:163], v[184:187], v[100:103]
	v_mfma_f32_16x16x32_bf16 v[96:99], v[168:171], v[184:187], v[96:99]
	s_barrier
	v_mfma_f32_16x16x32_bf16 v[84:87], v[160:163], v[212:215], v[84:87]
	v_mfma_f32_16x16x32_bf16 v[80:83], v[168:171], v[212:215], v[80:83]
	v_mfma_f32_16x16x32_bf16 v[68:71], v[160:163], v[232:235], v[68:71]
	v_mfma_f32_16x16x32_bf16 v[64:67], v[168:171], v[232:235], v[64:67]
	s_setprio 0
	s_add_i32 s35, s35, s79
	v_lshl_add_u64 v[194:195], s[28:29], 0, v[192:193]
	s_mov_b32 m0, s35
	ds_read_b128 v[172:175], v143 offset:16384
	ds_read_b128 v[176:179], v143 offset:17408
	ds_read_b128 v[180:183], v143 offset:18432
	ds_read_b128 v[184:187], v143 offset:19456
	ds_read_b128 v[188:191], v143 offset:20480
	ds_read_b128 v[212:215], v143 offset:21504
	ds_read_b128 v[216:219], v143 offset:22528
	ds_read_b128 v[232:235], v143 offset:23552
	global_load_lds_dwordx4 v[194:195], off
	s_add_i32 m0, s35, 0x2000
	s_add_u32 s40, s28, 0x40000
	v_lshl_add_u64 v[196:197], s[28:29], 0, v[132:133]
	s_addc_u32 s41, s29, 0
	s_add_i32 s35, s38, s79
	global_load_lds_dwordx4 v[196:197], off
	v_lshl_add_u64 v[202:203], s[40:41], 0, v[192:193]
	s_mov_b32 m0, s35
	v_lshl_add_u64 v[204:205], s[44:45], 0, v[130:131]
	global_load_lds_dwordx4 v[202:203], off
	v_lshl_add_u64 v[202:203], s[40:41], 0, v[132:133]
	s_add_i32 m0, s35, 0x2000
	s_nop 0
	global_load_lds_dwordx4 v[202:203], off
	v_lshl_add_u64 v[202:203], s[44:45], 0, v[128:129]
	s_mov_b32 m0, s80
	s_nop 0
	global_load_lds_dwordx4 v[202:203], off
	s_mov_b32 m0, s81
	s_nop 0
	global_load_lds_dwordx4 v[204:205], off
	s_waitcnt vmcnt(8)
	s_waitcnt lgkmcnt(0)
	s_barrier
; #define PG8_STAGE(bufoff, gbase, voff) do { _Pragma("unroll") for (int _i = 0; _i < 2; ++_i) \
;         __builtin_amdgcn_global_load_lds((const unsigned*)((const char*)(gbase) + (voff)[_i]), (PG8_LAS unsigned*)(lds + (bufoff) + ldsw + _i * 8192), 16, 0, 0); } while (0)
; #define PG8_LDA(dst, b, h) do { _Pragma("unroll") for (int m = 0; m < 4; ++m) _Pragma("unroll") for (int k = 0; k < 2; ++k) dst[m][k] = *(const PG8_LAS bf16x8*)(lds + PG8_SA(b, h) + aoff + m * 2048 + k * 1024); } while (0)
; #define PG8_LDB(dst, b, h) do { _Pragma("unroll") for (int n = 0; n < 2; ++n) _Pragma("unroll") for (int k = 0; k < 2; ++k) dst[n][k] = *(const PG8_LAS bf16x8*)(lds + PG8_SB(b, h) + boff + n * 2048 + k * 1024); } while (0)
; #define PG8_MMA(ai, bj, At, Bt) do { __builtin_amdgcn_s_setprio(1); _Pragma("unroll") for (int m = 0; m < 4; ++m) _Pragma("unroll") for (int n = 0; n < 2; ++n) _Pragma("unroll") for (int k = 0; k < 2; ++k) \
;         acc[ai][bj][m][n] = __builtin_amdgcn_mfma_f32_16x16x32_bf16(Bt[n][k], At[m][k], acc[ai][bj][m][n], 0, 0, 0); __builtin_amdgcn_s_setprio(0); } while (0)
; #define PG8_WAIT_V(n) asm volatile("s_waitcnt vmcnt(" #n ")" ::: "memory")
; #define PG8_WAIT_L(n) asm volatile("s_waitcnt lgkmcnt(" #n ")" ::: "memory")
; #define PG8_BAR __builtin_amdgcn_s_barrier()
; #define PG8_SCHED __builtin_amdgcn_sched_barrier(0)
; template <class Epi, class Sched, bool ALIGN_EPI = false, bool SP2 = false>
; __device__ __forceinline__ void gemm_phase(PG8_LAS unsigned char* lds, const Gemm g, const Sched& S, const Epi& E, const int tid) {
;     ...
;             PG8_WAIT_V(8); PG8_WAIT_L(0); PG8_BAR; PG8_MMA(1, 0, At, B0); PG8_MMA(1, 1, At, B1); PG8_BAR; PG8_SCHED;
;             PG8_LDB(B0, 1, 0); PG8_LDB(B1, 1, 1); PG8_SCHED; PG8_LDA(At, 1, 0); PG8_STAGE(PG8_SA(0, 1), a2 + hstep, voffA);
;             PG8_WAIT_V(8); PG8_WAIT_L(0); PG8_BAR; PG8_MMA(0, 0, At, B0); PG8_MMA(0, 1, At, B1); PG8_BAR; PG8_SCHED;
	s_setprio 1
	s_waitcnt lgkmcnt(0)
	v_mfma_f32_16x16x32_bf16 v[60:63], v[138:141], v[172:175], v[60:63]
	v_mfma_f32_16x16x32_bf16 v[56:59], v[148:151], v[172:175], v[56:59]
	v_mfma_f32_16x16x32_bf16 v[44:47], v[138:141], v[180:183], v[44:47]
	v_mfma_f32_16x16x32_bf16 v[40:43], v[148:151], v[180:183], v[40:43]
	v_mfma_f32_16x16x32_bf16 v[28:31], v[138:141], v[188:191], v[28:31]
	v_mfma_f32_16x16x32_bf16 v[24:27], v[148:151], v[188:191], v[24:27]
	v_mfma_f32_16x16x32_bf16 v[12:15], v[138:141], v[216:219], v[12:15]
	v_mfma_f32_16x16x32_bf16 v[8:11], v[148:151], v[216:219], v[8:11]
	v_mfma_f32_16x16x32_bf16 v[60:63], v[144:147], v[176:179], v[60:63]
	v_mfma_f32_16x16x32_bf16 v[56:59], v[152:155], v[176:179], v[56:59]
	v_mfma_f32_16x16x32_bf16 v[44:47], v[144:147], v[184:187], v[44:47]
	v_mfma_f32_16x16x32_bf16 v[40:43], v[152:155], v[184:187], v[40:43]
	v_mfma_f32_16x16x32_bf16 v[28:31], v[144:147], v[212:215], v[28:31]
	v_mfma_f32_16x16x32_bf16 v[24:27], v[152:155], v[212:215], v[24:27]
	v_mfma_f32_16x16x32_bf16 v[12:15], v[144:147], v[232:235], v[12:15]
	v_mfma_f32_16x16x32_bf16 v[8:11], v[152:155], v[232:235], v[8:11]
	s_setprio 0
	s_setprio 1
	v_mfma_f32_16x16x32_bf16 v[52:55], v[156:159], v[172:175], v[52:55]
	v_mfma_f32_16x16x32_bf16 v[48:51], v[164:167], v[172:175], v[48:51]
	v_mfma_f32_16x16x32_bf16 v[36:39], v[156:159], v[180:183], v[36:39]
	v_mfma_f32_16x16x32_bf16 v[32:35], v[164:167], v[180:183], v[32:35]
	v_mfma_f32_16x16x32_bf16 v[20:23], v[156:159], v[188:191], v[20:23]
	v_mfma_f32_16x16x32_bf16 v[16:19], v[164:167], v[188:191], v[16:19]
	v_mfma_f32_16x16x32_bf16 v[4:7], v[156:159], v[216:219], v[4:7]
	v_mfma_f32_16x16x32_bf16 v[0:3], v[164:167], v[216:219], v[0:3]
	v_mfma_f32_16x16x32_bf16 v[52:55], v[160:163], v[176:179], v[52:55]
	v_mfma_f32_16x16x32_bf16 v[48:51], v[168:171], v[176:179], v[48:51]
	v_mfma_f32_16x16x32_bf16 v[36:39], v[160:163], v[184:187], v[36:39]
	v_mfma_f32_16x16x32_bf16 v[32:35], v[168:171], v[184:187], v[32:35]
	s_barrier
	v_mfma_f32_16x16x32_bf16 v[20:23], v[160:163], v[212:215], v[20:23]
	v_mfma_f32_16x16x32_bf16 v[16:19], v[168:171], v[212:215], v[16:19]
	v_mfma_f32_16x16x32_bf16 v[4:7], v[160:163], v[232:235], v[4:7]
	v_mfma_f32_16x16x32_bf16 v[0:3], v[168:171], v[232:235], v[0:3]
	s_setprio 0
	s_add_i32 s35, 0, 0x18000
	s_add_i32 s38, 0, 0x1c000
	v_add_u32_e32 v152, s35, v142
	v_add_u32_e32 v168, s38, v142
	ds_read_b128 v[138:141], v152
	ds_read_b128 v[144:147], v152 offset:1024
	ds_read_b128 v[148:151], v152 offset:2048
	ds_read_b128 v[152:155], v152 offset:3072
	ds_read_b128 v[156:159], v168
	ds_read_b128 v[160:163], v168 offset:1024
	ds_read_b128 v[164:167], v168 offset:2048
	ds_read_b128 v[168:171], v168 offset:3072
	s_add_u32 s40, s44, 0x40000
	s_addc_u32 s41, s45, 0
	s_mov_b32 m0, s82
	v_lshl_add_u64 v[206:207], s[40:41], 0, v[128:129]
	ds_read_b128 v[172:175], v143 offset:32768
	ds_read_b128 v[176:179], v143 offset:33792
	ds_read_b128 v[180:183], v143 offset:34816
	ds_read_b128 v[184:187], v143 offset:35840
	ds_read_b128 v[188:191], v143 offset:36864
	ds_read_b128 v[212:215], v143 offset:37888
	ds_read_b128 v[216:219], v143 offset:38912
	ds_read_b128 v[232:235], v143 offset:39936
	global_load_lds_dwordx4 v[206:207], off
	v_lshl_add_u64 v[206:207], s[40:41], 0, v[130:131]
	s_mov_b32 m0, s83
	s_nop 0
	global_load_lds_dwordx4 v[206:207], off
	s_waitcnt vmcnt(8)
	s_waitcnt lgkmcnt(0)
	s_barrier
	s_setprio 1
	s_waitcnt lgkmcnt(0)
	v_mfma_f32_16x16x32_bf16 v[124:127], v[138:141], v[172:175], v[124:127]
	v_mfma_f32_16x16x32_bf16 v[120:123], v[148:151], v[172:175], v[120:123]
	v_mfma_f32_16x16x32_bf16 v[108:111], v[138:141], v[180:183], v[108:111]
	v_mfma_f32_16x16x32_bf16 v[104:107], v[148:151], v[180:183], v[104:107]
	v_mfma_f32_16x16x32_bf16 v[92:95], v[138:141], v[188:191], v[92:95]
	v_mfma_f32_16x16x32_bf16 v[88:91], v[148:151], v[188:191], v[88:91]
	v_mfma_f32_16x16x32_bf16 v[76:79], v[138:141], v[216:219], v[76:79]
	v_mfma_f32_16x16x32_bf16 v[72:75], v[148:151], v[216:219], v[72:75]
	v_mfma_f32_16x16x32_bf16 v[124:127], v[144:147], v[176:179], v[124:127]
	v_mfma_f32_16x16x32_bf16 v[120:123], v[152:155], v[176:179], v[120:123]
	v_mfma_f32_16x16x32_bf16 v[108:111], v[144:147], v[184:187], v[108:111]
	v_mfma_f32_16x16x32_bf16 v[104:107], v[152:155], v[184:187], v[104:107]
	v_mfma_f32_16x16x32_bf16 v[92:95], v[144:147], v[212:215], v[92:95]
	v_mfma_f32_16x16x32_bf16 v[88:91], v[152:155], v[212:215], v[88:91]
	v_mfma_f32_16x16x32_bf16 v[76:79], v[144:147], v[232:235], v[76:79]
	v_mfma_f32_16x16x32_bf16 v[72:75], v[152:155], v[232:235], v[72:75]
	s_setprio 0
	s_setprio 1
	v_mfma_f32_16x16x32_bf16 v[116:119], v[156:159], v[172:175], v[116:119]
	v_mfma_f32_16x16x32_bf16 v[112:115], v[164:167], v[172:175], v[112:115]
	v_mfma_f32_16x16x32_bf16 v[100:103], v[156:159], v[180:183], v[100:103]
	v_mfma_f32_16x16x32_bf16 v[96:99], v[164:167], v[180:183], v[96:99]
	v_mfma_f32_16x16x32_bf16 v[84:87], v[156:159], v[188:191], v[84:87]
	v_mfma_f32_16x16x32_bf16 v[80:83], v[164:167], v[188:191], v[80:83]
	v_mfma_f32_16x16x32_bf16 v[68:71], v[156:159], v[216:219], v[68:71]
	v_mfma_f32_16x16x32_bf16 v[64:67], v[164:167], v[216:219], v[64:67]
	v_mfma_f32_16x16x32_bf16 v[116:119], v[160:163], v[176:179], v[116:119]
	v_mfma_f32_16x16x32_bf16 v[112:115], v[168:171], v[176:179], v[112:115]
	v_mfma_f32_16x16x32_bf16 v[100:103], v[160:163], v[184:187], v[100:103]
	v_mfma_f32_16x16x32_bf16 v[96:99], v[168:171], v[184:187], v[96:99]
	s_barrier
; #define PG8_STAGE(bufoff, gbase, voff) do { _Pragma("unroll") for (int _i = 0; _i < 2; ++_i) \
;         __builtin_amdgcn_global_load_lds((const unsigned*)((const char*)(gbase) + (voff)[_i]), (PG8_LAS unsigned*)(lds + (bufoff) + ldsw + _i * 8192), 16, 0, 0); } while (0)
; #define PG8_LDA(dst, b, h) do { _Pragma("unroll") for (int m = 0; m < 4; ++m) _Pragma("unroll") for (int k = 0; k < 2; ++k) dst[m][k] = *(const PG8_LAS bf16x8*)(lds + PG8_SA(b, h) + aoff + m * 2048 + k * 1024); } while (0)
; #define PG8_MMA(ai, bj, At, Bt) do { __builtin_amdgcn_s_setprio(1); _Pragma("unroll") for (int m = 0; m < 4; ++m) _Pragma("unroll") for (int n = 0; n < 2; ++n) _Pragma("unroll") for (int k = 0; k < 2; ++k) \
;         acc[ai][bj][m][n] = __builtin_amdgcn_mfma_f32_16x16x32_bf16(Bt[n][k], At[m][k], acc[ai][bj][m][n], 0, 0, 0); __builtin_amdgcn_s_setprio(0); } while (0)
; #define PG8_WAIT_V(n) asm volatile("s_waitcnt vmcnt(" #n ")" ::: "memory")
; #define PG8_WAIT_L(n) asm volatile("s_waitcnt lgkmcnt(" #n ")" ::: "memory")
; #define PG8_BAR __builtin_amdgcn_s_barrier()
; #define PG8_SCHED __builtin_amdgcn_sched_barrier(0)
; template <class Epi, class Sched, bool ALIGN_EPI = false, bool SP2 = false>
; __device__ __forceinline__ void gemm_phase(PG8_LAS unsigned char* lds, const Gemm g, const Sched& S, const Epi& E, const int tid) {
;     ...
;             PG8_WAIT_V(8); PG8_WAIT_L(0); PG8_BAR; PG8_MMA(0, 0, At, B0); PG8_MMA(0, 1, At, B1); PG8_BAR; PG8_SCHED;
;             PG8_LDA(At, 1, 1); PG8_STAGE(PG8_SB(1, 0), b3, voffB); PG8_STAGE(PG8_SB(1, 1), b3 + hstep, voffB); PG8_STAGE(PG8_SA(1, 0), a3, voffA);
;             PG8_WAIT_V(8); PG8_WAIT_L(0); PG8_BAR; PG8_MMA(1, 0, At, B0); PG8_MMA(1, 1, At, B1); PG8_BAR; PG8_SCHED;
;     ...
;         if constexpr (ALIGN_EPI) { if (wr == 0) PG8_BAR; }
	v_mfma_f32_16x16x32_bf16 v[84:87], v[160:163], v[212:215], v[84:87]
	v_mfma_f32_16x16x32_bf16 v[80:83], v[168:171], v[212:215], v[80:83]
	v_mfma_f32_16x16x32_bf16 v[68:71], v[160:163], v[232:235], v[68:71]
	v_mfma_f32_16x16x32_bf16 v[64:67], v[168:171], v[232:235], v[64:67]
	s_setprio 0
	s_add_i32 s35, s35, s79
	v_lshl_add_u64 v[194:195], v[194:195], 0, s[36:37]
	s_mov_b32 m0, s35
	ds_read_b128 v[172:175], v143 offset:49152
	ds_read_b128 v[176:179], v143 offset:50176
	ds_read_b128 v[180:183], v143 offset:51200
	ds_read_b128 v[184:187], v143 offset:52224
	ds_read_b128 v[188:191], v143 offset:53248
	ds_read_b128 v[212:215], v143 offset:54272
	ds_read_b128 v[216:219], v143 offset:55296
	ds_read_b128 v[232:235], v143 offset:56320
	global_load_lds_dwordx4 v[194:195], off
	s_add_i32 m0, s35, 0x2000
	s_add_u32 s28, s28, 0x40080
	v_lshl_add_u64 v[194:195], v[196:197], 0, s[36:37]
	s_addc_u32 s29, s29, 0
	s_add_i32 s35, s38, s79
	global_load_lds_dwordx4 v[194:195], off
	v_lshl_add_u64 v[194:195], s[28:29], 0, v[192:193]
	s_mov_b32 m0, s35
	s_nop 0
	global_load_lds_dwordx4 v[194:195], off
	v_lshl_add_u64 v[194:195], s[28:29], 0, v[132:133]
	s_add_i32 m0, s35, 0x2000
	s_nop 0
	global_load_lds_dwordx4 v[194:195], off
	v_lshl_add_u64 v[194:195], v[202:203], 0, s[36:37]
	s_mov_b32 m0, s84
	s_nop 0
	global_load_lds_dwordx4 v[194:195], off
	v_lshl_add_u64 v[194:195], v[204:205], 0, s[36:37]
	s_mov_b32 m0, s85
	s_nop 0
	global_load_lds_dwordx4 v[194:195], off
	s_waitcnt vmcnt(8)
	s_waitcnt lgkmcnt(0)
	s_barrier
	s_setprio 1
	s_waitcnt lgkmcnt(0)
	v_mfma_f32_16x16x32_bf16 v[60:63], v[138:141], v[172:175], v[60:63]
	v_mfma_f32_16x16x32_bf16 v[56:59], v[148:151], v[172:175], v[56:59]
	v_mfma_f32_16x16x32_bf16 v[44:47], v[138:141], v[180:183], v[44:47]
	v_mfma_f32_16x16x32_bf16 v[40:43], v[148:151], v[180:183], v[40:43]
	v_mfma_f32_16x16x32_bf16 v[28:31], v[138:141], v[188:191], v[28:31]
	v_mfma_f32_16x16x32_bf16 v[24:27], v[148:151], v[188:191], v[24:27]
	v_mfma_f32_16x16x32_bf16 v[12:15], v[138:141], v[216:219], v[12:15]
	v_mfma_f32_16x16x32_bf16 v[8:11], v[148:151], v[216:219], v[8:11]
	v_mfma_f32_16x16x32_bf16 v[60:63], v[144:147], v[176:179], v[60:63]
	v_mfma_f32_16x16x32_bf16 v[56:59], v[152:155], v[176:179], v[56:59]
	v_mfma_f32_16x16x32_bf16 v[44:47], v[144:147], v[184:187], v[44:47]
	v_mfma_f32_16x16x32_bf16 v[40:43], v[152:155], v[184:187], v[40:43]
	v_mfma_f32_16x16x32_bf16 v[28:31], v[144:147], v[212:215], v[28:31]
	v_mfma_f32_16x16x32_bf16 v[24:27], v[152:155], v[212:215], v[24:27]
	v_mfma_f32_16x16x32_bf16 v[12:15], v[144:147], v[232:235], v[12:15]
	v_mfma_f32_16x16x32_bf16 v[8:11], v[152:155], v[232:235], v[8:11]
	s_setprio 0
	s_setprio 1
	v_mfma_f32_16x16x32_bf16 v[52:55], v[156:159], v[172:175], v[52:55]
	v_mfma_f32_16x16x32_bf16 v[48:51], v[164:167], v[172:175], v[48:51]
	v_mfma_f32_16x16x32_bf16 v[36:39], v[156:159], v[180:183], v[36:39]
	v_mfma_f32_16x16x32_bf16 v[32:35], v[164:167], v[180:183], v[32:35]
	v_mfma_f32_16x16x32_bf16 v[20:23], v[156:159], v[188:191], v[20:23]
	v_mfma_f32_16x16x32_bf16 v[16:19], v[164:167], v[188:191], v[16:19]
	v_mfma_f32_16x16x32_bf16 v[4:7], v[156:159], v[216:219], v[4:7]
	v_mfma_f32_16x16x32_bf16 v[0:3], v[164:167], v[216:219], v[0:3]
	v_mfma_f32_16x16x32_bf16 v[52:55], v[160:163], v[176:179], v[52:55]
	v_mfma_f32_16x16x32_bf16 v[48:51], v[168:171], v[176:179], v[48:51]
	v_mfma_f32_16x16x32_bf16 v[36:39], v[160:163], v[184:187], v[36:39]
	v_mfma_f32_16x16x32_bf16 v[32:35], v[168:171], v[184:187], v[32:35]
	s_barrier
	v_mfma_f32_16x16x32_bf16 v[20:23], v[160:163], v[212:215], v[20:23]
	v_mfma_f32_16x16x32_bf16 v[16:19], v[168:171], v[212:215], v[16:19]
	v_mfma_f32_16x16x32_bf16 v[4:7], v[160:163], v[232:235], v[4:7]
	v_mfma_f32_16x16x32_bf16 v[0:3], v[168:171], v[232:235], v[0:3]
	s_setprio 0
	s_add_i32 s34, s34, 2
	s_add_u32 s22, s22, 0x100
	s_addc_u32 s23, s23, 0
	s_add_u32 s21, s21, 0x100
	s_addc_u32 s26, s26, 0
	s_cmp_gt_u32 s34, 13
	s_cbranch_scc0 .LBB0_324
	s_nop 7
	s_and_b64 vcc, exec, s[10:11]
	s_cbranch_vccz .LBB0_327
	s_barrier

; #define PG8_STAGE(bufoff, gbase, voff) do { _Pragma("unroll") for (int _i = 0; _i < 2; ++_i) \
;         __builtin_amdgcn_global_load_lds((const unsigned*)((const char*)(gbase) + (voff)[_i]), (PG8_LAS unsigned*)(lds + (bufoff) + ldsw + _i * 8192), 16, 0, 0); } while (0)
; #define PG8_LDA(dst, b, h) do { _Pragma("unroll") for (int m = 0; m < 4; ++m) _Pragma("unroll") for (int k = 0; k < 2; ++k) dst[m][k] = *(const PG8_LAS bf16x8*)(lds + PG8_SA(b, h) + aoff + m * 2048 + k * 1024); } while (0)
; #define PG8_LDB(dst, b, h) do { _Pragma("unroll") for (int n = 0; n < 2; ++n) _Pragma("unroll") for (int k = 0; k < 2; ++k) dst[n][k] = *(const PG8_LAS bf16x8*)(lds + PG8_SB(b, h) + boff + n * 2048 + k * 1024); } while (0)
; #define PG8_MMA(ai, bj, At, Bt) do { __builtin_amdgcn_s_setprio(1); _Pragma("unroll") for (int m = 0; m < 4; ++m) _Pragma("unroll") for (int n = 0; n < 2; ++n) _Pragma("unroll") for (int k = 0; k < 2; ++k) \
;         acc[ai][bj][m][n] = __builtin_amdgcn_mfma_f32_16x16x32_bf16(Bt[n][k], At[m][k], acc[ai][bj][m][n], 0, 0, 0); __builtin_amdgcn_s_setprio(0); } while (0)
; #define PG8_WAIT_V(n) asm volatile("s_waitcnt vmcnt(" #n ")" ::: "memory")
; #define PG8_WAIT_L(n) asm volatile("s_waitcnt lgkmcnt(" #n ")" ::: "memory")
; template <class Epi, class Sched, bool ALIGN_EPI = false, bool SP2 = false>
; __device__ __forceinline__ void gemm_phase(PG8_LAS unsigned char* lds, const Gemm g, const Sched& S, const Epi& E, const int tid) {
;     ...
;             const bool last = (t == nt - 2);
;             const char* a1 = cA + (size_t)(t + 1) * kstep;
;             const char* a2 = last ? nA : cA + (size_t)(t + 2) * kstep; const char* b2 = last ? nB : cB + (size_t)(t + 2) * kstep;
;             const char* a3 = a2 + kstep; const char* b3 = b2 + kstep;
;             if (last && has_next) S.a_ready(nxt);
;             if constexpr (SP2) {
;             PG8_LDB(B0, 0, 0); PG8_LDB(B1, 0, 1); PG8_SCHED; PG8_LDA(At, 0, 0); PG8_STAGE(PG8_SA(1, 1), a1 + hstep, voffA);
;             PG8_WAIT_V(8); PG8_WAIT_L(0); PG8_BAR; PG8_MMA(0, 0, At, B0); PG8_MMA(0, 1, At, B1); PG8_BAR; PG8_SCHED;
;             PG8_LDA(At, 0, 1); PG8_STAGE(PG8_SB(0, 0), b2, voffB); PG8_STAGE(PG8_SB(0, 1), b2 + hstep, voffB); PG8_STAGE(PG8_SA(0, 0), a2, voffA);
;             PG8_WAIT_V(8); PG8_WAIT_L(0); PG8_BAR; PG8_MMA(1, 0, At, B0); PG8_MMA(1, 1, At, B1); PG8_BAR; PG8_SCHED;
.LBB0_348:
	s_add_u32 s35, s28, 0xfffe0080
	s_addc_u32 s38, s29, -1
	s_add_i32 s40, 0, 0x10000
	s_cmp_eq_u32 s34, 4
	s_cselect_b32 s59, s1, s38
	s_cselect_b32 s58, s2, s35
	s_cselect_b32 s45, s15, s26
	s_cselect_b32 s44, s17, s23
	s_add_i32 s35, 0, 0x14000
	v_add_u32_e32 v152, s40, v142
	v_add_u32_e32 v168, s35, v142
	ds_read_b128 v[138:141], v152
	ds_read_b128 v[144:147], v152 offset:1024
	ds_read_b128 v[148:151], v152 offset:2048
	ds_read_b128 v[152:155], v152 offset:3072
	ds_read_b128 v[156:159], v168
	ds_read_b128 v[160:163], v168 offset:1024
	ds_read_b128 v[164:167], v168 offset:2048
	ds_read_b128 v[168:171], v168 offset:3072
	v_lshl_add_u64 v[194:195], s[28:29], 0, v[134:135]
	s_add_i32 m0, s83, 0xc000
	ds_read_b128 v[172:175], v143
	ds_read_b128 v[176:179], v143 offset:1024
	ds_read_b128 v[180:183], v143 offset:2048
	ds_read_b128 v[184:187], v143 offset:3072
	ds_read_b128 v[188:191], v143 offset:4096
	ds_read_b128 v[212:215], v143 offset:5120
	ds_read_b128 v[216:219], v143 offset:6144
	ds_read_b128 v[232:235], v143 offset:7168
	global_load_lds_dwordx4 v[194:195], off
	v_lshl_add_u64 v[194:195], s[28:29], 0, v[136:137]
	s_add_i32 m0, s83, 0xe000
	s_nop 0
	global_load_lds_dwordx4 v[194:195], off
	s_waitcnt vmcnt(8)
	s_waitcnt lgkmcnt(0)
	s_barrier
	s_setprio 1
	s_waitcnt lgkmcnt(0)
	v_mfma_f32_16x16x32_bf16 v[124:127], v[138:141], v[172:175], v[124:127]
	v_mfma_f32_16x16x32_bf16 v[120:123], v[148:151], v[172:175], v[120:123]
	v_mfma_f32_16x16x32_bf16 v[108:111], v[138:141], v[180:183], v[108:111]
	v_mfma_f32_16x16x32_bf16 v[104:107], v[148:151], v[180:183], v[104:107]
	v_mfma_f32_16x16x32_bf16 v[92:95], v[138:141], v[188:191], v[92:95]
	v_mfma_f32_16x16x32_bf16 v[88:91], v[148:151], v[188:191], v[88:91]
	v_mfma_f32_16x16x32_bf16 v[76:79], v[138:141], v[216:219], v[76:79]
	v_mfma_f32_16x16x32_bf16 v[72:75], v[148:151], v[216:219], v[72:75]
	v_mfma_f32_16x16x32_bf16 v[124:127], v[144:147], v[176:179], v[124:127]
	v_mfma_f32_16x16x32_bf16 v[120:123], v[152:155], v[176:179], v[120:123]
	v_mfma_f32_16x16x32_bf16 v[108:111], v[144:147], v[184:187], v[108:111]
	v_mfma_f32_16x16x32_bf16 v[104:107], v[152:155], v[184:187], v[104:107]
	v_mfma_f32_16x16x32_bf16 v[92:95], v[144:147], v[212:215], v[92:95]
	v_mfma_f32_16x16x32_bf16 v[88:91], v[152:155], v[212:215], v[88:91]
	v_mfma_f32_16x16x32_bf16 v[76:79], v[144:147], v[232:235], v[76:79]
	v_mfma_f32_16x16x32_bf16 v[72:75], v[152:155], v[232:235], v[72:75]
	s_setprio 0
	s_setprio 1
	v_mfma_f32_16x16x32_bf16 v[116:119], v[156:159], v[172:175], v[116:119]
	v_mfma_f32_16x16x32_bf16 v[112:115], v[164:167], v[172:175], v[112:115]
	v_mfma_f32_16x16x32_bf16 v[100:103], v[156:159], v[180:183], v[100:103]
	v_mfma_f32_16x16x32_bf16 v[96:99], v[164:167], v[180:183], v[96:99]
	v_mfma_f32_16x16x32_bf16 v[84:87], v[156:159], v[188:191], v[84:87]
	v_mfma_f32_16x16x32_bf16 v[80:83], v[164:167], v[188:191], v[80:83]
	v_mfma_f32_16x16x32_bf16 v[68:71], v[156:159], v[216:219], v[68:71]
	v_mfma_f32_16x16x32_bf16 v[64:67], v[164:167], v[216:219], v[64:67]
	v_mfma_f32_16x16x32_bf16 v[116:119], v[160:163], v[176:179], v[116:119]
	v_mfma_f32_16x16x32_bf16 v[112:115], v[168:171], v[176:179], v[112:115]
	v_mfma_f32_16x16x32_bf16 v[100:103], v[160:163], v[184:187], v[100:103]
	v_mfma_f32_16x16x32_bf16 v[96:99], v[168:171], v[184:187], v[96:99]
	s_barrier
	v_mfma_f32_16x16x32_bf16 v[84:87], v[160:163], v[212:215], v[84:87]
	v_mfma_f32_16x16x32_bf16 v[80:83], v[168:171], v[212:215], v[80:83]
	v_mfma_f32_16x16x32_bf16 v[68:71], v[160:163], v[232:235], v[68:71]
	v_mfma_f32_16x16x32_bf16 v[64:67], v[168:171], v[232:235], v[64:67]
	s_setprio 0
	s_add_i32 s38, s40, s82
	v_lshl_add_u64 v[194:195], s[44:45], 0, v[192:193]
	s_mov_b32 m0, s38
	ds_read_b128 v[172:175], v143 offset:16384
	ds_read_b128 v[176:179], v143 offset:17408
	ds_read_b128 v[180:183], v143 offset:18432
	ds_read_b128 v[184:187], v143 offset:19456
	ds_read_b128 v[188:191], v143 offset:20480
	ds_read_b128 v[212:215], v143 offset:21504
	ds_read_b128 v[216:219], v143 offset:22528
	ds_read_b128 v[232:235], v143 offset:23552
	global_load_lds_dwordx4 v[194:195], off
	s_add_i32 m0, s38, 0x2000
	s_add_u32 s40, s44, 0x20000
	v_lshl_add_u64 v[196:197], s[44:45], 0, v[132:133]
	s_addc_u32 s41, s45, 0
	s_add_i32 s35, s35, s82
	global_load_lds_dwordx4 v[196:197], off
	v_lshl_add_u64 v[202:203], s[40:41], 0, v[192:193]
	s_mov_b32 m0, s35
	v_lshl_add_u64 v[204:205], s[58:59], 0, v[130:131]
	global_load_lds_dwordx4 v[202:203], off
	v_lshl_add_u64 v[202:203], s[40:41], 0, v[132:133]
	s_add_i32 m0, s35, 0x2000
	s_nop 0
	global_load_lds_dwordx4 v[202:203], off
	v_lshl_add_u64 v[202:203], s[58:59], 0, v[128:129]
	s_mov_b32 m0, s83
	s_nop 0
	global_load_lds_dwordx4 v[202:203], off
	s_mov_b32 m0, s84
	s_nop 0
	global_load_lds_dwordx4 v[204:205], off
	s_waitcnt vmcnt(8)
	s_waitcnt lgkmcnt(0)
	s_barrier
; #define PG8_STAGE(bufoff, gbase, voff) do { _Pragma("unroll") for (int _i = 0; _i < 2; ++_i) \
;         __builtin_amdgcn_global_load_lds((const unsigned*)((const char*)(gbase) + (voff)[_i]), (PG8_LAS unsigned*)(lds + (bufoff) + ldsw + _i * 8192), 16, 0, 0); } while (0)
; #define PG8_LDA(dst, b, h) do { _Pragma("unroll") for (int m = 0; m < 4; ++m) _Pragma("unroll") for (int k = 0; k < 2; ++k) dst[m][k] = *(const PG8_LAS bf16x8*)(lds + PG8_SA(b, h) + aoff + m * 2048 + k * 1024); } while (0)
; #define PG8_LDB(dst, b, h) do { _Pragma("unroll") for (int n = 0; n < 2; ++n) _Pragma("unroll") for (int k = 0; k < 2; ++k) dst[n][k] = *(const PG8_LAS bf16x8*)(lds + PG8_SB(b, h) + boff + n * 2048 + k * 1024); } while (0)
; #define PG8_MMA(ai, bj, At, Bt) do { __builtin_amdgcn_s_setprio(1); _Pragma("unroll") for (int m = 0; m < 4; ++m) _Pragma("unroll") for (int n = 0; n < 2; ++n) _Pragma("unroll") for (int k = 0; k < 2; ++k) \
;         acc[ai][bj][m][n] = __builtin_amdgcn_mfma_f32_16x16x32_bf16(Bt[n][k], At[m][k], acc[ai][bj][m][n], 0, 0, 0); __builtin_amdgcn_s_setprio(0); } while (0)
; #define PG8_WAIT_V(n) asm volatile("s_waitcnt vmcnt(" #n ")" ::: "memory")
; #define PG8_WAIT_L(n) asm volatile("s_waitcnt lgkmcnt(" #n ")" ::: "memory")
; #define PG8_BAR __builtin_amdgcn_s_barrier()
; #define PG8_SCHED __builtin_amdgcn_sched_barrier(0)
; template <class Epi, class Sched, bool ALIGN_EPI = false, bool SP2 = false>
; __device__ __forceinline__ void gemm_phase(PG8_LAS unsigned char* lds, const Gemm g, const Sched& S, const Epi& E, const int tid) {
;     ...
;             PG8_WAIT_V(8); PG8_WAIT_L(0); PG8_BAR; PG8_MMA(1, 0, At, B0); PG8_MMA(1, 1, At, B1); PG8_BAR; PG8_SCHED;
;             PG8_LDB(B0, 1, 0); PG8_LDB(B1, 1, 1); PG8_SCHED; PG8_LDA(At, 1, 0); PG8_STAGE(PG8_SA(0, 1), a2 + hstep, voffA);
;             PG8_WAIT_V(8); PG8_WAIT_L(0); PG8_BAR; PG8_MMA(0, 0, At, B0); PG8_MMA(0, 1, At, B1); PG8_BAR; PG8_SCHED;
	s_setprio 1
	s_waitcnt lgkmcnt(0)
	v_mfma_f32_16x16x32_bf16 v[60:63], v[138:141], v[172:175], v[60:63]
	v_mfma_f32_16x16x32_bf16 v[56:59], v[148:151], v[172:175], v[56:59]
	v_mfma_f32_16x16x32_bf16 v[44:47], v[138:141], v[180:183], v[44:47]
	v_mfma_f32_16x16x32_bf16 v[40:43], v[148:151], v[180:183], v[40:43]
	v_mfma_f32_16x16x32_bf16 v[28:31], v[138:141], v[188:191], v[28:31]
	v_mfma_f32_16x16x32_bf16 v[24:27], v[148:151], v[188:191], v[24:27]
	v_mfma_f32_16x16x32_bf16 v[12:15], v[138:141], v[216:219], v[12:15]
	v_mfma_f32_16x16x32_bf16 v[8:11], v[148:151], v[216:219], v[8:11]
	v_mfma_f32_16x16x32_bf16 v[60:63], v[144:147], v[176:179], v[60:63]
	v_mfma_f32_16x16x32_bf16 v[56:59], v[152:155], v[176:179], v[56:59]
	v_mfma_f32_16x16x32_bf16 v[44:47], v[144:147], v[184:187], v[44:47]
	v_mfma_f32_16x16x32_bf16 v[40:43], v[152:155], v[184:187], v[40:43]
	v_mfma_f32_16x16x32_bf16 v[28:31], v[144:147], v[212:215], v[28:31]
	v_mfma_f32_16x16x32_bf16 v[24:27], v[152:155], v[212:215], v[24:27]
	v_mfma_f32_16x16x32_bf16 v[12:15], v[144:147], v[232:235], v[12:15]
	v_mfma_f32_16x16x32_bf16 v[8:11], v[152:155], v[232:235], v[8:11]
	s_setprio 0
	s_setprio 1
	v_mfma_f32_16x16x32_bf16 v[52:55], v[156:159], v[172:175], v[52:55]
	v_mfma_f32_16x16x32_bf16 v[48:51], v[164:167], v[172:175], v[48:51]
	v_mfma_f32_16x16x32_bf16 v[36:39], v[156:159], v[180:183], v[36:39]
	v_mfma_f32_16x16x32_bf16 v[32:35], v[164:167], v[180:183], v[32:35]
	v_mfma_f32_16x16x32_bf16 v[20:23], v[156:159], v[188:191], v[20:23]
	v_mfma_f32_16x16x32_bf16 v[16:19], v[164:167], v[188:191], v[16:19]
	v_mfma_f32_16x16x32_bf16 v[4:7], v[156:159], v[216:219], v[4:7]
	v_mfma_f32_16x16x32_bf16 v[0:3], v[164:167], v[216:219], v[0:3]
	v_mfma_f32_16x16x32_bf16 v[52:55], v[160:163], v[176:179], v[52:55]
	v_mfma_f32_16x16x32_bf16 v[48:51], v[168:171], v[176:179], v[48:51]
	v_mfma_f32_16x16x32_bf16 v[36:39], v[160:163], v[184:187], v[36:39]
	v_mfma_f32_16x16x32_bf16 v[32:35], v[168:171], v[184:187], v[32:35]
	s_barrier
	v_mfma_f32_16x16x32_bf16 v[20:23], v[160:163], v[212:215], v[20:23]
	v_mfma_f32_16x16x32_bf16 v[16:19], v[168:171], v[212:215], v[16:19]
	v_mfma_f32_16x16x32_bf16 v[4:7], v[160:163], v[232:235], v[4:7]
	v_mfma_f32_16x16x32_bf16 v[0:3], v[168:171], v[232:235], v[0:3]
	s_setprio 0
	s_add_i32 s35, 0, 0x18000
	s_add_i32 s38, 0, 0x1c000
	v_add_u32_e32 v152, s35, v142
	v_add_u32_e32 v168, s38, v142
	ds_read_b128 v[138:141], v152
	ds_read_b128 v[144:147], v152 offset:1024
	ds_read_b128 v[148:151], v152 offset:2048
	ds_read_b128 v[152:155], v152 offset:3072
	ds_read_b128 v[156:159], v168
	ds_read_b128 v[160:163], v168 offset:1024
	ds_read_b128 v[164:167], v168 offset:2048
	ds_read_b128 v[168:171], v168 offset:3072
	s_add_u32 s40, s58, 0x20000
	s_addc_u32 s41, s59, 0
	s_mov_b32 m0, s85
	v_lshl_add_u64 v[206:207], s[40:41], 0, v[128:129]
	ds_read_b128 v[172:175], v143 offset:32768
	ds_read_b128 v[176:179], v143 offset:33792
	ds_read_b128 v[180:183], v143 offset:34816
	ds_read_b128 v[184:187], v143 offset:35840
	ds_read_b128 v[188:191], v143 offset:36864
	ds_read_b128 v[212:215], v143 offset:37888
	ds_read_b128 v[216:219], v143 offset:38912
	ds_read_b128 v[232:235], v143 offset:39936
	global_load_lds_dwordx4 v[206:207], off
	v_lshl_add_u64 v[206:207], s[40:41], 0, v[130:131]
	s_mov_b32 m0, s86
	s_nop 0
	global_load_lds_dwordx4 v[206:207], off
	s_waitcnt vmcnt(8)
	s_waitcnt lgkmcnt(0)
	s_barrier
	s_setprio 1
	s_waitcnt lgkmcnt(0)
	v_mfma_f32_16x16x32_bf16 v[124:127], v[138:141], v[172:175], v[124:127]
	v_mfma_f32_16x16x32_bf16 v[120:123], v[148:151], v[172:175], v[120:123]
	v_mfma_f32_16x16x32_bf16 v[108:111], v[138:141], v[180:183], v[108:111]
	v_mfma_f32_16x16x32_bf16 v[104:107], v[148:151], v[180:183], v[104:107]
	v_mfma_f32_16x16x32_bf16 v[92:95], v[138:141], v[188:191], v[92:95]
	v_mfma_f32_16x16x32_bf16 v[88:91], v[148:151], v[188:191], v[88:91]
	v_mfma_f32_16x16x32_bf16 v[76:79], v[138:141], v[216:219], v[76:79]
	v_mfma_f32_16x16x32_bf16 v[72:75], v[148:151], v[216:219], v[72:75]
	v_mfma_f32_16x16x32_bf16 v[124:127], v[144:147], v[176:179], v[124:127]
	v_mfma_f32_16x16x32_bf16 v[120:123], v[152:155], v[176:179], v[120:123]
	v_mfma_f32_16x16x32_bf16 v[108:111], v[144:147], v[184:187], v[108:111]
	v_mfma_f32_16x16x32_bf16 v[104:107], v[152:155], v[184:187], v[104:107]
	v_mfma_f32_16x16x32_bf16 v[92:95], v[144:147], v[212:215], v[92:95]
	v_mfma_f32_16x16x32_bf16 v[88:91], v[152:155], v[212:215], v[88:91]
	v_mfma_f32_16x16x32_bf16 v[76:79], v[144:147], v[232:235], v[76:79]
	v_mfma_f32_16x16x32_bf16 v[72:75], v[152:155], v[232:235], v[72:75]
	s_setprio 0
	s_setprio 1
	v_mfma_f32_16x16x32_bf16 v[116:119], v[156:159], v[172:175], v[116:119]
	v_mfma_f32_16x16x32_bf16 v[112:115], v[164:167], v[172:175], v[112:115]
	v_mfma_f32_16x16x32_bf16 v[100:103], v[156:159], v[180:183], v[100:103]
	v_mfma_f32_16x16x32_bf16 v[96:99], v[164:167], v[180:183], v[96:99]
	v_mfma_f32_16x16x32_bf16 v[84:87], v[156:159], v[188:191], v[84:87]
	v_mfma_f32_16x16x32_bf16 v[80:83], v[164:167], v[188:191], v[80:83]
	v_mfma_f32_16x16x32_bf16 v[68:71], v[156:159], v[216:219], v[68:71]
	v_mfma_f32_16x16x32_bf16 v[64:67], v[164:167], v[216:219], v[64:67]
	v_mfma_f32_16x16x32_bf16 v[116:119], v[160:163], v[176:179], v[116:119]
	v_mfma_f32_16x16x32_bf16 v[112:115], v[168:171], v[176:179], v[112:115]
	v_mfma_f32_16x16x32_bf16 v[100:103], v[160:163], v[184:187], v[100:103]
	v_mfma_f32_16x16x32_bf16 v[96:99], v[168:171], v[184:187], v[96:99]
	s_barrier
; #define PG8_STAGE(bufoff, gbase, voff) do { _Pragma("unroll") for (int _i = 0; _i < 2; ++_i) \
;         __builtin_amdgcn_global_load_lds((const unsigned*)((const char*)(gbase) + (voff)[_i]), (PG8_LAS unsigned*)(lds + (bufoff) + ldsw + _i * 8192), 16, 0, 0); } while (0)
; #define PG8_LDA(dst, b, h) do { _Pragma("unroll") for (int m = 0; m < 4; ++m) _Pragma("unroll") for (int k = 0; k < 2; ++k) dst[m][k] = *(const PG8_LAS bf16x8*)(lds + PG8_SA(b, h) + aoff + m * 2048 + k * 1024); } while (0)
; #define PG8_MMA(ai, bj, At, Bt) do { __builtin_amdgcn_s_setprio(1); _Pragma("unroll") for (int m = 0; m < 4; ++m) _Pragma("unroll") for (int n = 0; n < 2; ++n) _Pragma("unroll") for (int k = 0; k < 2; ++k) \
;         acc[ai][bj][m][n] = __builtin_amdgcn_mfma_f32_16x16x32_bf16(Bt[n][k], At[m][k], acc[ai][bj][m][n], 0, 0, 0); __builtin_amdgcn_s_setprio(0); } while (0)
; #define PG8_WAIT_V(n) asm volatile("s_waitcnt vmcnt(" #n ")" ::: "memory")
; #define PG8_WAIT_L(n) asm volatile("s_waitcnt lgkmcnt(" #n ")" ::: "memory")
; #define PG8_BAR __builtin_amdgcn_s_barrier()
; #define PG8_SCHED __builtin_amdgcn_sched_barrier(0)
; template <class Epi, class Sched, bool ALIGN_EPI = false, bool SP2 = false>
; __device__ __forceinline__ void gemm_phase(PG8_LAS unsigned char* lds, const Gemm g, const Sched& S, const Epi& E, const int tid) {
;     ...
;             PG8_WAIT_V(8); PG8_WAIT_L(0); PG8_BAR; PG8_MMA(0, 0, At, B0); PG8_MMA(0, 1, At, B1); PG8_BAR; PG8_SCHED;
;             PG8_LDA(At, 1, 1); PG8_STAGE(PG8_SB(1, 0), b3, voffB); PG8_STAGE(PG8_SB(1, 1), b3 + hstep, voffB); PG8_STAGE(PG8_SA(1, 0), a3, voffA);
;             PG8_WAIT_V(8); PG8_WAIT_L(0); PG8_BAR; PG8_MMA(1, 0, At, B0); PG8_MMA(1, 1, At, B1); PG8_BAR; PG8_SCHED;
;     ...
;         if constexpr (ALIGN_EPI) { if (wr == 0) PG8_BAR; }
	v_mfma_f32_16x16x32_bf16 v[84:87], v[160:163], v[212:215], v[84:87]
	v_mfma_f32_16x16x32_bf16 v[80:83], v[168:171], v[212:215], v[80:83]
	v_mfma_f32_16x16x32_bf16 v[68:71], v[160:163], v[232:235], v[68:71]
	v_mfma_f32_16x16x32_bf16 v[64:67], v[168:171], v[232:235], v[64:67]
	s_setprio 0
	s_add_i32 s35, s35, s82
	v_lshl_add_u64 v[194:195], v[194:195], 0, s[36:37]
	s_mov_b32 m0, s35
	ds_read_b128 v[172:175], v143 offset:49152
	ds_read_b128 v[176:179], v143 offset:50176
	ds_read_b128 v[180:183], v143 offset:51200
	ds_read_b128 v[184:187], v143 offset:52224
	ds_read_b128 v[188:191], v143 offset:53248
	ds_read_b128 v[212:215], v143 offset:54272
	ds_read_b128 v[216:219], v143 offset:55296
	ds_read_b128 v[232:235], v143 offset:56320
	global_load_lds_dwordx4 v[194:195], off
	s_add_i32 m0, s35, 0x2000
	s_add_u32 s40, s44, 0x20080
	v_lshl_add_u64 v[194:195], v[196:197], 0, s[36:37]
	s_addc_u32 s41, s45, 0
	s_add_i32 s35, s38, s82
	global_load_lds_dwordx4 v[194:195], off
	v_lshl_add_u64 v[194:195], s[40:41], 0, v[192:193]
	s_mov_b32 m0, s35
	s_nop 0
	global_load_lds_dwordx4 v[194:195], off
	v_lshl_add_u64 v[194:195], s[40:41], 0, v[132:133]
	s_add_i32 m0, s35, 0x2000
	s_nop 0
	global_load_lds_dwordx4 v[194:195], off
	v_lshl_add_u64 v[194:195], v[202:203], 0, s[36:37]
	s_mov_b32 m0, s87
	s_nop 0
	global_load_lds_dwordx4 v[194:195], off
	v_lshl_add_u64 v[194:195], v[204:205], 0, s[36:37]
	s_mov_b32 m0, s88
	s_nop 0
	global_load_lds_dwordx4 v[194:195], off
	s_waitcnt vmcnt(8)
	s_waitcnt lgkmcnt(0)
	s_barrier
	s_setprio 1
	s_waitcnt lgkmcnt(0)
	v_mfma_f32_16x16x32_bf16 v[60:63], v[138:141], v[172:175], v[60:63]
	v_mfma_f32_16x16x32_bf16 v[56:59], v[148:151], v[172:175], v[56:59]
	v_mfma_f32_16x16x32_bf16 v[44:47], v[138:141], v[180:183], v[44:47]
	v_mfma_f32_16x16x32_bf16 v[40:43], v[148:151], v[180:183], v[40:43]
	v_mfma_f32_16x16x32_bf16 v[28:31], v[138:141], v[188:191], v[28:31]
	v_mfma_f32_16x16x32_bf16 v[24:27], v[148:151], v[188:191], v[24:27]
	v_mfma_f32_16x16x32_bf16 v[12:15], v[138:141], v[216:219], v[12:15]
	v_mfma_f32_16x16x32_bf16 v[8:11], v[148:151], v[216:219], v[8:11]
	v_mfma_f32_16x16x32_bf16 v[60:63], v[144:147], v[176:179], v[60:63]
	v_mfma_f32_16x16x32_bf16 v[56:59], v[152:155], v[176:179], v[56:59]
	v_mfma_f32_16x16x32_bf16 v[44:47], v[144:147], v[184:187], v[44:47]
	v_mfma_f32_16x16x32_bf16 v[40:43], v[152:155], v[184:187], v[40:43]
	v_mfma_f32_16x16x32_bf16 v[28:31], v[144:147], v[212:215], v[28:31]
	v_mfma_f32_16x16x32_bf16 v[24:27], v[152:155], v[212:215], v[24:27]
	v_mfma_f32_16x16x32_bf16 v[12:15], v[144:147], v[232:235], v[12:15]
	v_mfma_f32_16x16x32_bf16 v[8:11], v[152:155], v[232:235], v[8:11]
	s_setprio 0
	s_setprio 1
	v_mfma_f32_16x16x32_bf16 v[52:55], v[156:159], v[172:175], v[52:55]
	v_mfma_f32_16x16x32_bf16 v[48:51], v[164:167], v[172:175], v[48:51]
	v_mfma_f32_16x16x32_bf16 v[36:39], v[156:159], v[180:183], v[36:39]
	v_mfma_f32_16x16x32_bf16 v[32:35], v[164:167], v[180:183], v[32:35]
	v_mfma_f32_16x16x32_bf16 v[20:23], v[156:159], v[188:191], v[20:23]
	v_mfma_f32_16x16x32_bf16 v[16:19], v[164:167], v[188:191], v[16:19]
	v_mfma_f32_16x16x32_bf16 v[4:7], v[156:159], v[216:219], v[4:7]
	v_mfma_f32_16x16x32_bf16 v[0:3], v[164:167], v[216:219], v[0:3]
	v_mfma_f32_16x16x32_bf16 v[52:55], v[160:163], v[176:179], v[52:55]
	v_mfma_f32_16x16x32_bf16 v[48:51], v[168:171], v[176:179], v[48:51]
	v_mfma_f32_16x16x32_bf16 v[36:39], v[160:163], v[184:187], v[36:39]
	v_mfma_f32_16x16x32_bf16 v[32:35], v[168:171], v[184:187], v[32:35]
	s_barrier
	v_mfma_f32_16x16x32_bf16 v[20:23], v[160:163], v[212:215], v[20:23]
	v_mfma_f32_16x16x32_bf16 v[16:19], v[168:171], v[212:215], v[16:19]
	v_mfma_f32_16x16x32_bf16 v[4:7], v[160:163], v[232:235], v[4:7]
	v_mfma_f32_16x16x32_bf16 v[0:3], v[168:171], v[232:235], v[0:3]
	s_setprio 0
	s_add_i32 s34, s34, 2
	s_add_u32 s28, s28, 0x100
	s_addc_u32 s29, s29, 0
	s_add_u32 s23, s23, 0x100
	s_addc_u32 s26, s26, 0
	s_cmp_gt_u32 s34, 5
	s_cbranch_scc0 .LBB0_348
	s_nop 7
	s_and_b64 vcc, exec, s[12:13]
	s_cbranch_vccz .LBB0_351
	s_barrier

; #define PG8_STAGE(bufoff, gbase, voff) do { _Pragma("unroll") for (int _i = 0; _i < 2; ++_i) \
;         __builtin_amdgcn_global_load_lds((const unsigned*)((const char*)(gbase) + (voff)[_i]), (PG8_LAS unsigned*)(lds + (bufoff) + ldsw + _i * 8192), 16, 0, 0); } while (0)
; #define PG8_LDA(dst, b, h) do { _Pragma("unroll") for (int m = 0; m < 4; ++m) _Pragma("unroll") for (int k = 0; k < 2; ++k) dst[m][k] = *(const PG8_LAS bf16x8*)(lds + PG8_SA(b, h) + aoff + m * 2048 + k * 1024); } while (0)
; #define PG8_LDB(dst, b, h) do { _Pragma("unroll") for (int n = 0; n < 2; ++n) _Pragma("unroll") for (int k = 0; k < 2; ++k) dst[n][k] = *(const PG8_LAS bf16x8*)(lds + PG8_SB(b, h) + boff + n * 2048 + k * 1024); } while (0)
; #define PG8_MMA(ai, bj, At, Bt) do { __builtin_amdgcn_s_setprio(1); _Pragma("unroll") for (int m = 0; m < 4; ++m) _Pragma("unroll") for (int n = 0; n < 2; ++n) _Pragma("unroll") for (int k = 0; k < 2; ++k) \
;         acc[ai][bj][m][n] = __builtin_amdgcn_mfma_f32_16x16x32_bf16(Bt[n][k], At[m][k], acc[ai][bj][m][n], 0, 0, 0); __builtin_amdgcn_s_setprio(0); } while (0)
; #define PG8_WAIT_V(n) asm volatile("s_waitcnt vmcnt(" #n ")" ::: "memory")
; #define PG8_WAIT_L(n) asm volatile("s_waitcnt lgkmcnt(" #n ")" ::: "memory")
; template <class Epi, class Sched, bool ALIGN_EPI = false, bool SP2 = false>
; __device__ __forceinline__ void gemm_phase(PG8_LAS unsigned char* lds, const Gemm g, const Sched& S, const Epi& E, const int tid) {
;     ...
;             const bool last = (t == nt - 2);
;             const char* a1 = cA + (size_t)(t + 1) * kstep;
;             const char* a2 = last ? nA : cA + (size_t)(t + 2) * kstep; const char* b2 = last ? nB : cB + (size_t)(t + 2) * kstep;
;             const char* a3 = a2 + kstep; const char* b3 = b2 + kstep;
;             if (last && has_next) S.a_ready(nxt);
;             if constexpr (SP2) {
;             PG8_LDB(B0, 0, 0); PG8_LDB(B1, 0, 1); PG8_SCHED; PG8_LDA(At, 0, 0); PG8_STAGE(PG8_SA(1, 1), a1 + hstep, voffA);
;             PG8_WAIT_V(8); PG8_WAIT_L(0); PG8_BAR; PG8_MMA(0, 0, At, B0); PG8_MMA(0, 1, At, B1); PG8_BAR; PG8_SCHED;
;             PG8_LDA(At, 0, 1); PG8_STAGE(PG8_SB(0, 0), b2, voffB); PG8_STAGE(PG8_SB(0, 1), b2 + hstep, voffB); PG8_STAGE(PG8_SA(0, 0), a2, voffA);
;             PG8_WAIT_V(8); PG8_WAIT_L(0); PG8_BAR; PG8_MMA(1, 0, At, B0); PG8_MMA(1, 1, At, B1); PG8_BAR; PG8_SCHED;
.LBB0_485:
	s_add_u32 s38, s8, 0xfffc0080
	s_addc_u32 s40, s9, -1
	s_add_i32 s41, 0, 0x10000
	s_cmp_eq_u32 s35, 12
	s_cselect_b32 s59, s0, s40
	s_cselect_b32 s58, s1, s38
	s_cselect_b32 s45, s2, s34
	s_cselect_b32 s44, s15, s17
	s_add_i32 s38, 0, 0x14000
	v_add_u32_e32 v140, s41, v184
	v_add_u32_e32 v168, s38, v184
	ds_read_b128 v[128:131], v140
	ds_read_b128 v[132:135], v140 offset:1024
	ds_read_b128 v[136:139], v140 offset:2048
	ds_read_b128 v[140:143], v140 offset:3072
	ds_read_b128 v[144:147], v168
	ds_read_b128 v[148:151], v168 offset:1024
	ds_read_b128 v[164:167], v168 offset:2048
	ds_read_b128 v[168:171], v168 offset:3072
	v_lshl_add_u64 v[190:191], s[8:9], 0, v[160:161]
	s_add_i32 m0, s23, 0xc000
	ds_read_b128 v[172:175], v185
	ds_read_b128 v[176:179], v185 offset:1024
	ds_read_b128 v[180:183], v185 offset:2048
	ds_read_b128 v[186:189], v185 offset:3072
	ds_read_b128 v[212:215], v185 offset:4096
	ds_read_b128 v[216:219], v185 offset:5120
	ds_read_b128 v[232:235], v185 offset:6144
	ds_read_b128 v[236:239], v185 offset:7168
	global_load_lds_dwordx4 v[190:191], off
	v_lshl_add_u64 v[190:191], s[8:9], 0, v[162:163]
	s_add_i32 m0, s23, 0xe000
	s_nop 0
	global_load_lds_dwordx4 v[190:191], off
	s_waitcnt vmcnt(8)
	s_waitcnt lgkmcnt(0)
	s_barrier
	s_setprio 1
	s_waitcnt lgkmcnt(0)
	v_mfma_f32_16x16x32_bf16 v[124:127], v[128:131], v[172:175], v[124:127]
	v_mfma_f32_16x16x32_bf16 v[120:123], v[136:139], v[172:175], v[120:123]
	v_mfma_f32_16x16x32_bf16 v[108:111], v[128:131], v[180:183], v[108:111]
	v_mfma_f32_16x16x32_bf16 v[104:107], v[136:139], v[180:183], v[104:107]
	v_mfma_f32_16x16x32_bf16 v[92:95], v[128:131], v[212:215], v[92:95]
	v_mfma_f32_16x16x32_bf16 v[88:91], v[136:139], v[212:215], v[88:91]
	v_mfma_f32_16x16x32_bf16 v[76:79], v[128:131], v[232:235], v[76:79]
	v_mfma_f32_16x16x32_bf16 v[72:75], v[136:139], v[232:235], v[72:75]
	v_mfma_f32_16x16x32_bf16 v[124:127], v[132:135], v[176:179], v[124:127]
	v_mfma_f32_16x16x32_bf16 v[120:123], v[140:143], v[176:179], v[120:123]
	v_mfma_f32_16x16x32_bf16 v[108:111], v[132:135], v[186:189], v[108:111]
	v_mfma_f32_16x16x32_bf16 v[104:107], v[140:143], v[186:189], v[104:107]
	v_mfma_f32_16x16x32_bf16 v[92:95], v[132:135], v[216:219], v[92:95]
	v_mfma_f32_16x16x32_bf16 v[88:91], v[140:143], v[216:219], v[88:91]
	v_mfma_f32_16x16x32_bf16 v[76:79], v[132:135], v[236:239], v[76:79]
	v_mfma_f32_16x16x32_bf16 v[72:75], v[140:143], v[236:239], v[72:75]
	s_setprio 0
	s_setprio 1
	v_mfma_f32_16x16x32_bf16 v[116:119], v[144:147], v[172:175], v[116:119]
	v_mfma_f32_16x16x32_bf16 v[112:115], v[164:167], v[172:175], v[112:115]
	v_mfma_f32_16x16x32_bf16 v[100:103], v[144:147], v[180:183], v[100:103]
	v_mfma_f32_16x16x32_bf16 v[96:99], v[164:167], v[180:183], v[96:99]
	v_mfma_f32_16x16x32_bf16 v[84:87], v[144:147], v[212:215], v[84:87]
	v_mfma_f32_16x16x32_bf16 v[80:83], v[164:167], v[212:215], v[80:83]
	v_mfma_f32_16x16x32_bf16 v[68:71], v[144:147], v[232:235], v[68:71]
	v_mfma_f32_16x16x32_bf16 v[64:67], v[164:167], v[232:235], v[64:67]
	v_mfma_f32_16x16x32_bf16 v[116:119], v[148:151], v[176:179], v[116:119]
	v_mfma_f32_16x16x32_bf16 v[112:115], v[168:171], v[176:179], v[112:115]
	v_mfma_f32_16x16x32_bf16 v[100:103], v[148:151], v[186:189], v[100:103]
	v_mfma_f32_16x16x32_bf16 v[96:99], v[168:171], v[186:189], v[96:99]
	s_barrier
	v_mfma_f32_16x16x32_bf16 v[84:87], v[148:151], v[216:219], v[84:87]
	v_mfma_f32_16x16x32_bf16 v[80:83], v[168:171], v[216:219], v[80:83]
	v_mfma_f32_16x16x32_bf16 v[68:71], v[148:151], v[236:239], v[68:71]
	v_mfma_f32_16x16x32_bf16 v[64:67], v[168:171], v[236:239], v[64:67]
	s_setprio 0
	s_add_i32 s40, s41, s83
	v_lshl_add_u64 v[190:191], s[44:45], 0, v[154:155]
	s_mov_b32 m0, s40
	ds_read_b128 v[172:175], v185 offset:16384
	ds_read_b128 v[176:179], v185 offset:17408
	ds_read_b128 v[180:183], v185 offset:18432
	ds_read_b128 v[186:189], v185 offset:19456
	ds_read_b128 v[212:215], v185 offset:20480
	ds_read_b128 v[216:219], v185 offset:21504
	ds_read_b128 v[232:235], v185 offset:22528
	ds_read_b128 v[236:239], v185 offset:23552
	global_load_lds_dwordx4 v[190:191], off
	s_add_i32 m0, s40, 0x2000
	s_add_u32 s40, s44, 0x40000
	v_lshl_add_u64 v[194:195], s[44:45], 0, v[158:159]
	s_addc_u32 s41, s45, 0
	s_add_i32 s38, s38, s83
	global_load_lds_dwordx4 v[194:195], off
	v_lshl_add_u64 v[196:197], s[40:41], 0, v[154:155]
	s_mov_b32 m0, s38
	v_lshl_add_u64 v[202:203], s[58:59], 0, v[156:157]
	global_load_lds_dwordx4 v[196:197], off
	v_lshl_add_u64 v[196:197], s[40:41], 0, v[158:159]
	s_add_i32 m0, s38, 0x2000
	s_nop 0
	global_load_lds_dwordx4 v[196:197], off
	v_lshl_add_u64 v[196:197], s[58:59], 0, v[152:153]
	s_mov_b32 m0, s23
	s_nop 0
	global_load_lds_dwordx4 v[196:197], off
	s_mov_b32 m0, s29
	s_nop 0
	global_load_lds_dwordx4 v[202:203], off
	s_waitcnt vmcnt(8)
	s_waitcnt lgkmcnt(0)
	s_barrier
; #define PG8_STAGE(bufoff, gbase, voff) do { _Pragma("unroll") for (int _i = 0; _i < 2; ++_i) \
;         __builtin_amdgcn_global_load_lds((const unsigned*)((const char*)(gbase) + (voff)[_i]), (PG8_LAS unsigned*)(lds + (bufoff) + ldsw + _i * 8192), 16, 0, 0); } while (0)
; #define PG8_LDA(dst, b, h) do { _Pragma("unroll") for (int m = 0; m < 4; ++m) _Pragma("unroll") for (int k = 0; k < 2; ++k) dst[m][k] = *(const PG8_LAS bf16x8*)(lds + PG8_SA(b, h) + aoff + m * 2048 + k * 1024); } while (0)
; #define PG8_LDB(dst, b, h) do { _Pragma("unroll") for (int n = 0; n < 2; ++n) _Pragma("unroll") for (int k = 0; k < 2; ++k) dst[n][k] = *(const PG8_LAS bf16x8*)(lds + PG8_SB(b, h) + boff + n * 2048 + k * 1024); } while (0)
; #define PG8_MMA(ai, bj, At, Bt) do { __builtin_amdgcn_s_setprio(1); _Pragma("unroll") for (int m = 0; m < 4; ++m) _Pragma("unroll") for (int n = 0; n < 2; ++n) _Pragma("unroll") for (int k = 0; k < 2; ++k) \
;         acc[ai][bj][m][n] = __builtin_amdgcn_mfma_f32_16x16x32_bf16(Bt[n][k], At[m][k], acc[ai][bj][m][n], 0, 0, 0); __builtin_amdgcn_s_setprio(0); } while (0)
; #define PG8_WAIT_V(n) asm volatile("s_waitcnt vmcnt(" #n ")" ::: "memory")
; #define PG8_WAIT_L(n) asm volatile("s_waitcnt lgkmcnt(" #n ")" ::: "memory")
; #define PG8_BAR __builtin_amdgcn_s_barrier()
; #define PG8_SCHED __builtin_amdgcn_sched_barrier(0)
; template <class Epi, class Sched, bool ALIGN_EPI = false, bool SP2 = false>
; __device__ __forceinline__ void gemm_phase(PG8_LAS unsigned char* lds, const Gemm g, const Sched& S, const Epi& E, const int tid) {
;     ...
;             PG8_WAIT_V(8); PG8_WAIT_L(0); PG8_BAR; PG8_MMA(1, 0, At, B0); PG8_MMA(1, 1, At, B1); PG8_BAR; PG8_SCHED;
;             PG8_LDB(B0, 1, 0); PG8_LDB(B1, 1, 1); PG8_SCHED; PG8_LDA(At, 1, 0); PG8_STAGE(PG8_SA(0, 1), a2 + hstep, voffA);
;             PG8_WAIT_V(8); PG8_WAIT_L(0); PG8_BAR; PG8_MMA(0, 0, At, B0); PG8_MMA(0, 1, At, B1); PG8_BAR; PG8_SCHED;
	s_setprio 1
	s_waitcnt lgkmcnt(0)
	v_mfma_f32_16x16x32_bf16 v[60:63], v[128:131], v[172:175], v[60:63]
	v_mfma_f32_16x16x32_bf16 v[56:59], v[136:139], v[172:175], v[56:59]
	v_mfma_f32_16x16x32_bf16 v[44:47], v[128:131], v[180:183], v[44:47]
	v_mfma_f32_16x16x32_bf16 v[40:43], v[136:139], v[180:183], v[40:43]
	v_mfma_f32_16x16x32_bf16 v[28:31], v[128:131], v[212:215], v[28:31]
	v_mfma_f32_16x16x32_bf16 v[24:27], v[136:139], v[212:215], v[24:27]
	v_mfma_f32_16x16x32_bf16 v[12:15], v[128:131], v[232:235], v[12:15]
	v_mfma_f32_16x16x32_bf16 v[8:11], v[136:139], v[232:235], v[8:11]
	v_mfma_f32_16x16x32_bf16 v[60:63], v[132:135], v[176:179], v[60:63]
	v_mfma_f32_16x16x32_bf16 v[56:59], v[140:143], v[176:179], v[56:59]
	v_mfma_f32_16x16x32_bf16 v[44:47], v[132:135], v[186:189], v[44:47]
	v_mfma_f32_16x16x32_bf16 v[40:43], v[140:143], v[186:189], v[40:43]
	v_mfma_f32_16x16x32_bf16 v[28:31], v[132:135], v[216:219], v[28:31]
	v_mfma_f32_16x16x32_bf16 v[24:27], v[140:143], v[216:219], v[24:27]
	v_mfma_f32_16x16x32_bf16 v[12:15], v[132:135], v[236:239], v[12:15]
	v_mfma_f32_16x16x32_bf16 v[8:11], v[140:143], v[236:239], v[8:11]
	s_setprio 0
	s_setprio 1
	v_mfma_f32_16x16x32_bf16 v[52:55], v[144:147], v[172:175], v[52:55]
	v_mfma_f32_16x16x32_bf16 v[48:51], v[164:167], v[172:175], v[48:51]
	v_mfma_f32_16x16x32_bf16 v[36:39], v[144:147], v[180:183], v[36:39]
	v_mfma_f32_16x16x32_bf16 v[32:35], v[164:167], v[180:183], v[32:35]
	v_mfma_f32_16x16x32_bf16 v[20:23], v[144:147], v[212:215], v[20:23]
	v_mfma_f32_16x16x32_bf16 v[16:19], v[164:167], v[212:215], v[16:19]
	v_mfma_f32_16x16x32_bf16 v[4:7], v[144:147], v[232:235], v[4:7]
	v_mfma_f32_16x16x32_bf16 v[0:3], v[164:167], v[232:235], v[0:3]
	v_mfma_f32_16x16x32_bf16 v[52:55], v[148:151], v[176:179], v[52:55]
	v_mfma_f32_16x16x32_bf16 v[48:51], v[168:171], v[176:179], v[48:51]
	v_mfma_f32_16x16x32_bf16 v[36:39], v[148:151], v[186:189], v[36:39]
	v_mfma_f32_16x16x32_bf16 v[32:35], v[168:171], v[186:189], v[32:35]
	s_barrier
	v_mfma_f32_16x16x32_bf16 v[20:23], v[148:151], v[216:219], v[20:23]
	v_mfma_f32_16x16x32_bf16 v[16:19], v[168:171], v[216:219], v[16:19]
	v_mfma_f32_16x16x32_bf16 v[4:7], v[148:151], v[236:239], v[4:7]
	v_mfma_f32_16x16x32_bf16 v[0:3], v[168:171], v[236:239], v[0:3]
	s_setprio 0
	s_add_i32 s38, 0, 0x18000
	s_add_i32 s46, 0, 0x1c000
	v_add_u32_e32 v140, s38, v184
	v_add_u32_e32 v168, s46, v184
	ds_read_b128 v[128:131], v140
	ds_read_b128 v[132:135], v140 offset:1024
	ds_read_b128 v[136:139], v140 offset:2048
	ds_read_b128 v[140:143], v140 offset:3072
	ds_read_b128 v[144:147], v168
	ds_read_b128 v[148:151], v168 offset:1024
	ds_read_b128 v[164:167], v168 offset:2048
	ds_read_b128 v[168:171], v168 offset:3072
	s_add_u32 s40, s58, 0x40000
	s_addc_u32 s41, s59, 0
	s_mov_b32 m0, s84
	v_lshl_add_u64 v[204:205], s[40:41], 0, v[152:153]
	ds_read_b128 v[172:175], v185 offset:32768
	ds_read_b128 v[176:179], v185 offset:33792
	ds_read_b128 v[180:183], v185 offset:34816
	ds_read_b128 v[186:189], v185 offset:35840
	ds_read_b128 v[212:215], v185 offset:36864
	ds_read_b128 v[216:219], v185 offset:37888
	ds_read_b128 v[232:235], v185 offset:38912
	ds_read_b128 v[236:239], v185 offset:39936
	global_load_lds_dwordx4 v[204:205], off
	v_lshl_add_u64 v[204:205], s[40:41], 0, v[156:157]
	s_mov_b32 m0, s85
	s_nop 0
	global_load_lds_dwordx4 v[204:205], off
	s_waitcnt vmcnt(8)
	s_waitcnt lgkmcnt(0)
	s_barrier
	s_setprio 1
	s_waitcnt lgkmcnt(0)
	v_mfma_f32_16x16x32_bf16 v[124:127], v[128:131], v[172:175], v[124:127]
	v_mfma_f32_16x16x32_bf16 v[120:123], v[136:139], v[172:175], v[120:123]
	v_mfma_f32_16x16x32_bf16 v[108:111], v[128:131], v[180:183], v[108:111]
	v_mfma_f32_16x16x32_bf16 v[104:107], v[136:139], v[180:183], v[104:107]
	v_mfma_f32_16x16x32_bf16 v[92:95], v[128:131], v[212:215], v[92:95]
	v_mfma_f32_16x16x32_bf16 v[88:91], v[136:139], v[212:215], v[88:91]
	v_mfma_f32_16x16x32_bf16 v[76:79], v[128:131], v[232:235], v[76:79]
	v_mfma_f32_16x16x32_bf16 v[72:75], v[136:139], v[232:235], v[72:75]
	v_mfma_f32_16x16x32_bf16 v[124:127], v[132:135], v[176:179], v[124:127]
	v_mfma_f32_16x16x32_bf16 v[120:123], v[140:143], v[176:179], v[120:123]
	v_mfma_f32_16x16x32_bf16 v[108:111], v[132:135], v[186:189], v[108:111]
	v_mfma_f32_16x16x32_bf16 v[104:107], v[140:143], v[186:189], v[104:107]
	v_mfma_f32_16x16x32_bf16 v[92:95], v[132:135], v[216:219], v[92:95]
	v_mfma_f32_16x16x32_bf16 v[88:91], v[140:143], v[216:219], v[88:91]
	v_mfma_f32_16x16x32_bf16 v[76:79], v[132:135], v[236:239], v[76:79]
	v_mfma_f32_16x16x32_bf16 v[72:75], v[140:143], v[236:239], v[72:75]
	s_setprio 0
	s_setprio 1
	v_mfma_f32_16x16x32_bf16 v[116:119], v[144:147], v[172:175], v[116:119]
	v_mfma_f32_16x16x32_bf16 v[112:115], v[164:167], v[172:175], v[112:115]
	v_mfma_f32_16x16x32_bf16 v[100:103], v[144:147], v[180:183], v[100:103]
	v_mfma_f32_16x16x32_bf16 v[96:99], v[164:167], v[180:183], v[96:99]
	v_mfma_f32_16x16x32_bf16 v[84:87], v[144:147], v[212:215], v[84:87]
	v_mfma_f32_16x16x32_bf16 v[80:83], v[164:167], v[212:215], v[80:83]
	v_mfma_f32_16x16x32_bf16 v[68:71], v[144:147], v[232:235], v[68:71]
	v_mfma_f32_16x16x32_bf16 v[64:67], v[164:167], v[232:235], v[64:67]
	v_mfma_f32_16x16x32_bf16 v[116:119], v[148:151], v[176:179], v[116:119]
	v_mfma_f32_16x16x32_bf16 v[112:115], v[168:171], v[176:179], v[112:115]
	v_mfma_f32_16x16x32_bf16 v[100:103], v[148:151], v[186:189], v[100:103]
	v_mfma_f32_16x16x32_bf16 v[96:99], v[168:171], v[186:189], v[96:99]
	s_barrier
; #define PG8_STAGE(bufoff, gbase, voff) do { _Pragma("unroll") for (int _i = 0; _i < 2; ++_i) \
;         __builtin_amdgcn_global_load_lds((const unsigned*)((const char*)(gbase) + (voff)[_i]), (PG8_LAS unsigned*)(lds + (bufoff) + ldsw + _i * 8192), 16, 0, 0); } while (0)
; #define PG8_LDA(dst, b, h) do { _Pragma("unroll") for (int m = 0; m < 4; ++m) _Pragma("unroll") for (int k = 0; k < 2; ++k) dst[m][k] = *(const PG8_LAS bf16x8*)(lds + PG8_SA(b, h) + aoff + m * 2048 + k * 1024); } while (0)
; #define PG8_MMA(ai, bj, At, Bt) do { __builtin_amdgcn_s_setprio(1); _Pragma("unroll") for (int m = 0; m < 4; ++m) _Pragma("unroll") for (int n = 0; n < 2; ++n) _Pragma("unroll") for (int k = 0; k < 2; ++k) \
;         acc[ai][bj][m][n] = __builtin_amdgcn_mfma_f32_16x16x32_bf16(Bt[n][k], At[m][k], acc[ai][bj][m][n], 0, 0, 0); __builtin_amdgcn_s_setprio(0); } while (0)
; #define PG8_WAIT_V(n) asm volatile("s_waitcnt vmcnt(" #n ")" ::: "memory")
; #define PG8_WAIT_L(n) asm volatile("s_waitcnt lgkmcnt(" #n ")" ::: "memory")
; #define PG8_BAR __builtin_amdgcn_s_barrier()
; #define PG8_SCHED __builtin_amdgcn_sched_barrier(0)
; template <class Epi, class Sched, bool ALIGN_EPI = false, bool SP2 = false>
; __device__ __forceinline__ void gemm_phase(PG8_LAS unsigned char* lds, const Gemm g, const Sched& S, const Epi& E, const int tid) {
;     ...
;             PG8_WAIT_V(8); PG8_WAIT_L(0); PG8_BAR; PG8_MMA(0, 0, At, B0); PG8_MMA(0, 1, At, B1); PG8_BAR; PG8_SCHED;
;             PG8_LDA(At, 1, 1); PG8_STAGE(PG8_SB(1, 0), b3, voffB); PG8_STAGE(PG8_SB(1, 1), b3 + hstep, voffB); PG8_STAGE(PG8_SA(1, 0), a3, voffA);
;             PG8_WAIT_V(8); PG8_WAIT_L(0); PG8_BAR; PG8_MMA(1, 0, At, B0); PG8_MMA(1, 1, At, B1); PG8_BAR; PG8_SCHED;
;     ...
;         if constexpr (ALIGN_EPI) { if (wr == 0) PG8_BAR; }
	v_mfma_f32_16x16x32_bf16 v[84:87], v[148:151], v[216:219], v[84:87]
	v_mfma_f32_16x16x32_bf16 v[80:83], v[168:171], v[216:219], v[80:83]
	v_mfma_f32_16x16x32_bf16 v[68:71], v[148:151], v[236:239], v[68:71]
	v_mfma_f32_16x16x32_bf16 v[64:67], v[168:171], v[236:239], v[64:67]
	s_setprio 0
	s_add_i32 s38, s38, s83
	v_lshl_add_u64 v[190:191], v[190:191], 0, s[36:37]
	s_mov_b32 m0, s38
	ds_read_b128 v[172:175], v185 offset:49152
	ds_read_b128 v[176:179], v185 offset:50176
	ds_read_b128 v[180:183], v185 offset:51200
	ds_read_b128 v[186:189], v185 offset:52224
	ds_read_b128 v[212:215], v185 offset:53248
	ds_read_b128 v[216:219], v185 offset:54272
	ds_read_b128 v[232:235], v185 offset:55296
	ds_read_b128 v[236:239], v185 offset:56320
	global_load_lds_dwordx4 v[190:191], off
	s_add_i32 m0, s38, 0x2000
	s_add_u32 s40, s44, 0x40080
	v_lshl_add_u64 v[190:191], v[194:195], 0, s[36:37]
	s_addc_u32 s41, s45, 0
	s_add_i32 s38, s46, s83
	global_load_lds_dwordx4 v[190:191], off
	v_lshl_add_u64 v[190:191], s[40:41], 0, v[154:155]
	s_mov_b32 m0, s38
	s_nop 0
	global_load_lds_dwordx4 v[190:191], off
	v_lshl_add_u64 v[190:191], s[40:41], 0, v[158:159]
	s_add_i32 m0, s38, 0x2000
	s_nop 0
	global_load_lds_dwordx4 v[190:191], off
	v_lshl_add_u64 v[190:191], v[196:197], 0, s[36:37]
	s_mov_b32 m0, s86
	s_nop 0
	global_load_lds_dwordx4 v[190:191], off
	v_lshl_add_u64 v[190:191], v[202:203], 0, s[36:37]
	s_mov_b32 m0, s87
	s_nop 0
	global_load_lds_dwordx4 v[190:191], off
	s_waitcnt vmcnt(8)
	s_waitcnt lgkmcnt(0)
	s_barrier
	s_setprio 1
	s_waitcnt lgkmcnt(0)
	v_mfma_f32_16x16x32_bf16 v[60:63], v[128:131], v[172:175], v[60:63]
	v_mfma_f32_16x16x32_bf16 v[56:59], v[136:139], v[172:175], v[56:59]
	v_mfma_f32_16x16x32_bf16 v[44:47], v[128:131], v[180:183], v[44:47]
	v_mfma_f32_16x16x32_bf16 v[40:43], v[136:139], v[180:183], v[40:43]
	v_mfma_f32_16x16x32_bf16 v[28:31], v[128:131], v[212:215], v[28:31]
	v_mfma_f32_16x16x32_bf16 v[24:27], v[136:139], v[212:215], v[24:27]
	v_mfma_f32_16x16x32_bf16 v[12:15], v[128:131], v[232:235], v[12:15]
	v_mfma_f32_16x16x32_bf16 v[8:11], v[136:139], v[232:235], v[8:11]
	v_mfma_f32_16x16x32_bf16 v[60:63], v[132:135], v[176:179], v[60:63]
	v_mfma_f32_16x16x32_bf16 v[56:59], v[140:143], v[176:179], v[56:59]
	v_mfma_f32_16x16x32_bf16 v[44:47], v[132:135], v[186:189], v[44:47]
	v_mfma_f32_16x16x32_bf16 v[40:43], v[140:143], v[186:189], v[40:43]
	v_mfma_f32_16x16x32_bf16 v[28:31], v[132:135], v[216:219], v[28:31]
	v_mfma_f32_16x16x32_bf16 v[24:27], v[140:143], v[216:219], v[24:27]
	v_mfma_f32_16x16x32_bf16 v[12:15], v[132:135], v[236:239], v[12:15]
	v_mfma_f32_16x16x32_bf16 v[8:11], v[140:143], v[236:239], v[8:11]
	s_setprio 0
	s_setprio 1
	v_mfma_f32_16x16x32_bf16 v[52:55], v[144:147], v[172:175], v[52:55]
	v_mfma_f32_16x16x32_bf16 v[48:51], v[164:167], v[172:175], v[48:51]
	v_mfma_f32_16x16x32_bf16 v[36:39], v[144:147], v[180:183], v[36:39]
	v_mfma_f32_16x16x32_bf16 v[32:35], v[164:167], v[180:183], v[32:35]
	v_mfma_f32_16x16x32_bf16 v[20:23], v[144:147], v[212:215], v[20:23]
	v_mfma_f32_16x16x32_bf16 v[16:19], v[164:167], v[212:215], v[16:19]
	v_mfma_f32_16x16x32_bf16 v[4:7], v[144:147], v[232:235], v[4:7]
	v_mfma_f32_16x16x32_bf16 v[0:3], v[164:167], v[232:235], v[0:3]
	v_mfma_f32_16x16x32_bf16 v[52:55], v[148:151], v[176:179], v[52:55]
	v_mfma_f32_16x16x32_bf16 v[48:51], v[168:171], v[176:179], v[48:51]
	v_mfma_f32_16x16x32_bf16 v[36:39], v[148:151], v[186:189], v[36:39]
	v_mfma_f32_16x16x32_bf16 v[32:35], v[168:171], v[186:189], v[32:35]
	s_barrier
	v_mfma_f32_16x16x32_bf16 v[20:23], v[148:151], v[216:219], v[20:23]
	v_mfma_f32_16x16x32_bf16 v[16:19], v[168:171], v[216:219], v[16:19]
	v_mfma_f32_16x16x32_bf16 v[4:7], v[148:151], v[236:239], v[4:7]
	v_mfma_f32_16x16x32_bf16 v[0:3], v[168:171], v[236:239], v[0:3]
	s_setprio 0
	s_add_i32 s35, s35, 2
	s_add_u32 s8, s8, 0x100
	s_addc_u32 s9, s9, 0
	s_add_u32 s17, s17, 0x100
	s_addc_u32 s34, s34, 0
	s_cmp_gt_u32 s35, 13
	s_cbranch_scc0 .LBB0_485
	s_nop 7
	s_and_b64 vcc, exec, s[12:13]
	s_cbranch_vccz .LBB0_488
	s_barrier
